# v12 + first/after-asm nop trims in DPP blocks, dedupe of prev/next token loads in sample scan loop, compact SGPR-offset addressing in ffn_in reload blocks
# speedup vs baseline: 1.0055x; 1.0055x over previous
; DEV void gemm_gload(GRegs& g, const bf16_t* A0, int lda0, const bf16_t* A1, int lda1, int ksplit,
;                     const bf16_t* Bt, int ldb, int k0, int tid) {
;   const bf16_t* Ab; int lda, kk;
;   if (k0 < ksplit) { Ab = A0; lda = lda0; kk = k0; }
;   else { Ab = A1; lda = lda1; kk = k0 - ksplit; }
;   const int row = tid >> 2, kc = (tid & 3) * 8;
;   const bf16_t* pa = Ab + (size_t)row * lda + kk + kc;
;   const bf16_t* pb = Bt + (size_t)row * ldb + k0 + kc;
;   g.a0 = *(const u32x4*)(pa);
;   g.a1 = *(const u32x4*)(pa + (size_t)64 * lda);
;   g.a2 = *(const u32x4*)(pa + (size_t)128 * lda);
;   g.a3 = *(const u32x4*)(pa + (size_t)192 * lda);
;   g.b0 = *(const u32x4*)(pb);
;   g.b1 = *(const u32x4*)(pb + (size_t)64 * ldb);
; }
; template <bool RES, class Epi>
; DEV void gemm_tile_x(const bf16_t* A0, int lda0, const bf16_t* A1, int lda1, int ksplit,
;                      const bf16_t* Bt, int ldb, int K, char* smem, const float* resb, Epi epi) {
;     ...
;   f32x16 acc[4][2];
; #pragma unroll
;   for (int i = 0; i < 4; ++i)
; #pragma unroll
;     for (int j = 0; j < 2; ++j)
; #pragma unroll
;       for (int r = 0; r < 16; ++r) acc[i][j][r] = 0.f;
;   GRegs g, g1;
;   const int nk = K >> 5;
;   const int woff = (tid >> 2) * 32 + (((tid & 3) ^ ((tid >> 4) & 3)) << 3);
;   const int swz = (lane >> 2) & 3, hh = lane >> 5;
;   const int raoff = (wm * 128 + (lane & 31)) * 32;
;   const int rboff = GSA + (wn * 64 + (lane & 31)) * 32;
;   const int ko0 = ((0 + hh) ^ swz) << 3, ko1 = ((2 + hh) ^ swz) << 3;
;   __syncthreads();
;   gemm_gload(g, A0, lda0, A1, lda1, ksplit, Bt, ldb, 0, tid);
;   if (nk > 1) gemm_gload(g1, A0, lda0, A1, lda1, ksplit, Bt, ldb, 32, tid);
;   gemm_lds_write(g, sbase + woff, sbase + GSA + woff);
;   if (nk > 2) gemm_gload(g, A0, lda0, A1, lda1, ksplit, Bt, ldb, 64, tid);
;   __syncthreads();
.LBB0_175:
	s_mul_hi_u32 s52, s48, 0xba2e8ba3
	s_lshr_b32 s52, s52, 7
	s_lshl_b32 s53, s52, 2
	s_mulk_i32 s52, 0xff50
	s_add_i32 s52, s52, s48
	s_add_i32 s53, s53, s88
	s_and_b32 s48, s48, 3
	s_or_b32 s48, s53, s48
	s_lshl_b64 s[54:55], s[48:49], 19
	s_ashr_i32 s52, s52, 2
	v_lshl_add_u64 v[52:53], v[188:189], 0, s[54:55]
	s_ashr_i32 s53, s52, 31
	v_add_co_u32_e32 v56, vcc, s91, v52
	s_lshl_b64 s[56:57], s[52:53], 18
	s_nop 0
	v_addc_co_u32_e32 v57, vcc, 0, v53, vcc
	s_mov_b32 s53, 0x40000
	v_add_co_u32_e32 v58, vcc, s53, v52
	s_mov_b32 s53, 0x60000
	s_nop 0
	v_addc_co_u32_e32 v59, vcc, 0, v53, vcc
	v_add_co_u32_e32 v60, vcc, s53, v52
	v_lshl_add_u64 v[54:55], v[186:187], 0, s[56:57]
	s_nop 0
	v_addc_co_u32_e32 v61, vcc, 0, v53, vcc
	v_add_co_u32_e32 v62, vcc, s91, v54
	s_nop 1
	v_addc_co_u32_e32 v63, vcc, 0, v55, vcc
	s_barrier
	global_load_dwordx4 v[28:31], v[52:53], off
	global_load_dwordx4 v[32:35], v[56:57], off
	global_load_dwordx4 v[36:39], v[58:59], off
	global_load_dwordx4 v[40:43], v[60:61], off
	global_load_dwordx4 v[44:47], v[54:55], off
	global_load_dwordx4 v[48:51], v[62:63], off
	global_load_dwordx4 v[128:131], v[52:53], off offset:64
	global_load_dwordx4 v[136:139], v[56:57], off offset:64
	global_load_dwordx4 v[148:151], v[60:61], off offset:64
	global_load_dwordx4 v[132:135], v[52:53], off offset:128
	global_load_dwordx4 v[140:143], v[56:57], off offset:128
	global_load_dwordx4 v[144:147], v[58:59], off offset:64
	global_load_dwordx4 v[152:155], v[58:59], off offset:128
	global_load_dwordx4 v[160:163], v[54:55], off offset:64
	global_load_dwordx4 v[164:167], v[54:55], off offset:128
	global_load_dwordx4 v[156:159], v[60:61], off offset:128
	global_load_dwordx4 v[168:171], v[62:63], off offset:64
	global_load_dwordx4 v[172:175], v[62:63], off offset:128
	v_mov_b32_e32 v0, 0
	s_mov_b32 s53, -2
	v_mov_b32_e32 v1, v0
	v_mov_b32_e32 v2, v0
	v_mov_b32_e32 v3, v0
	v_mov_b32_e32 v4, v0
	v_mov_b32_e32 v5, v0
	v_mov_b32_e32 v6, v0
	v_mov_b32_e32 v7, v0
	v_mov_b32_e32 v8, v0
	v_mov_b32_e32 v9, v0
	v_mov_b32_e32 v10, v0
	v_mov_b32_e32 v11, v0
	v_mov_b32_e32 v12, v0
	v_mov_b32_e32 v13, v0
	v_mov_b32_e32 v14, v0
	v_mov_b32_e32 v15, v0
	v_mov_b32_e32 v16, v0
	v_mov_b32_e32 v17, v0
	v_mov_b32_e32 v18, v0
	v_mov_b32_e32 v19, v0
	v_mov_b32_e32 v20, v0
	v_mov_b32_e32 v21, v0
	v_mov_b32_e32 v22, v0
	v_mov_b32_e32 v23, v0
	v_mov_b32_e32 v24, v0
	v_mov_b32_e32 v25, v0
	v_mov_b32_e32 v26, v0
	v_lshl_add_u64 v[192:193], v[184:185], 0, s[54:55]
	v_lshl_add_u64 v[194:195], v[184:185], 0, s[56:57]
	v_lshl_add_u64 v[192:193], v[192:193], 0, v[190:191]
	v_lshl_add_u64 v[194:195], v[194:195], 0, v[190:191]
	s_mov_b32 s56, 0x1b00000
	s_mov_b32 s57, 0
	v_lshl_add_u64 v[192:193], v[192:193], 0, s[56:57]
	v_mov_b32_e32 v27, v0
	v_mov_b32_e32 v52, v0
	v_mov_b32_e32 v53, v0
	v_mov_b32_e32 v54, v0
	v_mov_b32_e32 v55, v0
	v_mov_b32_e32 v56, v0
	v_mov_b32_e32 v57, v0
	v_mov_b32_e32 v58, v0
	v_mov_b32_e32 v59, v0
	v_mov_b32_e32 v60, v0
	v_mov_b32_e32 v61, v0
	v_mov_b32_e32 v62, v0
	v_mov_b32_e32 v63, v0
	v_mov_b32_e32 v64, v0
	v_mov_b32_e32 v65, v0
	v_mov_b32_e32 v66, v0
	v_mov_b32_e32 v67, v0
	v_mov_b32_e32 v68, v0
	v_mov_b32_e32 v69, v0
	v_mov_b32_e32 v70, v0
	v_mov_b32_e32 v71, v0
	s_waitcnt vmcnt(17)
	ds_write_b128 v179, v[28:31]
	s_waitcnt vmcnt(16)
	ds_write_b128 v179, v[32:35] offset:4096
	s_waitcnt vmcnt(15)
	ds_write_b128 v179, v[36:39] offset:8192
	s_waitcnt vmcnt(14)
	ds_write_b128 v179, v[40:43] offset:12288
	s_waitcnt vmcnt(13)
	ds_write_b128 v179, v[44:47] offset:16384
	s_waitcnt vmcnt(12)
	ds_write_b128 v179, v[48:51] offset:20480
	v_mov_b32_e32 v28, v0
	v_mov_b32_e32 v29, v0
	v_mov_b32_e32 v30, v0
	v_mov_b32_e32 v31, v0
	v_mov_b32_e32 v32, v0
	v_mov_b32_e32 v33, v0
	v_mov_b32_e32 v34, v0
	v_mov_b32_e32 v35, v0
	v_mov_b32_e32 v36, v0
	v_mov_b32_e32 v37, v0
	v_mov_b32_e32 v38, v0
	v_mov_b32_e32 v39, v0
	v_mov_b32_e32 v40, v0
	v_mov_b32_e32 v41, v0
	v_mov_b32_e32 v42, v0
	v_mov_b32_e32 v43, v0
	v_mov_b32_e32 v44, v0
	v_mov_b32_e32 v45, v0
	v_mov_b32_e32 v46, v0
	v_mov_b32_e32 v47, v0
	v_mov_b32_e32 v48, v0
	v_mov_b32_e32 v49, v0
	v_mov_b32_e32 v50, v0
	v_mov_b32_e32 v51, v0
	v_mov_b32_e32 v72, v0
	v_mov_b32_e32 v73, v0
	v_mov_b32_e32 v74, v0
	v_mov_b32_e32 v75, v0
	v_mov_b32_e32 v76, v0
	v_mov_b32_e32 v77, v0
	v_mov_b32_e32 v78, v0
	v_mov_b32_e32 v79, v0
	v_mov_b32_e32 v80, v0
	v_mov_b32_e32 v81, v0
	v_mov_b32_e32 v82, v0
	v_mov_b32_e32 v83, v0
	v_mov_b32_e32 v84, v0
	v_mov_b32_e32 v85, v0
	v_mov_b32_e32 v86, v0
	v_mov_b32_e32 v87, v0
	v_mov_b32_e32 v88, v0
	v_mov_b32_e32 v89, v0
	v_mov_b32_e32 v90, v0
	v_mov_b32_e32 v91, v0
	v_mov_b32_e32 v92, v0
	v_mov_b32_e32 v93, v0
	v_mov_b32_e32 v94, v0
	v_mov_b32_e32 v95, v0
	v_mov_b32_e32 v96, v0
	v_mov_b32_e32 v97, v0
	v_mov_b32_e32 v98, v0
	v_mov_b32_e32 v99, v0
	v_mov_b32_e32 v100, v0
	v_mov_b32_e32 v101, v0
	v_mov_b32_e32 v102, v0
	v_mov_b32_e32 v103, v0
	v_mov_b32_e32 v104, v0
	v_mov_b32_e32 v105, v0
	v_mov_b32_e32 v106, v0
	v_mov_b32_e32 v107, v0
	v_mov_b32_e32 v108, v0
	v_mov_b32_e32 v109, v0
	v_mov_b32_e32 v110, v0
	v_mov_b32_e32 v111, v0
	v_mov_b32_e32 v112, v0
	v_mov_b32_e32 v113, v0
	v_mov_b32_e32 v114, v0
	v_mov_b32_e32 v115, v0
	v_mov_b32_e32 v116, v0
	v_mov_b32_e32 v117, v0
	v_mov_b32_e32 v118, v0
	v_mov_b32_e32 v119, v0
	v_mov_b32_e32 v120, v0
	v_mov_b32_e32 v121, v0
	v_mov_b32_e32 v122, v0
	v_mov_b32_e32 v123, v0
	v_mov_b32_e32 v124, v0
	v_mov_b32_e32 v125, v0
	v_mov_b32_e32 v126, v0
	v_mov_b32_e32 v127, v0
	s_waitcnt lgkmcnt(0)
	s_barrier
	s_branch .LBB0_177

; template <bool RES, class Epi>
; DEV void gemm_tile_x(const bf16_t* A0, int lda0, const bf16_t* A1, int lda1, int ksplit,
;                      const bf16_t* Bt, int ldb, int K, char* smem, const float* resb, Epi epi) {
;     ...
;   for (int kt = 0; kt < nk; kt += 2) {
;     GEMM_COMPUTE(sbase);
;     if (kt + 1 < nk) gemm_lds_write(g1, sbase + GST + woff, sbase + GST + GSA + woff);
;     if (kt + 3 < nk) gemm_gload(g1, A0, lda0, A1, lda1, ksplit, Bt, ldb, (kt + 3) * 32, tid);
.LBB0_177:
	s_add_i32 s53, s53, 2
	s_cmp_gt_u32 s53, 28
	ds_read_b128 v[196:199], v200
	ds_read_b128 v[208:211], v201 offset:16384
	ds_read_b128 v[224:227], v201 offset:18432
	ds_read_b128 v[228:231], v200 offset:2048
	ds_read_b128 v[252:255], v203 offset:16384
	s_waitcnt lgkmcnt(3)
	v_mfma_f32_32x32x16_bf16 v[112:127], v[196:199], v[208:211], v[112:127]
	s_waitcnt lgkmcnt(2)
	v_mfma_f32_32x32x16_bf16 v[96:111], v[196:199], v[224:227], v[96:111]
	ds_read_b128 v[196:199], v200 offset:4096
	s_waitcnt lgkmcnt(2)
	v_mfma_f32_32x32x16_bf16 v[80:95], v[228:231], v[208:211], v[80:95]
	v_mfma_f32_32x32x16_bf16 v[64:79], v[228:231], v[224:227], v[64:79]
	ds_read_b128 v[228:231], v200 offset:6144
	s_waitcnt lgkmcnt(1)
	v_mfma_f32_32x32x16_bf16 v[48:63], v[196:199], v[208:211], v[48:63]
	v_mfma_f32_32x32x16_bf16 v[32:47], v[196:199], v[224:227], v[32:47]
	ds_read_b128 v[196:199], v202
	s_waitcnt lgkmcnt(1)
	v_mfma_f32_32x32x16_bf16 v[0:15], v[228:231], v[224:227], v[0:15]
	ds_read_b128 v[224:227], v203 offset:18432
	v_mfma_f32_32x32x16_bf16 v[16:31], v[228:231], v[208:211], v[16:31]
	ds_read_b128 v[228:231], v202 offset:2048
	s_waitcnt lgkmcnt(2)
	v_mfma_f32_32x32x16_bf16 v[112:127], v[196:199], v[252:255], v[112:127]
	s_waitcnt lgkmcnt(1)
	v_mfma_f32_32x32x16_bf16 v[96:111], v[196:199], v[224:227], v[96:111]
	ds_read_b128 v[196:199], v202 offset:4096
	s_waitcnt lgkmcnt(1)
	v_mfma_f32_32x32x16_bf16 v[80:95], v[228:231], v[252:255], v[80:95]
	v_mfma_f32_32x32x16_bf16 v[64:79], v[228:231], v[224:227], v[64:79]
	ds_read_b128 v[228:231], v202 offset:6144
	s_waitcnt vmcnt(5)
	ds_write_b128 v179, v[128:131] offset:24576
	s_waitcnt vmcnt(4)
	ds_write_b128 v179, v[136:139] offset:28672
	s_waitcnt vmcnt(3)
	ds_write_b128 v179, v[144:147] offset:32768
	s_waitcnt vmcnt(2)
	ds_write_b128 v179, v[148:151] offset:36864
	s_waitcnt vmcnt(1)
	ds_write_b128 v179, v[160:163] offset:40960
	s_waitcnt vmcnt(0)
	ds_write_b128 v179, v[168:171] offset:45056
	s_waitcnt lgkmcnt(7)
	v_mfma_f32_32x32x16_bf16 v[48:63], v[196:199], v[252:255], v[48:63]
	v_mfma_f32_32x32x16_bf16 v[32:47], v[196:199], v[224:227], v[32:47]
	s_waitcnt lgkmcnt(6)
	v_mfma_f32_32x32x16_bf16 v[16:31], v[228:231], v[252:255], v[16:31]
	v_mfma_f32_32x32x16_bf16 v[0:15], v[228:231], v[224:227], v[0:15]
	s_waitcnt lgkmcnt(0)
	s_cbranch_scc1 .LBB0_179
	global_load_dwordx4 v[128:131], v[192:193], off offset:192
	s_mov_b32 s56, 0x20000
	v_lshl_add_u64 v[136:137], v[192:193], 0, s[56:57]
	global_load_dwordx4 v[136:139], v[136:137], off offset:192
	s_mov_b32 s56, 0x40000
	v_lshl_add_u64 v[144:145], v[192:193], 0, s[56:57]
	global_load_dwordx4 v[144:147], v[144:145], off offset:192
	s_mov_b32 s56, 0x60000
	v_lshl_add_u64 v[148:149], v[192:193], 0, s[56:57]
	global_load_dwordx4 v[148:151], v[148:149], off offset:192
	global_load_dwordx4 v[160:163], v[194:195], off offset:192
	s_mov_b32 s56, 0x20000
	v_lshl_add_u64 v[168:169], v[194:195], 0, s[56:57]
	global_load_dwordx4 v[168:171], v[168:169], off offset:192

; template <bool RES, class Epi>
; DEV void gemm_tile_x(const bf16_t* A0, int lda0, const bf16_t* A1, int lda1, int ksplit,
;                      const bf16_t* Bt, int ldb, int K, char* smem, const float* resb, Epi epi) {
;     ...
;   for (int kt = 0; kt < nk; kt += 2) {
;     GEMM_COMPUTE(sbase);
;     if (kt + 1 < nk) gemm_lds_write(g1, sbase + GST + woff, sbase + GST + GSA + woff);
;     if (kt + 3 < nk) gemm_gload(g1, A0, lda0, A1, lda1, ksplit, Bt, ldb, (kt + 3) * 32, tid);
;     __syncthreads();
;     if (kt + 1 < nk) {
;       GEMM_COMPUTE(sbase + GST);
;       if (kt + 2 < nk) gemm_lds_write(g, sbase + woff, sbase + GSA + woff);
;       if (kt + 4 < nk) gemm_gload(g, A0, lda0, A1, lda1, ksplit, Bt, ldb, (kt + 4) * 32, tid);
;       __syncthreads();
;     }
;   }
.LBB0_181:
	s_cmp_gt_u32 s53, 27
	s_cbranch_scc1 .LBB0_176
	global_load_dwordx4 v[132:135], v[192:193], off offset:256
	s_mov_b32 s56, 0x20000
	v_lshl_add_u64 v[140:141], v[192:193], 0, s[56:57]
	global_load_dwordx4 v[140:143], v[140:141], off offset:256
	s_mov_b32 s56, 0x40000
	v_lshl_add_u64 v[152:153], v[192:193], 0, s[56:57]
	global_load_dwordx4 v[152:155], v[152:153], off offset:256
	s_mov_b32 s56, 0x60000
	v_lshl_add_u64 v[156:157], v[192:193], 0, s[56:57]
	global_load_dwordx4 v[156:159], v[156:157], off offset:256
	global_load_dwordx4 v[164:167], v[194:195], off offset:256
	s_mov_b32 s56, 0x20000
	v_lshl_add_u64 v[172:173], v[194:195], 0, s[56:57]
	global_load_dwordx4 v[172:175], v[172:173], off offset:256
	s_branch .LBB0_176

; DEV void row16_sum2(float& a, float& b) {
;   asm volatile("s_nop 1\n\tv_add_f32_dpp %0, %0, %0 row_ror:8 row_mask:0xf bank_mask:0xf\n\tv_add_f32_dpp %1, %1, %1 row_ror:8 row_mask:0xf bank_mask:0xf\n\t"
;                "s_nop 1\n\tv_add_f32_dpp %0, %0, %0 row_ror:4 row_mask:0xf bank_mask:0xf\n\tv_add_f32_dpp %1, %1, %1 row_ror:4 row_mask:0xf bank_mask:0xf\n\t"
;                "s_nop 1\n\tv_add_f32_dpp %0, %0, %0 row_ror:2 row_mask:0xf bank_mask:0xf\n\tv_add_f32_dpp %1, %1, %1 row_ror:2 row_mask:0xf bank_mask:0xf\n\t"
;                "s_nop 1\n\tv_add_f32_dpp %0, %0, %0 row_ror:1 row_mask:0xf bank_mask:0xf\n\tv_add_f32_dpp %1, %1, %1 row_ror:1 row_mask:0xf bank_mask:0xf\n\t"
;                "s_nop 0"
;                : "+v"(a), "+v"(b));
.LBB0_1944:
	v_lshlrev_b32_e32 v6, 2, v15
	ds_read_b128 v[14:17], v59 offset:27408
	ds_read_b128 v[18:21], v59 offset:27152
	ds_read_b128 v[22:25], v59 offset:26896
	ds_read_b128 v[26:29], v59 offset:26640
	ds_read_b32 v9, v7 offset:27920
	ds_read_b32 v30, v6 offset:27664
	ds_read_b32 v11, v7 offset:26368
	ds_read_b32 v96, v6 offset:26112
	ds_read_b128 v[32:35], v59 offset:25088
	ds_read_b128 v[76:79], v59 offset:26384
	ds_read_b128 v[80:83], v59 offset:25856
	ds_read_b128 v[84:87], v59 offset:24832
	ds_read_b128 v[88:91], v59 offset:25600
	ds_read_b128 v[92:95], v59 offset:25344
	s_waitcnt lgkmcnt(5)
	v_pk_mul_f32 v[32:33], v[0:1], v[32:33]
	s_waitcnt lgkmcnt(2)
	v_pk_mul_f32 v[0:1], v[0:1], v[84:85]
	v_pk_fma_f32 v[32:33], v[2:3], v[34:35], v[32:33]
	v_pk_mul_f32 v[2:3], v[2:3], v[86:87]
	s_waitcnt lgkmcnt(1)
	v_pk_fma_f32 v[0:1], v[96:97], v[88:89], v[0:1] op_sel_hi:[0,1,1]
	v_pk_fma_f32 v[2:3], v[96:97], v[90:91], v[2:3] op_sel_hi:[0,1,1]
	v_pk_mul_f32 v[34:35], v[80:81], v[0:1]
	v_add_f32_e32 v32, v32, v33
	v_pk_fma_f32 v[34:35], v[82:83], v[2:3], v[34:35]
	s_nop 0
	v_add_f32_e32 v33, v34, v35
	s_nop 0
	v_add_f32_dpp v32, v32, v32 row_ror:8 row_mask:0xf bank_mask:0xf
	v_add_f32_dpp v33, v33, v33 row_ror:8 row_mask:0xf bank_mask:0xf
	s_nop 0
	v_add_f32_dpp v32, v32, v32 row_ror:4 row_mask:0xf bank_mask:0xf
	v_add_f32_dpp v33, v33, v33 row_ror:4 row_mask:0xf bank_mask:0xf
	s_nop 0
	v_add_f32_dpp v32, v32, v32 row_ror:2 row_mask:0xf bank_mask:0xf
	v_add_f32_dpp v33, v33, v33 row_ror:2 row_mask:0xf bank_mask:0xf
	s_nop 0
	v_add_f32_dpp v32, v32, v32 row_ror:1 row_mask:0xf bank_mask:0xf
	v_add_f32_dpp v33, v33, v33 row_ror:1 row_mask:0xf bank_mask:0xf
	s_waitcnt lgkmcnt(0)
	v_pk_fma_f32 v[92:93], v[92:93], v[32:33], v[0:1] op_sel_hi:[1,0,1]
	v_pk_fma_f32 v[94:95], v[94:95], v[32:33], v[2:3] op_sel_hi:[1,0,1]
	v_pk_mul_f32 v[26:27], v[26:27], v[92:93]
	v_fmac_f32_e32 v33, v11, v32
	v_pk_fma_f32 v[26:27], v[28:29], v[94:95], v[26:27]
	v_pk_mul_f32 v[28:29], v[76:77], v[92:93]
	v_pk_mul_f32 v[76:77], v[78:79], v[94:95]
	v_pk_fma_f32 v[18:19], v[30:31], v[18:19], v[28:29] op_sel_hi:[0,1,1]
	ds_write_b32 v60, v33 offset:50688
	v_pk_fma_f32 v[20:21], v[30:31], v[20:21], v[76:77] op_sel_hi:[0,1,1]
	v_pk_mul_f32 v[14:15], v[14:15], v[18:19]
	ds_read_b128 v[0:3], v59 offset:27936
	ds_read_b128 v[32:35], v59 offset:28192
	ds_read_b128 v[80:83], v59 offset:28448
	ds_read_b128 v[84:87], v59 offset:28704
	ds_read_b128 v[88:91], v59 offset:28960
	ds_read_b32 v96, v6 offset:29216
	ds_read_b32 v11, v7 offset:29472
	v_pk_fma_f32 v[14:15], v[16:17], v[20:21], v[14:15]
	v_add_f32_e32 v26, v26, v27
	v_add_f32_e32 v14, v14, v15
	s_nop 0
	v_add_f32_dpp v26, v26, v26 row_ror:8 row_mask:0xf bank_mask:0xf
	v_add_f32_dpp v14, v14, v14 row_ror:8 row_mask:0xf bank_mask:0xf
	s_nop 0
	v_add_f32_dpp v26, v26, v26 row_ror:4 row_mask:0xf bank_mask:0xf
	v_add_f32_dpp v14, v14, v14 row_ror:4 row_mask:0xf bank_mask:0xf
	s_nop 0
	v_add_f32_dpp v26, v26, v26 row_ror:2 row_mask:0xf bank_mask:0xf
	v_add_f32_dpp v14, v14, v14 row_ror:2 row_mask:0xf bank_mask:0xf
	s_nop 0
	v_add_f32_dpp v26, v26, v26 row_ror:1 row_mask:0xf bank_mask:0xf
	v_add_f32_dpp v14, v14, v14 row_ror:1 row_mask:0xf bank_mask:0xf
	v_pk_fma_f32 v[92:93], v[22:23], v[26:27], v[18:19] op_sel_hi:[1,0,1]
	v_pk_fma_f32 v[94:95], v[24:25], v[26:27], v[20:21] op_sel_hi:[1,0,1]
	s_waitcnt lgkmcnt(6)
	v_pk_mul_f32 v[0:1], v[0:1], v[92:93]
	v_fmac_f32_e32 v14, v9, v26
	s_waitcnt lgkmcnt(5)
	v_pk_mul_f32 v[32:33], v[32:33], v[92:93]
	v_pk_mul_f32 v[2:3], v[2:3], v[94:95]
	s_waitcnt lgkmcnt(1)
	v_pk_fma_f32 v[0:1], v[84:85], v[96:97], v[0:1] op_sel_hi:[1,0,1]
	ds_write_b32 v60, v14 offset:50752
	v_pk_fma_f32 v[32:33], v[34:35], v[94:95], v[32:33]
	v_pk_fma_f32 v[2:3], v[86:87], v[96:97], v[2:3] op_sel_hi:[1,0,1]
	v_pk_mul_f32 v[34:35], v[88:89], v[0:1]
	ds_read_b128 v[14:17], v59 offset:29488
	ds_read_b128 v[18:21], v59 offset:29744
	ds_read_b128 v[22:25], v59 offset:30000
	ds_read_b128 v[26:29], v59 offset:30256
	ds_read_b128 v[76:79], v59 offset:30512
	ds_read_b32 v30, v6 offset:30768
	ds_read_b32 v9, v7 offset:31024
	v_pk_fma_f32 v[34:35], v[90:91], v[2:3], v[34:35]
	v_add_f32_e32 v32, v32, v33
	v_add_f32_e32 v33, v34, v35
	s_nop 0
	v_add_f32_dpp v32, v32, v32 row_ror:8 row_mask:0xf bank_mask:0xf
	v_add_f32_dpp v33, v33, v33 row_ror:8 row_mask:0xf bank_mask:0xf
	s_nop 0
	v_add_f32_dpp v32, v32, v32 row_ror:4 row_mask:0xf bank_mask:0xf
	v_add_f32_dpp v33, v33, v33 row_ror:4 row_mask:0xf bank_mask:0xf
	s_nop 0
	v_add_f32_dpp v32, v32, v32 row_ror:2 row_mask:0xf bank_mask:0xf
	v_add_f32_dpp v33, v33, v33 row_ror:2 row_mask:0xf bank_mask:0xf
	s_nop 0
	v_add_f32_dpp v32, v32, v32 row_ror:1 row_mask:0xf bank_mask:0xf
	v_add_f32_dpp v33, v33, v33 row_ror:1 row_mask:0xf bank_mask:0xf
	v_pk_fma_f32 v[92:93], v[80:81], v[32:33], v[0:1] op_sel_hi:[1,0,1]
	v_pk_fma_f32 v[94:95], v[82:83], v[32:33], v[2:3] op_sel_hi:[1,0,1]
	s_waitcnt lgkmcnt(6)
	v_pk_mul_f32 v[14:15], v[14:15], v[92:93]
	v_fmac_f32_e32 v33, v11, v32
	s_waitcnt lgkmcnt(5)
	v_pk_mul_f32 v[18:19], v[18:19], v[92:93]
	v_pk_mul_f32 v[16:17], v[16:17], v[94:95]
	s_waitcnt lgkmcnt(1)
; DEV void row16_sum2(float& a, float& b) {
;   asm volatile("s_nop 1\n\tv_add_f32_dpp %0, %0, %0 row_ror:8 row_mask:0xf bank_mask:0xf\n\tv_add_f32_dpp %1, %1, %1 row_ror:8 row_mask:0xf bank_mask:0xf\n\t"
;                "s_nop 1\n\tv_add_f32_dpp %0, %0, %0 row_ror:4 row_mask:0xf bank_mask:0xf\n\tv_add_f32_dpp %1, %1, %1 row_ror:4 row_mask:0xf bank_mask:0xf\n\t"
;                "s_nop 1\n\tv_add_f32_dpp %0, %0, %0 row_ror:2 row_mask:0xf bank_mask:0xf\n\tv_add_f32_dpp %1, %1, %1 row_ror:2 row_mask:0xf bank_mask:0xf\n\t"
;                "s_nop 1\n\tv_add_f32_dpp %0, %0, %0 row_ror:1 row_mask:0xf bank_mask:0xf\n\tv_add_f32_dpp %1, %1, %1 row_ror:1 row_mask:0xf bank_mask:0xf\n\t"
;                "s_nop 0"
;                : "+v"(a), "+v"(b));
	v_pk_fma_f32 v[14:15], v[26:27], v[30:31], v[14:15] op_sel_hi:[1,0,1]
	ds_write_b32 v60, v33 offset:50816
	v_pk_fma_f32 v[18:19], v[20:21], v[94:95], v[18:19]
	v_pk_fma_f32 v[16:17], v[28:29], v[30:31], v[16:17] op_sel_hi:[1,0,1]
	v_pk_mul_f32 v[20:21], v[76:77], v[14:15]
	ds_read_b128 v[0:3], v59 offset:31040
	ds_read_b128 v[32:35], v59 offset:31296
	ds_read_b128 v[80:83], v59 offset:31552
	ds_read_b128 v[84:87], v59 offset:31808
	ds_read_b128 v[88:91], v59 offset:32064
	ds_read_b32 v96, v6 offset:32320
	ds_read_b32 v11, v7 offset:32576
	v_pk_fma_f32 v[20:21], v[78:79], v[16:17], v[20:21]
	v_add_f32_e32 v18, v18, v19
	v_add_f32_e32 v19, v20, v21
	s_nop 0
	v_add_f32_dpp v18, v18, v18 row_ror:8 row_mask:0xf bank_mask:0xf
	v_add_f32_dpp v19, v19, v19 row_ror:8 row_mask:0xf bank_mask:0xf
	s_nop 0
	v_add_f32_dpp v18, v18, v18 row_ror:4 row_mask:0xf bank_mask:0xf
	v_add_f32_dpp v19, v19, v19 row_ror:4 row_mask:0xf bank_mask:0xf
	s_nop 0
	v_add_f32_dpp v18, v18, v18 row_ror:2 row_mask:0xf bank_mask:0xf
	v_add_f32_dpp v19, v19, v19 row_ror:2 row_mask:0xf bank_mask:0xf
	s_nop 0
	v_add_f32_dpp v18, v18, v18 row_ror:1 row_mask:0xf bank_mask:0xf
	v_add_f32_dpp v19, v19, v19 row_ror:1 row_mask:0xf bank_mask:0xf
	v_pk_fma_f32 v[92:93], v[22:23], v[18:19], v[14:15] op_sel_hi:[1,0,1]
	v_pk_fma_f32 v[94:95], v[24:25], v[18:19], v[16:17] op_sel_hi:[1,0,1]
	s_waitcnt lgkmcnt(6)
	v_pk_mul_f32 v[0:1], v[0:1], v[92:93]
	s_waitcnt lgkmcnt(5)
	v_pk_mul_f32 v[32:33], v[32:33], v[92:93]
	v_pk_mul_f32 v[2:3], v[2:3], v[94:95]
	s_waitcnt lgkmcnt(1)
	v_pk_fma_f32 v[0:1], v[84:85], v[96:97], v[0:1] op_sel_hi:[1,0,1]
	v_fmac_f32_e32 v19, v9, v18
	v_pk_fma_f32 v[32:33], v[34:35], v[94:95], v[32:33]
	v_pk_fma_f32 v[2:3], v[86:87], v[96:97], v[2:3] op_sel_hi:[1,0,1]
	v_pk_mul_f32 v[34:35], v[88:89], v[0:1]
	ds_write_b32 v60, v19 offset:50880
	v_pk_fma_f32 v[34:35], v[90:91], v[2:3], v[34:35]
	ds_read_b128 v[14:17], v59 offset:32848
	ds_read_b128 v[18:21], v59 offset:33104
	ds_read_b128 v[22:25], v59 offset:33360
	ds_read_b128 v[26:29], v59 offset:33616
	ds_read_b128 v[76:79], v59 offset:32592
	ds_read_b32 v30, v6 offset:33872
	ds_read_b32 v9, v7 offset:34128
	v_add_f32_e32 v32, v32, v33
	v_add_f32_e32 v33, v34, v35
	s_nop 0
	v_add_f32_dpp v32, v32, v32 row_ror:8 row_mask:0xf bank_mask:0xf
	v_add_f32_dpp v33, v33, v33 row_ror:8 row_mask:0xf bank_mask:0xf
	s_nop 0
	v_add_f32_dpp v32, v32, v32 row_ror:4 row_mask:0xf bank_mask:0xf
	v_add_f32_dpp v33, v33, v33 row_ror:4 row_mask:0xf bank_mask:0xf
	s_nop 0
	v_add_f32_dpp v32, v32, v32 row_ror:2 row_mask:0xf bank_mask:0xf
	v_add_f32_dpp v33, v33, v33 row_ror:2 row_mask:0xf bank_mask:0xf
	s_nop 0
	v_add_f32_dpp v32, v32, v32 row_ror:1 row_mask:0xf bank_mask:0xf
	v_add_f32_dpp v33, v33, v33 row_ror:1 row_mask:0xf bank_mask:0xf
	v_pk_fma_f32 v[92:93], v[80:81], v[32:33], v[0:1] op_sel_hi:[1,0,1]
	v_pk_fma_f32 v[94:95], v[82:83], v[32:33], v[2:3] op_sel_hi:[1,0,1]
	s_waitcnt lgkmcnt(6)
	v_pk_mul_f32 v[14:15], v[14:15], v[92:93]
	v_fmac_f32_e32 v33, v11, v32
	v_pk_fma_f32 v[14:15], v[16:17], v[94:95], v[14:15]
	s_waitcnt lgkmcnt(2)
	v_pk_mul_f32 v[16:17], v[76:77], v[92:93]
	v_pk_mul_f32 v[76:77], v[78:79], v[94:95]
	s_waitcnt lgkmcnt(1)
	v_pk_fma_f32 v[16:17], v[22:23], v[30:31], v[16:17] op_sel_hi:[1,0,1]
	ds_write_b32 v60, v33 offset:50944
	v_pk_fma_f32 v[22:23], v[24:25], v[30:31], v[76:77] op_sel_hi:[1,0,1]
	v_pk_mul_f32 v[24:25], v[26:27], v[16:17]
	ds_read_b128 v[0:3], v59 offset:34144
	ds_read_b128 v[32:35], v59 offset:34400
	ds_read_b128 v[80:83], v59 offset:34656
	ds_read_b128 v[84:87], v59 offset:34912
	ds_read_b128 v[88:91], v59 offset:35168
	ds_read_b32 v96, v6 offset:35424
	ds_read_b32 v11, v7 offset:35680
	v_pk_fma_f32 v[24:25], v[28:29], v[22:23], v[24:25]
	v_add_f32_e32 v14, v14, v15
	v_add_f32_e32 v15, v24, v25
	s_nop 0
	v_add_f32_dpp v14, v14, v14 row_ror:8 row_mask:0xf bank_mask:0xf
	v_add_f32_dpp v15, v15, v15 row_ror:8 row_mask:0xf bank_mask:0xf
	s_nop 0
	v_add_f32_dpp v14, v14, v14 row_ror:4 row_mask:0xf bank_mask:0xf
	v_add_f32_dpp v15, v15, v15 row_ror:4 row_mask:0xf bank_mask:0xf
	s_nop 0
	v_add_f32_dpp v14, v14, v14 row_ror:2 row_mask:0xf bank_mask:0xf
	v_add_f32_dpp v15, v15, v15 row_ror:2 row_mask:0xf bank_mask:0xf
	s_nop 0
	v_add_f32_dpp v14, v14, v14 row_ror:1 row_mask:0xf bank_mask:0xf
	v_add_f32_dpp v15, v15, v15 row_ror:1 row_mask:0xf bank_mask:0xf
	v_pk_fma_f32 v[92:93], v[18:19], v[14:15], v[16:17] op_sel_hi:[1,0,1]
	v_pk_fma_f32 v[94:95], v[20:21], v[14:15], v[22:23] op_sel_hi:[1,0,1]
	s_waitcnt lgkmcnt(6)
	v_pk_mul_f32 v[0:1], v[0:1], v[92:93]
	v_fmac_f32_e32 v15, v9, v14
	s_waitcnt lgkmcnt(5)
	v_pk_mul_f32 v[32:33], v[32:33], v[92:93]
	v_pk_mul_f32 v[2:3], v[2:3], v[94:95]
	s_waitcnt lgkmcnt(1)
	v_pk_fma_f32 v[0:1], v[84:85], v[96:97], v[0:1] op_sel_hi:[1,0,1]
	ds_write_b32 v60, v15 offset:51008
	v_pk_fma_f32 v[32:33], v[34:35], v[94:95], v[32:33]
	v_pk_fma_f32 v[2:3], v[86:87], v[96:97], v[2:3] op_sel_hi:[1,0,1]
	v_pk_mul_f32 v[34:35], v[88:89], v[0:1]
	ds_read_b128 v[14:17], v59 offset:35696
	ds_read_b128 v[18:21], v59 offset:35952
	ds_read_b128 v[22:25], v59 offset:36208
	ds_read_b128 v[26:29], v59 offset:36464
	ds_read_b128 v[76:79], v59 offset:36720
	ds_read_b32 v30, v6 offset:36976
	ds_read_b32 v9, v7 offset:37232
	v_pk_fma_f32 v[34:35], v[90:91], v[2:3], v[34:35]
	v_add_f32_e32 v32, v32, v33
	v_add_f32_e32 v33, v34, v35
	s_nop 0
	v_add_f32_dpp v32, v32, v32 row_ror:8 row_mask:0xf bank_mask:0xf
	v_add_f32_dpp v33, v33, v33 row_ror:8 row_mask:0xf bank_mask:0xf
	s_nop 0
	v_add_f32_dpp v32, v32, v32 row_ror:4 row_mask:0xf bank_mask:0xf
	v_add_f32_dpp v33, v33, v33 row_ror:4 row_mask:0xf bank_mask:0xf
	s_nop 0
	v_add_f32_dpp v32, v32, v32 row_ror:2 row_mask:0xf bank_mask:0xf
	v_add_f32_dpp v33, v33, v33 row_ror:2 row_mask:0xf bank_mask:0xf
	s_nop 0
	v_add_f32_dpp v32, v32, v32 row_ror:1 row_mask:0xf bank_mask:0xf
	v_add_f32_dpp v33, v33, v33 row_ror:1 row_mask:0xf bank_mask:0xf
	v_pk_fma_f32 v[92:93], v[80:81], v[32:33], v[0:1] op_sel_hi:[1,0,1]
	v_pk_fma_f32 v[94:95], v[82:83], v[32:33], v[2:3] op_sel_hi:[1,0,1]
	s_waitcnt lgkmcnt(6)
; DEV void row16_sum2(float& a, float& b) {
;   asm volatile("s_nop 1\n\tv_add_f32_dpp %0, %0, %0 row_ror:8 row_mask:0xf bank_mask:0xf\n\tv_add_f32_dpp %1, %1, %1 row_ror:8 row_mask:0xf bank_mask:0xf\n\t"
;                "s_nop 1\n\tv_add_f32_dpp %0, %0, %0 row_ror:4 row_mask:0xf bank_mask:0xf\n\tv_add_f32_dpp %1, %1, %1 row_ror:4 row_mask:0xf bank_mask:0xf\n\t"
;                "s_nop 1\n\tv_add_f32_dpp %0, %0, %0 row_ror:2 row_mask:0xf bank_mask:0xf\n\tv_add_f32_dpp %1, %1, %1 row_ror:2 row_mask:0xf bank_mask:0xf\n\t"
;                "s_nop 1\n\tv_add_f32_dpp %0, %0, %0 row_ror:1 row_mask:0xf bank_mask:0xf\n\tv_add_f32_dpp %1, %1, %1 row_ror:1 row_mask:0xf bank_mask:0xf\n\t"
;                "s_nop 0"
;                : "+v"(a), "+v"(b));
	v_pk_mul_f32 v[14:15], v[14:15], v[92:93]
	v_fmac_f32_e32 v33, v11, v32
	s_waitcnt lgkmcnt(5)
	v_pk_mul_f32 v[18:19], v[18:19], v[92:93]
	v_pk_mul_f32 v[16:17], v[16:17], v[94:95]
	s_waitcnt lgkmcnt(1)
	v_pk_fma_f32 v[14:15], v[26:27], v[30:31], v[14:15] op_sel_hi:[1,0,1]
	ds_write_b32 v60, v33 offset:51072
	v_pk_fma_f32 v[18:19], v[20:21], v[94:95], v[18:19]
	v_pk_fma_f32 v[16:17], v[28:29], v[30:31], v[16:17] op_sel_hi:[1,0,1]
	v_pk_mul_f32 v[20:21], v[76:77], v[14:15]
	ds_read_b128 v[0:3], v59 offset:37248
	ds_read_b128 v[32:35], v59 offset:37504
	ds_read_b128 v[80:83], v59 offset:37760
	ds_read_b128 v[84:87], v59 offset:38016
	ds_read_b128 v[88:91], v59 offset:38272
	ds_read_b32 v96, v6 offset:38528
	ds_read_b32 v11, v7 offset:38784
	v_pk_fma_f32 v[20:21], v[78:79], v[16:17], v[20:21]
	v_add_f32_e32 v18, v18, v19
	v_add_f32_e32 v19, v20, v21
	s_nop 0
	v_add_f32_dpp v18, v18, v18 row_ror:8 row_mask:0xf bank_mask:0xf
	v_add_f32_dpp v19, v19, v19 row_ror:8 row_mask:0xf bank_mask:0xf
	s_nop 0
	v_add_f32_dpp v18, v18, v18 row_ror:4 row_mask:0xf bank_mask:0xf
	v_add_f32_dpp v19, v19, v19 row_ror:4 row_mask:0xf bank_mask:0xf
	s_nop 0
	v_add_f32_dpp v18, v18, v18 row_ror:2 row_mask:0xf bank_mask:0xf
	v_add_f32_dpp v19, v19, v19 row_ror:2 row_mask:0xf bank_mask:0xf
	s_nop 0
	v_add_f32_dpp v18, v18, v18 row_ror:1 row_mask:0xf bank_mask:0xf
	v_add_f32_dpp v19, v19, v19 row_ror:1 row_mask:0xf bank_mask:0xf
	v_pk_fma_f32 v[92:93], v[22:23], v[18:19], v[14:15] op_sel_hi:[1,0,1]
	v_pk_fma_f32 v[94:95], v[24:25], v[18:19], v[16:17] op_sel_hi:[1,0,1]
	s_waitcnt lgkmcnt(6)
	v_pk_mul_f32 v[0:1], v[0:1], v[92:93]
	v_fmac_f32_e32 v19, v9, v18
	s_waitcnt lgkmcnt(5)
	v_pk_mul_f32 v[32:33], v[32:33], v[92:93]
	v_pk_mul_f32 v[2:3], v[2:3], v[94:95]
	s_waitcnt lgkmcnt(1)
	v_pk_fma_f32 v[0:1], v[84:85], v[96:97], v[0:1] op_sel_hi:[1,0,1]
	ds_write_b32 v60, v19 offset:51136
	v_pk_fma_f32 v[32:33], v[34:35], v[94:95], v[32:33]
	v_pk_fma_f32 v[2:3], v[86:87], v[96:97], v[2:3] op_sel_hi:[1,0,1]
	v_pk_mul_f32 v[34:35], v[88:89], v[0:1]
	ds_read_b128 v[14:17], v59 offset:38800
	ds_read_b128 v[18:21], v59 offset:39056
	ds_read_b128 v[22:25], v59 offset:39312
	ds_read_b128 v[26:29], v59 offset:39568
	ds_read_b128 v[76:79], v59 offset:39824
	ds_read_b32 v30, v6 offset:40080
	ds_read_b32 v9, v7 offset:40336
	v_pk_fma_f32 v[34:35], v[90:91], v[2:3], v[34:35]
	v_add_f32_e32 v32, v32, v33
	v_add_f32_e32 v33, v34, v35
	s_nop 0
	v_add_f32_dpp v32, v32, v32 row_ror:8 row_mask:0xf bank_mask:0xf
	v_add_f32_dpp v33, v33, v33 row_ror:8 row_mask:0xf bank_mask:0xf
	s_nop 0
	v_add_f32_dpp v32, v32, v32 row_ror:4 row_mask:0xf bank_mask:0xf
	v_add_f32_dpp v33, v33, v33 row_ror:4 row_mask:0xf bank_mask:0xf
	s_nop 0
	v_add_f32_dpp v32, v32, v32 row_ror:2 row_mask:0xf bank_mask:0xf
	v_add_f32_dpp v33, v33, v33 row_ror:2 row_mask:0xf bank_mask:0xf
	s_nop 0
	v_add_f32_dpp v32, v32, v32 row_ror:1 row_mask:0xf bank_mask:0xf
	v_add_f32_dpp v33, v33, v33 row_ror:1 row_mask:0xf bank_mask:0xf
	v_pk_fma_f32 v[92:93], v[80:81], v[32:33], v[0:1] op_sel_hi:[1,0,1]
	v_pk_fma_f32 v[94:95], v[82:83], v[32:33], v[2:3] op_sel_hi:[1,0,1]
	s_waitcnt lgkmcnt(6)
	v_pk_mul_f32 v[14:15], v[14:15], v[92:93]
	v_fmac_f32_e32 v33, v11, v32
	s_waitcnt lgkmcnt(5)
	v_pk_mul_f32 v[18:19], v[18:19], v[92:93]
	v_pk_mul_f32 v[16:17], v[16:17], v[94:95]
	s_waitcnt lgkmcnt(1)
	v_pk_fma_f32 v[14:15], v[26:27], v[30:31], v[14:15] op_sel_hi:[1,0,1]
	ds_write_b32 v60, v33 offset:51200
	v_pk_fma_f32 v[18:19], v[20:21], v[94:95], v[18:19]
	v_pk_fma_f32 v[16:17], v[28:29], v[30:31], v[16:17] op_sel_hi:[1,0,1]
	v_pk_mul_f32 v[20:21], v[76:77], v[14:15]
	ds_read_b128 v[0:3], v59 offset:40352
	ds_read_b128 v[32:35], v59 offset:40608
	ds_read_b128 v[80:83], v59 offset:40864
	ds_read_b128 v[84:87], v59 offset:41120
	ds_read_b128 v[88:91], v59 offset:41376
	ds_read_b32 v96, v6 offset:41632
	ds_read_b32 v11, v7 offset:41888
	v_pk_fma_f32 v[20:21], v[78:79], v[16:17], v[20:21]
	v_add_f32_e32 v18, v18, v19
	v_add_f32_e32 v19, v20, v21
	s_nop 0
	v_add_f32_dpp v18, v18, v18 row_ror:8 row_mask:0xf bank_mask:0xf
	v_add_f32_dpp v19, v19, v19 row_ror:8 row_mask:0xf bank_mask:0xf
	s_nop 0
	v_add_f32_dpp v18, v18, v18 row_ror:4 row_mask:0xf bank_mask:0xf
	v_add_f32_dpp v19, v19, v19 row_ror:4 row_mask:0xf bank_mask:0xf
	s_nop 0
	v_add_f32_dpp v18, v18, v18 row_ror:2 row_mask:0xf bank_mask:0xf
	v_add_f32_dpp v19, v19, v19 row_ror:2 row_mask:0xf bank_mask:0xf
	s_nop 0
	v_add_f32_dpp v18, v18, v18 row_ror:1 row_mask:0xf bank_mask:0xf
	v_add_f32_dpp v19, v19, v19 row_ror:1 row_mask:0xf bank_mask:0xf
	v_pk_fma_f32 v[92:93], v[22:23], v[18:19], v[14:15] op_sel_hi:[1,0,1]
	v_pk_fma_f32 v[94:95], v[24:25], v[18:19], v[16:17] op_sel_hi:[1,0,1]
	s_waitcnt lgkmcnt(6)
	v_pk_mul_f32 v[0:1], v[0:1], v[92:93]
	v_fmac_f32_e32 v19, v9, v18
	s_waitcnt lgkmcnt(5)
	v_pk_mul_f32 v[32:33], v[32:33], v[92:93]
	v_pk_mul_f32 v[2:3], v[2:3], v[94:95]
	s_waitcnt lgkmcnt(1)
	v_pk_fma_f32 v[0:1], v[84:85], v[96:97], v[0:1] op_sel_hi:[1,0,1]
	ds_write_b32 v60, v19 offset:51264
	v_pk_fma_f32 v[32:33], v[34:35], v[94:95], v[32:33]
	v_pk_fma_f32 v[2:3], v[86:87], v[96:97], v[2:3] op_sel_hi:[1,0,1]
	v_pk_mul_f32 v[34:35], v[88:89], v[0:1]
	ds_read_b128 v[14:17], v59 offset:41904
	ds_read_b128 v[18:21], v59 offset:42160
	ds_read_b128 v[22:25], v59 offset:42416
	ds_read_b128 v[26:29], v59 offset:42672
	ds_read_b128 v[76:79], v59 offset:42928
	ds_read_b32 v30, v6 offset:43184
	ds_read_b32 v9, v7 offset:43440
	v_pk_fma_f32 v[34:35], v[90:91], v[2:3], v[34:35]
	v_add_f32_e32 v32, v32, v33
	v_add_f32_e32 v33, v34, v35
	s_nop 0
	v_add_f32_dpp v32, v32, v32 row_ror:8 row_mask:0xf bank_mask:0xf
	v_add_f32_dpp v33, v33, v33 row_ror:8 row_mask:0xf bank_mask:0xf
	s_nop 0
	v_add_f32_dpp v32, v32, v32 row_ror:4 row_mask:0xf bank_mask:0xf
	v_add_f32_dpp v33, v33, v33 row_ror:4 row_mask:0xf bank_mask:0xf
	s_nop 0
	v_add_f32_dpp v32, v32, v32 row_ror:2 row_mask:0xf bank_mask:0xf
	v_add_f32_dpp v33, v33, v33 row_ror:2 row_mask:0xf bank_mask:0xf
	s_nop 0
	v_add_f32_dpp v32, v32, v32 row_ror:1 row_mask:0xf bank_mask:0xf
	v_add_f32_dpp v33, v33, v33 row_ror:1 row_mask:0xf bank_mask:0xf
	v_pk_fma_f32 v[92:93], v[80:81], v[32:33], v[0:1] op_sel_hi:[1,0,1]
	v_pk_fma_f32 v[94:95], v[82:83], v[32:33], v[2:3] op_sel_hi:[1,0,1]
	s_waitcnt lgkmcnt(6)
; DEV void row16_sum2(float& a, float& b) {
;   asm volatile("s_nop 1\n\tv_add_f32_dpp %0, %0, %0 row_ror:8 row_mask:0xf bank_mask:0xf\n\tv_add_f32_dpp %1, %1, %1 row_ror:8 row_mask:0xf bank_mask:0xf\n\t"
;                "s_nop 1\n\tv_add_f32_dpp %0, %0, %0 row_ror:4 row_mask:0xf bank_mask:0xf\n\tv_add_f32_dpp %1, %1, %1 row_ror:4 row_mask:0xf bank_mask:0xf\n\t"
;                "s_nop 1\n\tv_add_f32_dpp %0, %0, %0 row_ror:2 row_mask:0xf bank_mask:0xf\n\tv_add_f32_dpp %1, %1, %1 row_ror:2 row_mask:0xf bank_mask:0xf\n\t"
;                "s_nop 1\n\tv_add_f32_dpp %0, %0, %0 row_ror:1 row_mask:0xf bank_mask:0xf\n\tv_add_f32_dpp %1, %1, %1 row_ror:1 row_mask:0xf bank_mask:0xf\n\t"
;                "s_nop 0"
;                : "+v"(a), "+v"(b));
	v_pk_mul_f32 v[14:15], v[14:15], v[92:93]
	v_fmac_f32_e32 v33, v11, v32
	s_waitcnt lgkmcnt(5)
	v_pk_mul_f32 v[18:19], v[18:19], v[92:93]
	v_pk_mul_f32 v[16:17], v[16:17], v[94:95]
	s_waitcnt lgkmcnt(1)
	v_pk_fma_f32 v[14:15], v[26:27], v[30:31], v[14:15] op_sel_hi:[1,0,1]
	ds_write_b32 v60, v33 offset:51328
	v_pk_fma_f32 v[18:19], v[20:21], v[94:95], v[18:19]
	v_pk_fma_f32 v[16:17], v[28:29], v[30:31], v[16:17] op_sel_hi:[1,0,1]
	v_pk_mul_f32 v[20:21], v[76:77], v[14:15]
	ds_read_b128 v[0:3], v59 offset:43456
	ds_read_b128 v[32:35], v59 offset:43712
	ds_read_b128 v[80:83], v59 offset:43968
	ds_read_b128 v[84:87], v59 offset:44224
	ds_read_b128 v[88:91], v59 offset:44480
	ds_read_b32 v96, v6 offset:44736
	ds_read_b32 v11, v7 offset:44992
	v_pk_fma_f32 v[20:21], v[78:79], v[16:17], v[20:21]
	v_add_f32_e32 v18, v18, v19
	v_add_f32_e32 v19, v20, v21
	s_nop 0
	v_add_f32_dpp v18, v18, v18 row_ror:8 row_mask:0xf bank_mask:0xf
	v_add_f32_dpp v19, v19, v19 row_ror:8 row_mask:0xf bank_mask:0xf
	s_nop 0
	v_add_f32_dpp v18, v18, v18 row_ror:4 row_mask:0xf bank_mask:0xf
	v_add_f32_dpp v19, v19, v19 row_ror:4 row_mask:0xf bank_mask:0xf
	s_nop 0
	v_add_f32_dpp v18, v18, v18 row_ror:2 row_mask:0xf bank_mask:0xf
	v_add_f32_dpp v19, v19, v19 row_ror:2 row_mask:0xf bank_mask:0xf
	s_nop 0
	v_add_f32_dpp v18, v18, v18 row_ror:1 row_mask:0xf bank_mask:0xf
	v_add_f32_dpp v19, v19, v19 row_ror:1 row_mask:0xf bank_mask:0xf
	v_pk_fma_f32 v[92:93], v[22:23], v[18:19], v[14:15] op_sel_hi:[1,0,1]
	v_pk_fma_f32 v[94:95], v[24:25], v[18:19], v[16:17] op_sel_hi:[1,0,1]
	s_waitcnt lgkmcnt(6)
	v_pk_mul_f32 v[0:1], v[0:1], v[92:93]
	v_fmac_f32_e32 v19, v9, v18
	s_waitcnt lgkmcnt(5)
	v_pk_mul_f32 v[32:33], v[32:33], v[92:93]
	v_pk_mul_f32 v[2:3], v[2:3], v[94:95]
	s_waitcnt lgkmcnt(1)
	v_pk_fma_f32 v[0:1], v[84:85], v[96:97], v[0:1] op_sel_hi:[1,0,1]
	ds_write_b32 v60, v19 offset:51392
	v_pk_fma_f32 v[32:33], v[34:35], v[94:95], v[32:33]
	v_pk_fma_f32 v[2:3], v[86:87], v[96:97], v[2:3] op_sel_hi:[1,0,1]
	v_pk_mul_f32 v[34:35], v[88:89], v[0:1]
	ds_read_b128 v[14:17], v59 offset:45008
	ds_read_b128 v[18:21], v59 offset:45264
	ds_read_b128 v[22:25], v59 offset:45520
	ds_read_b128 v[26:29], v59 offset:45776
	ds_read_b128 v[76:79], v59 offset:46032
	ds_read_b32 v30, v6 offset:46288
	ds_read_b32 v9, v7 offset:46544
	v_pk_fma_f32 v[34:35], v[90:91], v[2:3], v[34:35]
	v_add_f32_e32 v32, v32, v33
	v_add_f32_e32 v33, v34, v35
	s_nop 0
	v_add_f32_dpp v32, v32, v32 row_ror:8 row_mask:0xf bank_mask:0xf
	v_add_f32_dpp v33, v33, v33 row_ror:8 row_mask:0xf bank_mask:0xf
	s_nop 0
	v_add_f32_dpp v32, v32, v32 row_ror:4 row_mask:0xf bank_mask:0xf
	v_add_f32_dpp v33, v33, v33 row_ror:4 row_mask:0xf bank_mask:0xf
	s_nop 0
	v_add_f32_dpp v32, v32, v32 row_ror:2 row_mask:0xf bank_mask:0xf
	v_add_f32_dpp v33, v33, v33 row_ror:2 row_mask:0xf bank_mask:0xf
	s_nop 0
	v_add_f32_dpp v32, v32, v32 row_ror:1 row_mask:0xf bank_mask:0xf
	v_add_f32_dpp v33, v33, v33 row_ror:1 row_mask:0xf bank_mask:0xf
	v_pk_fma_f32 v[92:93], v[80:81], v[32:33], v[0:1] op_sel_hi:[1,0,1]
	v_pk_fma_f32 v[94:95], v[82:83], v[32:33], v[2:3] op_sel_hi:[1,0,1]
	s_waitcnt lgkmcnt(6)
	v_pk_mul_f32 v[14:15], v[14:15], v[92:93]
	v_fmac_f32_e32 v33, v11, v32
	s_waitcnt lgkmcnt(5)
	v_pk_mul_f32 v[18:19], v[18:19], v[92:93]
	v_pk_mul_f32 v[16:17], v[16:17], v[94:95]
	s_waitcnt lgkmcnt(1)
; template <int RPL>
; DEV void rwkv_scan(const Params& p, int tb, int T, int head, int dir, int split, float* st) {
;     ...
;   RW_LOAD(rawA, scA, 0);
;   RW_STAGE(rawA, scA, 0, 0);
;   __syncthreads();
;   for (int ch = 0; ch < nch; ++ch) {
;     if (ch + 1 < nch) { RW_LOAD(rawA, scA, ch + 1); }
;     RW_MAIN(ch);
;     if (ch + 1 < nch) { RW_STAGE(rawA, scA, ch + 1, (ch + 1) & 1); }
;     __syncthreads();
;     RW_FLUSH(ch);
	v_pk_fma_f32 v[14:15], v[26:27], v[30:31], v[14:15] op_sel_hi:[1,0,1]
	ds_write_b32 v60, v33 offset:51456
	v_pk_fma_f32 v[18:19], v[20:21], v[94:95], v[18:19]
	v_pk_fma_f32 v[16:17], v[28:29], v[30:31], v[16:17] op_sel_hi:[1,0,1]
	v_pk_mul_f32 v[20:21], v[76:77], v[14:15]
	ds_read_b128 v[0:3], v59 offset:46560
	ds_read_b128 v[32:35], v59 offset:46816
	ds_read_b128 v[80:83], v59 offset:47072
	ds_read_b128 v[84:87], v59 offset:47328
	ds_read_b128 v[88:91], v59 offset:47584
	ds_read_b32 v96, v6 offset:47840
	ds_read_b32 v11, v7 offset:48096
	v_pk_fma_f32 v[20:21], v[78:79], v[16:17], v[20:21]
	v_add_f32_e32 v18, v18, v19
	v_add_f32_e32 v19, v20, v21
	s_nop 0
	v_add_f32_dpp v18, v18, v18 row_ror:8 row_mask:0xf bank_mask:0xf
	v_add_f32_dpp v19, v19, v19 row_ror:8 row_mask:0xf bank_mask:0xf
	s_nop 0
	v_add_f32_dpp v18, v18, v18 row_ror:4 row_mask:0xf bank_mask:0xf
	v_add_f32_dpp v19, v19, v19 row_ror:4 row_mask:0xf bank_mask:0xf
	s_nop 0
	v_add_f32_dpp v18, v18, v18 row_ror:2 row_mask:0xf bank_mask:0xf
	v_add_f32_dpp v19, v19, v19 row_ror:2 row_mask:0xf bank_mask:0xf
	s_nop 0
	v_add_f32_dpp v18, v18, v18 row_ror:1 row_mask:0xf bank_mask:0xf
	v_add_f32_dpp v19, v19, v19 row_ror:1 row_mask:0xf bank_mask:0xf
	v_pk_fma_f32 v[76:77], v[22:23], v[18:19], v[14:15] op_sel_hi:[1,0,1]
	v_pk_fma_f32 v[78:79], v[24:25], v[18:19], v[16:17] op_sel_hi:[1,0,1]
	s_waitcnt lgkmcnt(5)
	v_pk_mul_f32 v[32:33], v[32:33], v[76:77]
	v_pk_mul_f32 v[0:1], v[0:1], v[76:77]
	v_fmac_f32_e32 v19, v9, v18
	v_pk_fma_f32 v[32:33], v[34:35], v[78:79], v[32:33]
	v_pk_mul_f32 v[2:3], v[2:3], v[78:79]
	s_waitcnt lgkmcnt(1)
	v_pk_fma_f32 v[0:1], v[84:85], v[96:97], v[0:1] op_sel_hi:[1,0,1]
	ds_write_b32 v60, v19 offset:51520
	v_add_f32_e32 v30, v32, v33
	v_pk_fma_f32 v[2:3], v[86:87], v[96:97], v[2:3] op_sel_hi:[1,0,1]
	v_pk_mul_f32 v[32:33], v[88:89], v[0:1]
	ds_read_b128 v[14:17], v59 offset:48112
	ds_read_b128 v[18:21], v59 offset:48368
	ds_read_b128 v[22:25], v59 offset:48880
	ds_read_b128 v[26:29], v59 offset:49136
	ds_read_b32 v6, v6 offset:49392
	ds_read_b32 v9, v7 offset:49648
	v_pk_fma_f32 v[32:33], v[90:91], v[2:3], v[32:33]
	s_nop 0
	v_add_f32_e32 v32, v32, v33
	s_nop 0
	v_add_f32_dpp v30, v30, v30 row_ror:8 row_mask:0xf bank_mask:0xf
	v_add_f32_dpp v32, v32, v32 row_ror:8 row_mask:0xf bank_mask:0xf
	s_nop 0
	v_add_f32_dpp v30, v30, v30 row_ror:4 row_mask:0xf bank_mask:0xf
	v_add_f32_dpp v32, v32, v32 row_ror:4 row_mask:0xf bank_mask:0xf
	s_nop 0
	v_add_f32_dpp v30, v30, v30 row_ror:2 row_mask:0xf bank_mask:0xf
	v_add_f32_dpp v32, v32, v32 row_ror:2 row_mask:0xf bank_mask:0xf
	s_nop 0
	v_add_f32_dpp v30, v30, v30 row_ror:1 row_mask:0xf bank_mask:0xf
	v_add_f32_dpp v32, v32, v32 row_ror:1 row_mask:0xf bank_mask:0xf
	v_pk_fma_f32 v[0:1], v[80:81], v[30:31], v[0:1] op_sel_hi:[1,0,1]
	v_pk_fma_f32 v[2:3], v[82:83], v[30:31], v[2:3] op_sel_hi:[1,0,1]
	s_waitcnt lgkmcnt(4)
	v_pk_mul_f32 v[18:19], v[18:19], v[0:1]
	v_pk_mul_f32 v[0:1], v[14:15], v[0:1]
	v_pk_fma_f32 v[18:19], v[20:21], v[2:3], v[18:19]
	v_pk_mul_f32 v[2:3], v[16:17], v[2:3]
	s_waitcnt lgkmcnt(1)
	v_pk_fma_f32 v[0:1], v[22:23], v[6:7], v[0:1] op_sel_hi:[1,0,1]
	v_pk_fma_f32 v[2:3], v[24:25], v[6:7], v[2:3] op_sel_hi:[1,0,1]
	v_pk_mul_f32 v[0:1], v[26:27], v[0:1]
	v_fmac_f32_e32 v32, v11, v30
	v_pk_fma_f32 v[0:1], v[28:29], v[2:3], v[0:1]
	v_add_f32_e32 v11, v18, v19
	v_add_f32_e32 v0, v0, v1
	ds_write_b32 v60, v32 offset:51584
	s_nop 0
	v_add_f32_dpp v11, v11, v11 row_ror:8 row_mask:0xf bank_mask:0xf
	v_add_f32_dpp v0, v0, v0 row_ror:8 row_mask:0xf bank_mask:0xf
	s_nop 0
	v_add_f32_dpp v11, v11, v11 row_ror:4 row_mask:0xf bank_mask:0xf
	v_add_f32_dpp v0, v0, v0 row_ror:4 row_mask:0xf bank_mask:0xf
	s_nop 0
	v_add_f32_dpp v11, v11, v11 row_ror:2 row_mask:0xf bank_mask:0xf
	v_add_f32_dpp v0, v0, v0 row_ror:2 row_mask:0xf bank_mask:0xf
	s_nop 0
	v_add_f32_dpp v11, v11, v11 row_ror:1 row_mask:0xf bank_mask:0xf
	v_add_f32_dpp v0, v0, v0 row_ror:1 row_mask:0xf bank_mask:0xf
	s_waitcnt lgkmcnt(1)
	v_fmac_f32_e32 v0, v9, v11
	ds_write_b32 v60, v0 offset:51648
	s_waitcnt lgkmcnt(0)
	s_barrier
	ds_read_b32 v2, v184 offset:50688
	v_cndmask_b32_e32 v0, v62, v61, vcc
	v_add_u32_e32 v0, s3, v0
	v_ashrrev_i32_e32 v1, 31, v0
	v_lshlrev_b64 v[0:1], 10, v[0:1]
	v_lshl_add_u64 v[0:1], v[12:13], 0, v[0:1]
	s_waitcnt lgkmcnt(0)
	v_cvt_pk_bf16_f32 v2, v2, s0
	global_store_short v[0:1], v2, off
	s_setprio 0

; DEV void row16_sum2(float& a, float& b) {
;   asm volatile("s_nop 1\n\tv_add_f32_dpp %0, %0, %0 row_ror:8 row_mask:0xf bank_mask:0xf\n\tv_add_f32_dpp %1, %1, %1 row_ror:8 row_mask:0xf bank_mask:0xf\n\t"
;                "s_nop 1\n\tv_add_f32_dpp %0, %0, %0 row_ror:4 row_mask:0xf bank_mask:0xf\n\tv_add_f32_dpp %1, %1, %1 row_ror:4 row_mask:0xf bank_mask:0xf\n\t"
;                "s_nop 1\n\tv_add_f32_dpp %0, %0, %0 row_ror:2 row_mask:0xf bank_mask:0xf\n\tv_add_f32_dpp %1, %1, %1 row_ror:2 row_mask:0xf bank_mask:0xf\n\t"
;                "s_nop 1\n\tv_add_f32_dpp %0, %0, %0 row_ror:1 row_mask:0xf bank_mask:0xf\n\tv_add_f32_dpp %1, %1, %1 row_ror:1 row_mask:0xf bank_mask:0xf\n\t"
;                "s_nop 0"
;                : "+v"(a), "+v"(b));
.LBB0_1960:
	s_add_i32 s15, s21, 1
	s_and_b32 s21, s21, 1
	s_mul_i32 s22, s21, 0x6100
	v_lshl_add_u32 v32, v125, 2, s22
	v_lshl_or_b32 v30, v52, 2, s22
	v_add_u32_e32 v33, 0x400, v32
	ds_read_b128 v[136:139], v30
	ds_read_b128 v[142:145], v30 offset:256
	ds_read_b128 v[146:149], v30 offset:512
	ds_read_b128 v[150:153], v30 offset:768
	ds_read2_b64 v[154:157], v33 offset0:32 offset1:226
	v_mov_b32_e32 v6, s22
	s_waitcnt lgkmcnt(3)
	v_pk_mul_f32 v[34:35], v[26:27], v[142:143]
	ds_read_b128 v[158:161], v30 offset:1024
	ds_read_b128 v[162:165], v30 offset:1552
	ds_read_b128 v[166:169], v30 offset:1808
	ds_read_b128 v[170:173], v30 offset:2064
	ds_read_b128 v[186:189], v30 offset:2320
	ds_read_b128 v[190:193], v30 offset:2576
	ds_read_b32 v33, v6 offset:1536
	ds_read_b32 v141, v6 offset:3088
	v_pk_fma_f32 v[34:35], v[28:29], v[144:145], v[34:35]
	s_waitcnt lgkmcnt(8)
	v_pk_mul_f32 v[132:133], v[150:151], v[154:155] op_sel_hi:[1,0]
	v_add_f32_e32 v34, v34, v35
	v_pk_fma_f32 v[26:27], v[26:27], v[136:137], v[132:133]
	v_pk_mul_f32 v[132:133], v[152:153], v[154:155] op_sel_hi:[1,0]
	s_mulk_i32 s21, 0xa700
	v_pk_fma_f32 v[28:29], v[28:29], v[138:139], v[132:133]
	s_waitcnt lgkmcnt(7)
	v_pk_mul_f32 v[132:133], v[158:159], v[26:27]
	s_add_i32 s21, s22, s21
	v_pk_fma_f32 v[132:133], v[160:161], v[28:29], v[132:133]
	v_lshl_add_u32 v131, v51, 2, s21
	v_add_f32_e32 v35, v132, v133
	s_nop 0
	v_add_f32_dpp v34, v34, v34 row_ror:8 row_mask:0xf bank_mask:0xf
	v_add_f32_dpp v35, v35, v35 row_ror:8 row_mask:0xf bank_mask:0xf
	s_nop 0
	v_add_f32_dpp v34, v34, v34 row_ror:4 row_mask:0xf bank_mask:0xf
	v_add_f32_dpp v35, v35, v35 row_ror:4 row_mask:0xf bank_mask:0xf
	s_nop 0
	v_add_f32_dpp v34, v34, v34 row_ror:2 row_mask:0xf bank_mask:0xf
	v_add_f32_dpp v35, v35, v35 row_ror:2 row_mask:0xf bank_mask:0xf
	s_nop 0
	v_add_f32_dpp v34, v34, v34 row_ror:1 row_mask:0xf bank_mask:0xf
	v_add_f32_dpp v35, v35, v35 row_ror:1 row_mask:0xf bank_mask:0xf
	s_andn2_b64 vcc, exec, s[12:13]
	v_pk_fma_f32 v[174:175], v[148:149], v[34:35], v[28:29] op_sel_hi:[1,0,1]
	v_pk_mul_f32 v[28:29], v[150:151], v[154:155] op_sel:[0,1]
	v_pk_fma_f32 v[132:133], v[146:147], v[34:35], v[26:27] op_sel_hi:[1,0,1]
	v_pk_mul_f32 v[26:27], v[0:1], v[142:143]
	v_pk_fma_f32 v[0:1], v[0:1], v[136:137], v[28:29]
	v_pk_mul_f32 v[28:29], v[152:153], v[154:155] op_sel:[0,1]
	v_pk_fma_f32 v[26:27], v[2:3], v[144:145], v[26:27]
	v_pk_fma_f32 v[2:3], v[2:3], v[138:139], v[28:29]
	v_pk_mul_f32 v[28:29], v[158:159], v[0:1]
	s_waitcnt lgkmcnt(5)
	v_pk_mul_f32 v[152:153], v[166:167], v[132:133]
	v_pk_fma_f32 v[28:29], v[160:161], v[2:3], v[28:29]
	v_pk_fma_f32 v[152:153], v[168:169], v[174:175], v[152:153]
	v_pk_mul_f32 v[132:133], v[162:163], v[132:133]
	s_waitcnt lgkmcnt(1)
	v_fmac_f32_e32 v35, v33, v34
	v_add_f32_e32 v26, v26, v27
	v_add_f32_e32 v27, v28, v29
	v_add_f32_e32 v134, v152, v153
	v_pk_mul_f32 v[152:153], v[164:165], v[174:175]
	v_pk_fma_f32 v[132:133], v[186:187], v[156:157], v[132:133] op_sel_hi:[1,0,1]
	ds_write_b32 v131, v35 offset:49664
	s_nop 0
	v_add_f32_dpp v26, v26, v26 row_ror:8 row_mask:0xf bank_mask:0xf
	v_add_f32_dpp v27, v27, v27 row_ror:8 row_mask:0xf bank_mask:0xf
	s_nop 0
	v_add_f32_dpp v26, v26, v26 row_ror:4 row_mask:0xf bank_mask:0xf
	v_add_f32_dpp v27, v27, v27 row_ror:4 row_mask:0xf bank_mask:0xf
	s_nop 0
	v_add_f32_dpp v26, v26, v26 row_ror:2 row_mask:0xf bank_mask:0xf
	v_add_f32_dpp v27, v27, v27 row_ror:2 row_mask:0xf bank_mask:0xf
	s_nop 0
	v_add_f32_dpp v26, v26, v26 row_ror:1 row_mask:0xf bank_mask:0xf
	v_add_f32_dpp v27, v27, v27 row_ror:1 row_mask:0xf bank_mask:0xf
	v_pk_fma_f32 v[152:153], v[188:189], v[156:157], v[152:153] op_sel_hi:[1,0,1]
	v_pk_mul_f32 v[154:155], v[190:191], v[132:133]
	v_pk_fma_f32 v[34:35], v[146:147], v[26:27], v[0:1] op_sel_hi:[1,0,1]
	v_pk_fma_f32 v[150:151], v[148:149], v[26:27], v[2:3] op_sel_hi:[1,0,1]
	v_fmac_f32_e32 v27, v33, v26
	v_pk_fma_f32 v[154:155], v[192:193], v[152:153], v[154:155]
	ds_write_b32 v131, v27 offset:49668
	v_add_f32_e32 v154, v154, v155
	ds_read_b128 v[0:3], v30 offset:3104
	ds_read_b128 v[26:29], v30 offset:3360
	ds_read_b128 v[136:139], v30 offset:3616
	ds_read_b128 v[142:145], v30 offset:3872
	ds_read_b64 v[194:195], v32 offset:4384
	ds_read_b128 v[146:149], v30 offset:4128
	ds_read_b32 v33, v6 offset:4640
	s_nop 0
	v_add_f32_dpp v134, v134, v134 row_ror:8 row_mask:0xf bank_mask:0xf
	v_add_f32_dpp v154, v154, v154 row_ror:8 row_mask:0xf bank_mask:0xf
	s_nop 0
	v_add_f32_dpp v134, v134, v134 row_ror:4 row_mask:0xf bank_mask:0xf
	v_add_f32_dpp v154, v154, v154 row_ror:4 row_mask:0xf bank_mask:0xf
	s_nop 0
	v_add_f32_dpp v134, v134, v134 row_ror:2 row_mask:0xf bank_mask:0xf
	v_add_f32_dpp v154, v154, v154 row_ror:2 row_mask:0xf bank_mask:0xf
	s_nop 0
	v_add_f32_dpp v134, v134, v134 row_ror:1 row_mask:0xf bank_mask:0xf
	v_add_f32_dpp v154, v154, v154 row_ror:1 row_mask:0xf bank_mask:0xf
	v_pk_fma_f32 v[174:175], v[172:173], v[134:135], v[152:153] op_sel_hi:[1,0,1]
	v_pk_mul_f32 v[152:153], v[166:167], v[34:35]
	v_pk_mul_f32 v[34:35], v[162:163], v[34:35]
	v_pk_fma_f32 v[152:153], v[168:169], v[150:151], v[152:153]
	v_pk_mul_f32 v[150:151], v[164:165], v[150:151]
	v_pk_fma_f32 v[34:35], v[186:187], v[156:157], v[34:35] op_sel:[0,1,0]
	v_pk_fma_f32 v[132:133], v[170:171], v[134:135], v[132:133] op_sel_hi:[1,0,1]
	s_waitcnt lgkmcnt(9)
	v_fmac_f32_e32 v154, v141, v134
	v_add_f32_e32 v134, v152, v153
	v_pk_fma_f32 v[150:151], v[188:189], v[156:157], v[150:151] op_sel:[0,1,0]
	v_pk_mul_f32 v[152:153], v[190:191], v[34:35]
	s_waitcnt lgkmcnt(5)
; DEV void row16_sum2(float& a, float& b) {
;   asm volatile("s_nop 1\n\tv_add_f32_dpp %0, %0, %0 row_ror:8 row_mask:0xf bank_mask:0xf\n\tv_add_f32_dpp %1, %1, %1 row_ror:8 row_mask:0xf bank_mask:0xf\n\t"
;                "s_nop 1\n\tv_add_f32_dpp %0, %0, %0 row_ror:4 row_mask:0xf bank_mask:0xf\n\tv_add_f32_dpp %1, %1, %1 row_ror:4 row_mask:0xf bank_mask:0xf\n\t"
;                "s_nop 1\n\tv_add_f32_dpp %0, %0, %0 row_ror:2 row_mask:0xf bank_mask:0xf\n\tv_add_f32_dpp %1, %1, %1 row_ror:2 row_mask:0xf bank_mask:0xf\n\t"
;                "s_nop 1\n\tv_add_f32_dpp %0, %0, %0 row_ror:1 row_mask:0xf bank_mask:0xf\n\tv_add_f32_dpp %1, %1, %1 row_ror:1 row_mask:0xf bank_mask:0xf\n\t"
;                "s_nop 0"
;                : "+v"(a), "+v"(b));
	v_pk_mul_f32 v[186:187], v[26:27], v[132:133]
	v_pk_fma_f32 v[152:153], v[192:193], v[150:151], v[152:153]
	v_pk_mul_f32 v[132:133], v[0:1], v[132:133]
	v_add_f32_e32 v152, v152, v153
	ds_write_b32 v131, v154 offset:49792
	s_nop 0
	v_add_f32_dpp v134, v134, v134 row_ror:8 row_mask:0xf bank_mask:0xf
	v_add_f32_dpp v152, v152, v152 row_ror:8 row_mask:0xf bank_mask:0xf
	s_nop 0
	v_add_f32_dpp v134, v134, v134 row_ror:4 row_mask:0xf bank_mask:0xf
	v_add_f32_dpp v152, v152, v152 row_ror:4 row_mask:0xf bank_mask:0xf
	s_nop 0
	v_add_f32_dpp v134, v134, v134 row_ror:2 row_mask:0xf bank_mask:0xf
	v_add_f32_dpp v152, v152, v152 row_ror:2 row_mask:0xf bank_mask:0xf
	s_nop 0
	v_add_f32_dpp v134, v134, v134 row_ror:1 row_mask:0xf bank_mask:0xf
	v_add_f32_dpp v152, v152, v152 row_ror:1 row_mask:0xf bank_mask:0xf
	v_pk_fma_f32 v[186:187], v[28:29], v[174:175], v[186:187]
	v_pk_fma_f32 v[34:35], v[170:171], v[134:135], v[34:35] op_sel_hi:[1,0,1]
	v_pk_mul_f32 v[174:175], v[2:3], v[174:175]
	s_waitcnt lgkmcnt(3)
	v_pk_fma_f32 v[132:133], v[142:143], v[194:195], v[132:133] op_sel_hi:[1,0,1]
	v_pk_fma_f32 v[170:171], v[172:173], v[134:135], v[150:151] op_sel_hi:[1,0,1]
	v_fmac_f32_e32 v152, v141, v134
	v_add_f32_e32 v134, v186, v187
	v_pk_fma_f32 v[174:175], v[144:145], v[194:195], v[174:175] op_sel_hi:[1,0,1]
	s_waitcnt lgkmcnt(2)
	v_pk_mul_f32 v[186:187], v[146:147], v[132:133]
	v_pk_mul_f32 v[0:1], v[0:1], v[34:35]
	ds_write_b32 v131, v152 offset:49796
	v_pk_fma_f32 v[186:187], v[148:149], v[174:175], v[186:187]
	v_pk_mul_f32 v[26:27], v[26:27], v[34:35]
	v_pk_mul_f32 v[2:3], v[2:3], v[170:171]
	v_pk_fma_f32 v[0:1], v[142:143], v[194:195], v[0:1] op_sel:[0,1,0]
	ds_read_b128 v[150:153], v30 offset:4656
	ds_read_b128 v[154:157], v30 offset:4912
	ds_read_b128 v[158:161], v30 offset:5168
	ds_read_b128 v[162:165], v30 offset:5424
	ds_read_b64 v[172:173], v32 offset:5936
	ds_read_b128 v[166:169], v30 offset:5680
	ds_read_b32 v141, v6 offset:6192
	v_add_f32_e32 v179, v186, v187
	v_pk_fma_f32 v[26:27], v[28:29], v[170:171], v[26:27]
	v_pk_fma_f32 v[2:3], v[144:145], v[194:195], v[2:3] op_sel:[0,1,0]
	v_pk_mul_f32 v[28:29], v[146:147], v[0:1]
	s_nop 0
	v_add_f32_dpp v134, v134, v134 row_ror:8 row_mask:0xf bank_mask:0xf
	v_add_f32_dpp v179, v179, v179 row_ror:8 row_mask:0xf bank_mask:0xf
	s_nop 0
	v_add_f32_dpp v134, v134, v134 row_ror:4 row_mask:0xf bank_mask:0xf
	v_add_f32_dpp v179, v179, v179 row_ror:4 row_mask:0xf bank_mask:0xf
	s_nop 0
	v_add_f32_dpp v134, v134, v134 row_ror:2 row_mask:0xf bank_mask:0xf
	v_add_f32_dpp v179, v179, v179 row_ror:2 row_mask:0xf bank_mask:0xf
	s_nop 0
	v_add_f32_dpp v134, v134, v134 row_ror:1 row_mask:0xf bank_mask:0xf
	v_add_f32_dpp v179, v179, v179 row_ror:1 row_mask:0xf bank_mask:0xf
	v_add_f32_e32 v26, v26, v27
	v_pk_fma_f32 v[132:133], v[136:137], v[134:135], v[132:133] op_sel_hi:[1,0,1]
	v_pk_fma_f32 v[28:29], v[148:149], v[2:3], v[28:29]
	v_pk_fma_f32 v[174:175], v[138:139], v[134:135], v[174:175] op_sel_hi:[1,0,1]
	s_waitcnt lgkmcnt(9)
	v_fmac_f32_e32 v179, v33, v134
	v_add_f32_e32 v27, v28, v29
	s_waitcnt lgkmcnt(5)
	v_pk_mul_f32 v[188:189], v[154:155], v[132:133]
	v_pk_mul_f32 v[132:133], v[150:151], v[132:133]
	ds_write_b32 v131, v179 offset:49920
	s_nop 0
	v_add_f32_dpp v26, v26, v26 row_ror:8 row_mask:0xf bank_mask:0xf
	v_add_f32_dpp v27, v27, v27 row_ror:8 row_mask:0xf bank_mask:0xf
	s_nop 0
	v_add_f32_dpp v26, v26, v26 row_ror:4 row_mask:0xf bank_mask:0xf
	v_add_f32_dpp v27, v27, v27 row_ror:4 row_mask:0xf bank_mask:0xf
	s_nop 0
	v_add_f32_dpp v26, v26, v26 row_ror:2 row_mask:0xf bank_mask:0xf
	v_add_f32_dpp v27, v27, v27 row_ror:2 row_mask:0xf bank_mask:0xf
	s_nop 0
	v_add_f32_dpp v26, v26, v26 row_ror:1 row_mask:0xf bank_mask:0xf
	v_add_f32_dpp v27, v27, v27 row_ror:1 row_mask:0xf bank_mask:0xf
	v_pk_fma_f32 v[188:189], v[156:157], v[174:175], v[188:189]
	v_pk_fma_f32 v[34:35], v[136:137], v[26:27], v[0:1] op_sel_hi:[1,0,1]
	v_pk_mul_f32 v[174:175], v[152:153], v[174:175]
	s_waitcnt lgkmcnt(3)
	v_pk_fma_f32 v[132:133], v[162:163], v[172:173], v[132:133] op_sel_hi:[1,0,1]
	v_pk_fma_f32 v[170:171], v[138:139], v[26:27], v[2:3] op_sel_hi:[1,0,1]
	v_fmac_f32_e32 v27, v33, v26
	v_add_f32_e32 v134, v188, v189
	v_pk_fma_f32 v[174:175], v[164:165], v[172:173], v[174:175] op_sel_hi:[1,0,1]
	s_waitcnt lgkmcnt(2)
	v_pk_mul_f32 v[188:189], v[166:167], v[132:133]
	v_pk_mul_f32 v[154:155], v[154:155], v[34:35]
	v_pk_mul_f32 v[34:35], v[150:151], v[34:35]
	ds_write_b32 v131, v27 offset:49924
	v_pk_fma_f32 v[188:189], v[168:169], v[174:175], v[188:189]
	v_pk_mul_f32 v[150:151], v[152:153], v[170:171]
	v_pk_fma_f32 v[34:35], v[162:163], v[172:173], v[34:35] op_sel:[0,1,0]
	ds_read_b128 v[0:3], v30 offset:6208
	ds_read_b128 v[26:29], v30 offset:6464
	ds_read_b128 v[136:139], v30 offset:6720
	ds_read_b128 v[142:145], v30 offset:6976
	ds_read_b64 v[186:187], v32 offset:7488
	ds_read_b128 v[146:149], v30 offset:7232
	ds_read_b32 v33, v6 offset:7744
	v_add_f32_e32 v179, v188, v189
	v_pk_fma_f32 v[150:151], v[164:165], v[172:173], v[150:151] op_sel:[0,1,0]
	v_pk_mul_f32 v[152:153], v[166:167], v[34:35]
	s_nop 0
	v_add_f32_dpp v134, v134, v134 row_ror:8 row_mask:0xf bank_mask:0xf
	v_add_f32_dpp v179, v179, v179 row_ror:8 row_mask:0xf bank_mask:0xf
	s_nop 0
	v_add_f32_dpp v134, v134, v134 row_ror:4 row_mask:0xf bank_mask:0xf
	v_add_f32_dpp v179, v179, v179 row_ror:4 row_mask:0xf bank_mask:0xf
	s_nop 0
	v_add_f32_dpp v134, v134, v134 row_ror:2 row_mask:0xf bank_mask:0xf
	v_add_f32_dpp v179, v179, v179 row_ror:2 row_mask:0xf bank_mask:0xf
	s_nop 0
	v_add_f32_dpp v134, v134, v134 row_ror:1 row_mask:0xf bank_mask:0xf
	v_add_f32_dpp v179, v179, v179 row_ror:1 row_mask:0xf bank_mask:0xf
	v_pk_fma_f32 v[154:155], v[156:157], v[170:171], v[154:155]
	v_pk_fma_f32 v[132:133], v[158:159], v[134:135], v[132:133] op_sel_hi:[1,0,1]
	v_pk_fma_f32 v[152:153], v[168:169], v[150:151], v[152:153]
	v_pk_fma_f32 v[174:175], v[160:161], v[134:135], v[174:175] op_sel_hi:[1,0,1]
	s_waitcnt lgkmcnt(9)
; DEV void row16_sum2(float& a, float& b) {
;   asm volatile("s_nop 1\n\tv_add_f32_dpp %0, %0, %0 row_ror:8 row_mask:0xf bank_mask:0xf\n\tv_add_f32_dpp %1, %1, %1 row_ror:8 row_mask:0xf bank_mask:0xf\n\t"
;                "s_nop 1\n\tv_add_f32_dpp %0, %0, %0 row_ror:4 row_mask:0xf bank_mask:0xf\n\tv_add_f32_dpp %1, %1, %1 row_ror:4 row_mask:0xf bank_mask:0xf\n\t"
;                "s_nop 1\n\tv_add_f32_dpp %0, %0, %0 row_ror:2 row_mask:0xf bank_mask:0xf\n\tv_add_f32_dpp %1, %1, %1 row_ror:2 row_mask:0xf bank_mask:0xf\n\t"
;                "s_nop 1\n\tv_add_f32_dpp %0, %0, %0 row_ror:1 row_mask:0xf bank_mask:0xf\n\tv_add_f32_dpp %1, %1, %1 row_ror:1 row_mask:0xf bank_mask:0xf\n\t"
;                "s_nop 0"
;                : "+v"(a), "+v"(b));
	v_fmac_f32_e32 v179, v141, v134
	v_add_f32_e32 v134, v154, v155
	v_add_f32_e32 v152, v152, v153
	s_waitcnt lgkmcnt(5)
	v_pk_mul_f32 v[188:189], v[26:27], v[132:133]
	v_pk_mul_f32 v[132:133], v[0:1], v[132:133]
	ds_write_b32 v131, v179 offset:50048
	s_nop 0
	v_add_f32_dpp v134, v134, v134 row_ror:8 row_mask:0xf bank_mask:0xf
	v_add_f32_dpp v152, v152, v152 row_ror:8 row_mask:0xf bank_mask:0xf
	s_nop 0
	v_add_f32_dpp v134, v134, v134 row_ror:4 row_mask:0xf bank_mask:0xf
	v_add_f32_dpp v152, v152, v152 row_ror:4 row_mask:0xf bank_mask:0xf
	s_nop 0
	v_add_f32_dpp v134, v134, v134 row_ror:2 row_mask:0xf bank_mask:0xf
	v_add_f32_dpp v152, v152, v152 row_ror:2 row_mask:0xf bank_mask:0xf
	s_nop 0
	v_add_f32_dpp v134, v134, v134 row_ror:1 row_mask:0xf bank_mask:0xf
	v_add_f32_dpp v152, v152, v152 row_ror:1 row_mask:0xf bank_mask:0xf
	v_pk_fma_f32 v[188:189], v[28:29], v[174:175], v[188:189]
	v_pk_fma_f32 v[34:35], v[158:159], v[134:135], v[34:35] op_sel_hi:[1,0,1]
	v_pk_mul_f32 v[174:175], v[2:3], v[174:175]
	s_waitcnt lgkmcnt(3)
	v_pk_fma_f32 v[132:133], v[142:143], v[186:187], v[132:133] op_sel_hi:[1,0,1]
	v_pk_fma_f32 v[170:171], v[160:161], v[134:135], v[150:151] op_sel_hi:[1,0,1]
	v_fmac_f32_e32 v152, v141, v134
	v_add_f32_e32 v134, v188, v189
	v_pk_fma_f32 v[174:175], v[144:145], v[186:187], v[174:175] op_sel_hi:[1,0,1]
	s_waitcnt lgkmcnt(2)
	v_pk_mul_f32 v[188:189], v[146:147], v[132:133]
	v_pk_mul_f32 v[0:1], v[0:1], v[34:35]
	ds_write_b32 v131, v152 offset:50052
	v_pk_fma_f32 v[188:189], v[148:149], v[174:175], v[188:189]
	v_pk_mul_f32 v[26:27], v[26:27], v[34:35]
	v_pk_mul_f32 v[2:3], v[2:3], v[170:171]
	v_pk_fma_f32 v[0:1], v[142:143], v[186:187], v[0:1] op_sel:[0,1,0]
	ds_read_b128 v[150:153], v30 offset:7760
	ds_read_b128 v[154:157], v30 offset:8016
	ds_read_b128 v[158:161], v30 offset:8272
	ds_read_b128 v[162:165], v30 offset:8528
	ds_read_b64 v[172:173], v32 offset:9040
	ds_read_b128 v[166:169], v30 offset:8784
	ds_read_b32 v141, v6 offset:9296
	v_add_f32_e32 v179, v188, v189
	v_pk_fma_f32 v[26:27], v[28:29], v[170:171], v[26:27]
	v_pk_fma_f32 v[2:3], v[144:145], v[186:187], v[2:3] op_sel:[0,1,0]
	v_pk_mul_f32 v[28:29], v[146:147], v[0:1]
	s_nop 0
	v_add_f32_dpp v134, v134, v134 row_ror:8 row_mask:0xf bank_mask:0xf
	v_add_f32_dpp v179, v179, v179 row_ror:8 row_mask:0xf bank_mask:0xf
	s_nop 0
	v_add_f32_dpp v134, v134, v134 row_ror:4 row_mask:0xf bank_mask:0xf
	v_add_f32_dpp v179, v179, v179 row_ror:4 row_mask:0xf bank_mask:0xf
	s_nop 0
	v_add_f32_dpp v134, v134, v134 row_ror:2 row_mask:0xf bank_mask:0xf
	v_add_f32_dpp v179, v179, v179 row_ror:2 row_mask:0xf bank_mask:0xf
	s_nop 0
	v_add_f32_dpp v134, v134, v134 row_ror:1 row_mask:0xf bank_mask:0xf
	v_add_f32_dpp v179, v179, v179 row_ror:1 row_mask:0xf bank_mask:0xf
	v_add_f32_e32 v26, v26, v27
	v_pk_fma_f32 v[132:133], v[136:137], v[134:135], v[132:133] op_sel_hi:[1,0,1]
	v_pk_fma_f32 v[28:29], v[148:149], v[2:3], v[28:29]
	v_pk_fma_f32 v[174:175], v[138:139], v[134:135], v[174:175] op_sel_hi:[1,0,1]
	s_waitcnt lgkmcnt(9)
	v_fmac_f32_e32 v179, v33, v134
	v_add_f32_e32 v27, v28, v29
	s_waitcnt lgkmcnt(5)
	v_pk_mul_f32 v[188:189], v[154:155], v[132:133]
	v_pk_mul_f32 v[132:133], v[150:151], v[132:133]
	ds_write_b32 v131, v179 offset:50176
	s_nop 0
	v_add_f32_dpp v26, v26, v26 row_ror:8 row_mask:0xf bank_mask:0xf
	v_add_f32_dpp v27, v27, v27 row_ror:8 row_mask:0xf bank_mask:0xf
	s_nop 0
	v_add_f32_dpp v26, v26, v26 row_ror:4 row_mask:0xf bank_mask:0xf
	v_add_f32_dpp v27, v27, v27 row_ror:4 row_mask:0xf bank_mask:0xf
	s_nop 0
	v_add_f32_dpp v26, v26, v26 row_ror:2 row_mask:0xf bank_mask:0xf
	v_add_f32_dpp v27, v27, v27 row_ror:2 row_mask:0xf bank_mask:0xf
	s_nop 0
	v_add_f32_dpp v26, v26, v26 row_ror:1 row_mask:0xf bank_mask:0xf
	v_add_f32_dpp v27, v27, v27 row_ror:1 row_mask:0xf bank_mask:0xf
	v_pk_fma_f32 v[188:189], v[156:157], v[174:175], v[188:189]
	v_pk_fma_f32 v[34:35], v[136:137], v[26:27], v[0:1] op_sel_hi:[1,0,1]
	v_pk_mul_f32 v[174:175], v[152:153], v[174:175]
	s_waitcnt lgkmcnt(3)
	v_pk_fma_f32 v[132:133], v[162:163], v[172:173], v[132:133] op_sel_hi:[1,0,1]
	v_pk_fma_f32 v[170:171], v[138:139], v[26:27], v[2:3] op_sel_hi:[1,0,1]
	v_fmac_f32_e32 v27, v33, v26
	v_add_f32_e32 v134, v188, v189
	v_pk_fma_f32 v[174:175], v[164:165], v[172:173], v[174:175] op_sel_hi:[1,0,1]
	s_waitcnt lgkmcnt(2)
	v_pk_mul_f32 v[188:189], v[166:167], v[132:133]
	v_pk_mul_f32 v[154:155], v[154:155], v[34:35]
	v_pk_mul_f32 v[34:35], v[150:151], v[34:35]
	ds_write_b32 v131, v27 offset:50180
	v_pk_fma_f32 v[188:189], v[168:169], v[174:175], v[188:189]
	v_pk_mul_f32 v[150:151], v[152:153], v[170:171]
	v_pk_fma_f32 v[34:35], v[162:163], v[172:173], v[34:35] op_sel:[0,1,0]
	ds_read_b128 v[0:3], v30 offset:9312
	ds_read_b128 v[26:29], v30 offset:9568
	ds_read_b128 v[136:139], v30 offset:9824
	ds_read_b128 v[142:145], v30 offset:10080
	ds_read_b64 v[186:187], v32 offset:10592
	ds_read_b128 v[146:149], v30 offset:10336
	ds_read_b32 v33, v6 offset:10848
	v_add_f32_e32 v179, v188, v189
	v_pk_fma_f32 v[150:151], v[164:165], v[172:173], v[150:151] op_sel:[0,1,0]
	v_pk_mul_f32 v[152:153], v[166:167], v[34:35]
	s_nop 0
	v_add_f32_dpp v134, v134, v134 row_ror:8 row_mask:0xf bank_mask:0xf
	v_add_f32_dpp v179, v179, v179 row_ror:8 row_mask:0xf bank_mask:0xf
	s_nop 0
	v_add_f32_dpp v134, v134, v134 row_ror:4 row_mask:0xf bank_mask:0xf
	v_add_f32_dpp v179, v179, v179 row_ror:4 row_mask:0xf bank_mask:0xf
	s_nop 0
	v_add_f32_dpp v134, v134, v134 row_ror:2 row_mask:0xf bank_mask:0xf
	v_add_f32_dpp v179, v179, v179 row_ror:2 row_mask:0xf bank_mask:0xf
	s_nop 0
	v_add_f32_dpp v134, v134, v134 row_ror:1 row_mask:0xf bank_mask:0xf
	v_add_f32_dpp v179, v179, v179 row_ror:1 row_mask:0xf bank_mask:0xf
	v_pk_fma_f32 v[154:155], v[156:157], v[170:171], v[154:155]
	v_pk_fma_f32 v[132:133], v[158:159], v[134:135], v[132:133] op_sel_hi:[1,0,1]
	v_pk_fma_f32 v[152:153], v[168:169], v[150:151], v[152:153]
	v_pk_fma_f32 v[174:175], v[160:161], v[134:135], v[174:175] op_sel_hi:[1,0,1]
	s_waitcnt lgkmcnt(9)
; DEV void row16_sum2(float& a, float& b) {
;   asm volatile("s_nop 1\n\tv_add_f32_dpp %0, %0, %0 row_ror:8 row_mask:0xf bank_mask:0xf\n\tv_add_f32_dpp %1, %1, %1 row_ror:8 row_mask:0xf bank_mask:0xf\n\t"
;                "s_nop 1\n\tv_add_f32_dpp %0, %0, %0 row_ror:4 row_mask:0xf bank_mask:0xf\n\tv_add_f32_dpp %1, %1, %1 row_ror:4 row_mask:0xf bank_mask:0xf\n\t"
;                "s_nop 1\n\tv_add_f32_dpp %0, %0, %0 row_ror:2 row_mask:0xf bank_mask:0xf\n\tv_add_f32_dpp %1, %1, %1 row_ror:2 row_mask:0xf bank_mask:0xf\n\t"
;                "s_nop 1\n\tv_add_f32_dpp %0, %0, %0 row_ror:1 row_mask:0xf bank_mask:0xf\n\tv_add_f32_dpp %1, %1, %1 row_ror:1 row_mask:0xf bank_mask:0xf\n\t"
;                "s_nop 0"
;                : "+v"(a), "+v"(b));
	v_fmac_f32_e32 v179, v141, v134
	v_add_f32_e32 v134, v154, v155
	v_add_f32_e32 v152, v152, v153
	s_waitcnt lgkmcnt(5)
	v_pk_mul_f32 v[188:189], v[26:27], v[132:133]
	v_pk_mul_f32 v[132:133], v[0:1], v[132:133]
	ds_write_b32 v131, v179 offset:50304
	s_nop 0
	v_add_f32_dpp v134, v134, v134 row_ror:8 row_mask:0xf bank_mask:0xf
	v_add_f32_dpp v152, v152, v152 row_ror:8 row_mask:0xf bank_mask:0xf
	s_nop 0
	v_add_f32_dpp v134, v134, v134 row_ror:4 row_mask:0xf bank_mask:0xf
	v_add_f32_dpp v152, v152, v152 row_ror:4 row_mask:0xf bank_mask:0xf
	s_nop 0
	v_add_f32_dpp v134, v134, v134 row_ror:2 row_mask:0xf bank_mask:0xf
	v_add_f32_dpp v152, v152, v152 row_ror:2 row_mask:0xf bank_mask:0xf
	s_nop 0
	v_add_f32_dpp v134, v134, v134 row_ror:1 row_mask:0xf bank_mask:0xf
	v_add_f32_dpp v152, v152, v152 row_ror:1 row_mask:0xf bank_mask:0xf
	v_pk_fma_f32 v[188:189], v[28:29], v[174:175], v[188:189]
	v_pk_fma_f32 v[34:35], v[158:159], v[134:135], v[34:35] op_sel_hi:[1,0,1]
	v_pk_mul_f32 v[174:175], v[2:3], v[174:175]
	s_waitcnt lgkmcnt(3)
	v_pk_fma_f32 v[132:133], v[142:143], v[186:187], v[132:133] op_sel_hi:[1,0,1]
	v_pk_fma_f32 v[170:171], v[160:161], v[134:135], v[150:151] op_sel_hi:[1,0,1]
	v_fmac_f32_e32 v152, v141, v134
	v_add_f32_e32 v134, v188, v189
	v_pk_fma_f32 v[174:175], v[144:145], v[186:187], v[174:175] op_sel_hi:[1,0,1]
	s_waitcnt lgkmcnt(2)
	v_pk_mul_f32 v[188:189], v[146:147], v[132:133]
	v_pk_mul_f32 v[0:1], v[0:1], v[34:35]
	ds_write_b32 v131, v152 offset:50308
	v_pk_fma_f32 v[188:189], v[148:149], v[174:175], v[188:189]
	v_pk_mul_f32 v[26:27], v[26:27], v[34:35]
	v_pk_mul_f32 v[2:3], v[2:3], v[170:171]
	v_pk_fma_f32 v[0:1], v[142:143], v[186:187], v[0:1] op_sel:[0,1,0]
	ds_read_b128 v[150:153], v30 offset:10864
	ds_read_b128 v[154:157], v30 offset:11120
	ds_read_b128 v[158:161], v30 offset:11376
	ds_read_b128 v[162:165], v30 offset:11632
	ds_read_b64 v[172:173], v32 offset:12144
	ds_read_b128 v[166:169], v30 offset:11888
	ds_read_b32 v141, v6 offset:12400
	v_add_f32_e32 v179, v188, v189
	v_pk_fma_f32 v[26:27], v[28:29], v[170:171], v[26:27]
	v_pk_fma_f32 v[2:3], v[144:145], v[186:187], v[2:3] op_sel:[0,1,0]
	v_pk_mul_f32 v[28:29], v[146:147], v[0:1]
	s_nop 0
	v_add_f32_dpp v134, v134, v134 row_ror:8 row_mask:0xf bank_mask:0xf
	v_add_f32_dpp v179, v179, v179 row_ror:8 row_mask:0xf bank_mask:0xf
	s_nop 0
	v_add_f32_dpp v134, v134, v134 row_ror:4 row_mask:0xf bank_mask:0xf
	v_add_f32_dpp v179, v179, v179 row_ror:4 row_mask:0xf bank_mask:0xf
	s_nop 0
	v_add_f32_dpp v134, v134, v134 row_ror:2 row_mask:0xf bank_mask:0xf
	v_add_f32_dpp v179, v179, v179 row_ror:2 row_mask:0xf bank_mask:0xf
	s_nop 0
	v_add_f32_dpp v134, v134, v134 row_ror:1 row_mask:0xf bank_mask:0xf
	v_add_f32_dpp v179, v179, v179 row_ror:1 row_mask:0xf bank_mask:0xf
	v_add_f32_e32 v26, v26, v27
	v_pk_fma_f32 v[132:133], v[136:137], v[134:135], v[132:133] op_sel_hi:[1,0,1]
	v_pk_fma_f32 v[28:29], v[148:149], v[2:3], v[28:29]
	v_pk_fma_f32 v[174:175], v[138:139], v[134:135], v[174:175] op_sel_hi:[1,0,1]
	s_waitcnt lgkmcnt(9)
	v_fmac_f32_e32 v179, v33, v134
	v_add_f32_e32 v27, v28, v29
	s_waitcnt lgkmcnt(5)
	v_pk_mul_f32 v[188:189], v[154:155], v[132:133]
	v_pk_mul_f32 v[132:133], v[150:151], v[132:133]
	ds_write_b32 v131, v179 offset:50432
	s_nop 0
	v_add_f32_dpp v26, v26, v26 row_ror:8 row_mask:0xf bank_mask:0xf
	v_add_f32_dpp v27, v27, v27 row_ror:8 row_mask:0xf bank_mask:0xf
	s_nop 0
	v_add_f32_dpp v26, v26, v26 row_ror:4 row_mask:0xf bank_mask:0xf
	v_add_f32_dpp v27, v27, v27 row_ror:4 row_mask:0xf bank_mask:0xf
	s_nop 0
	v_add_f32_dpp v26, v26, v26 row_ror:2 row_mask:0xf bank_mask:0xf
	v_add_f32_dpp v27, v27, v27 row_ror:2 row_mask:0xf bank_mask:0xf
	s_nop 0
	v_add_f32_dpp v26, v26, v26 row_ror:1 row_mask:0xf bank_mask:0xf
	v_add_f32_dpp v27, v27, v27 row_ror:1 row_mask:0xf bank_mask:0xf
	v_pk_fma_f32 v[188:189], v[156:157], v[174:175], v[188:189]
	v_pk_fma_f32 v[34:35], v[136:137], v[26:27], v[0:1] op_sel_hi:[1,0,1]
	v_pk_mul_f32 v[174:175], v[152:153], v[174:175]
	s_waitcnt lgkmcnt(3)
	v_pk_fma_f32 v[132:133], v[162:163], v[172:173], v[132:133] op_sel_hi:[1,0,1]
	v_pk_fma_f32 v[170:171], v[138:139], v[26:27], v[2:3] op_sel_hi:[1,0,1]
	v_fmac_f32_e32 v27, v33, v26
	v_add_f32_e32 v134, v188, v189
	v_pk_fma_f32 v[174:175], v[164:165], v[172:173], v[174:175] op_sel_hi:[1,0,1]
	s_waitcnt lgkmcnt(2)
	v_pk_mul_f32 v[188:189], v[166:167], v[132:133]
	v_pk_mul_f32 v[154:155], v[154:155], v[34:35]
	v_pk_mul_f32 v[34:35], v[150:151], v[34:35]
	ds_write_b32 v131, v27 offset:50436
	v_pk_fma_f32 v[188:189], v[168:169], v[174:175], v[188:189]
	v_pk_mul_f32 v[150:151], v[152:153], v[170:171]
	v_pk_fma_f32 v[34:35], v[162:163], v[172:173], v[34:35] op_sel:[0,1,0]
	ds_read_b128 v[0:3], v30 offset:12416
	ds_read_b128 v[26:29], v30 offset:12672
	ds_read_b128 v[136:139], v30 offset:12928
	ds_read_b128 v[142:145], v30 offset:13184
	ds_read_b64 v[186:187], v32 offset:13696
	ds_read_b128 v[146:149], v30 offset:13440
	ds_read_b32 v33, v6 offset:13952
	v_add_f32_e32 v179, v188, v189
	v_pk_fma_f32 v[150:151], v[164:165], v[172:173], v[150:151] op_sel:[0,1,0]
	v_pk_mul_f32 v[152:153], v[166:167], v[34:35]
	s_nop 0
	v_add_f32_dpp v134, v134, v134 row_ror:8 row_mask:0xf bank_mask:0xf
	v_add_f32_dpp v179, v179, v179 row_ror:8 row_mask:0xf bank_mask:0xf
	s_nop 0
	v_add_f32_dpp v134, v134, v134 row_ror:4 row_mask:0xf bank_mask:0xf
	v_add_f32_dpp v179, v179, v179 row_ror:4 row_mask:0xf bank_mask:0xf
	s_nop 0
	v_add_f32_dpp v134, v134, v134 row_ror:2 row_mask:0xf bank_mask:0xf
	v_add_f32_dpp v179, v179, v179 row_ror:2 row_mask:0xf bank_mask:0xf
	s_nop 0
	v_add_f32_dpp v134, v134, v134 row_ror:1 row_mask:0xf bank_mask:0xf
	v_add_f32_dpp v179, v179, v179 row_ror:1 row_mask:0xf bank_mask:0xf
	v_pk_fma_f32 v[154:155], v[156:157], v[170:171], v[154:155]
	v_pk_fma_f32 v[132:133], v[158:159], v[134:135], v[132:133] op_sel_hi:[1,0,1]
	v_pk_fma_f32 v[152:153], v[168:169], v[150:151], v[152:153]
	v_pk_fma_f32 v[174:175], v[160:161], v[134:135], v[174:175] op_sel_hi:[1,0,1]
	s_waitcnt lgkmcnt(9)
; DEV void row16_sum2(float& a, float& b) {
;   asm volatile("s_nop 1\n\tv_add_f32_dpp %0, %0, %0 row_ror:8 row_mask:0xf bank_mask:0xf\n\tv_add_f32_dpp %1, %1, %1 row_ror:8 row_mask:0xf bank_mask:0xf\n\t"
;                "s_nop 1\n\tv_add_f32_dpp %0, %0, %0 row_ror:4 row_mask:0xf bank_mask:0xf\n\tv_add_f32_dpp %1, %1, %1 row_ror:4 row_mask:0xf bank_mask:0xf\n\t"
;                "s_nop 1\n\tv_add_f32_dpp %0, %0, %0 row_ror:2 row_mask:0xf bank_mask:0xf\n\tv_add_f32_dpp %1, %1, %1 row_ror:2 row_mask:0xf bank_mask:0xf\n\t"
;                "s_nop 1\n\tv_add_f32_dpp %0, %0, %0 row_ror:1 row_mask:0xf bank_mask:0xf\n\tv_add_f32_dpp %1, %1, %1 row_ror:1 row_mask:0xf bank_mask:0xf\n\t"
;                "s_nop 0"
;                : "+v"(a), "+v"(b));
	v_fmac_f32_e32 v179, v141, v134
	v_add_f32_e32 v134, v154, v155
	v_add_f32_e32 v152, v152, v153
	s_waitcnt lgkmcnt(5)
	v_pk_mul_f32 v[188:189], v[26:27], v[132:133]
	v_pk_mul_f32 v[132:133], v[0:1], v[132:133]
	ds_write_b32 v131, v179 offset:50560
	s_nop 0
	v_add_f32_dpp v134, v134, v134 row_ror:8 row_mask:0xf bank_mask:0xf
	v_add_f32_dpp v152, v152, v152 row_ror:8 row_mask:0xf bank_mask:0xf
	s_nop 0
	v_add_f32_dpp v134, v134, v134 row_ror:4 row_mask:0xf bank_mask:0xf
	v_add_f32_dpp v152, v152, v152 row_ror:4 row_mask:0xf bank_mask:0xf
	s_nop 0
	v_add_f32_dpp v134, v134, v134 row_ror:2 row_mask:0xf bank_mask:0xf
	v_add_f32_dpp v152, v152, v152 row_ror:2 row_mask:0xf bank_mask:0xf
	s_nop 0
	v_add_f32_dpp v134, v134, v134 row_ror:1 row_mask:0xf bank_mask:0xf
	v_add_f32_dpp v152, v152, v152 row_ror:1 row_mask:0xf bank_mask:0xf
	v_pk_fma_f32 v[188:189], v[28:29], v[174:175], v[188:189]
	v_pk_fma_f32 v[34:35], v[158:159], v[134:135], v[34:35] op_sel_hi:[1,0,1]
	v_pk_mul_f32 v[174:175], v[2:3], v[174:175]
	s_waitcnt lgkmcnt(3)
	v_pk_fma_f32 v[132:133], v[142:143], v[186:187], v[132:133] op_sel_hi:[1,0,1]
	v_pk_fma_f32 v[170:171], v[160:161], v[134:135], v[150:151] op_sel_hi:[1,0,1]
	v_fmac_f32_e32 v152, v141, v134
	v_add_f32_e32 v134, v188, v189
	v_pk_fma_f32 v[174:175], v[144:145], v[186:187], v[174:175] op_sel_hi:[1,0,1]
	s_waitcnt lgkmcnt(2)
	v_pk_mul_f32 v[188:189], v[146:147], v[132:133]
	v_pk_mul_f32 v[0:1], v[0:1], v[34:35]
	ds_write_b32 v131, v152 offset:50564
	v_pk_fma_f32 v[188:189], v[148:149], v[174:175], v[188:189]
	v_pk_mul_f32 v[26:27], v[26:27], v[34:35]
	v_pk_mul_f32 v[2:3], v[2:3], v[170:171]
	v_pk_fma_f32 v[0:1], v[142:143], v[186:187], v[0:1] op_sel:[0,1,0]
	ds_read_b128 v[150:153], v30 offset:13968
	ds_read_b128 v[154:157], v30 offset:14224
	ds_read_b128 v[158:161], v30 offset:14480
	ds_read_b128 v[162:165], v30 offset:14736
	ds_read_b64 v[172:173], v32 offset:15248
	ds_read_b128 v[166:169], v30 offset:14992
	ds_read_b32 v141, v6 offset:15504
	v_add_f32_e32 v179, v188, v189
	v_pk_fma_f32 v[26:27], v[28:29], v[170:171], v[26:27]
	v_pk_fma_f32 v[2:3], v[144:145], v[186:187], v[2:3] op_sel:[0,1,0]
	v_pk_mul_f32 v[28:29], v[146:147], v[0:1]
	s_nop 0
	v_add_f32_dpp v134, v134, v134 row_ror:8 row_mask:0xf bank_mask:0xf
	v_add_f32_dpp v179, v179, v179 row_ror:8 row_mask:0xf bank_mask:0xf
	s_nop 0
	v_add_f32_dpp v134, v134, v134 row_ror:4 row_mask:0xf bank_mask:0xf
	v_add_f32_dpp v179, v179, v179 row_ror:4 row_mask:0xf bank_mask:0xf
	s_nop 0
	v_add_f32_dpp v134, v134, v134 row_ror:2 row_mask:0xf bank_mask:0xf
	v_add_f32_dpp v179, v179, v179 row_ror:2 row_mask:0xf bank_mask:0xf
	s_nop 0
	v_add_f32_dpp v134, v134, v134 row_ror:1 row_mask:0xf bank_mask:0xf
	v_add_f32_dpp v179, v179, v179 row_ror:1 row_mask:0xf bank_mask:0xf
	v_add_f32_e32 v26, v26, v27
	v_pk_fma_f32 v[132:133], v[136:137], v[134:135], v[132:133] op_sel_hi:[1,0,1]
	v_pk_fma_f32 v[28:29], v[148:149], v[2:3], v[28:29]
	v_pk_fma_f32 v[174:175], v[138:139], v[134:135], v[174:175] op_sel_hi:[1,0,1]
	s_waitcnt lgkmcnt(9)
	v_fmac_f32_e32 v179, v33, v134
	v_add_f32_e32 v27, v28, v29
	s_waitcnt lgkmcnt(5)
	v_pk_mul_f32 v[188:189], v[154:155], v[132:133]
	v_pk_mul_f32 v[132:133], v[150:151], v[132:133]
	ds_write_b32 v131, v179 offset:50688
	s_nop 0
	v_add_f32_dpp v26, v26, v26 row_ror:8 row_mask:0xf bank_mask:0xf
	v_add_f32_dpp v27, v27, v27 row_ror:8 row_mask:0xf bank_mask:0xf
	s_nop 0
	v_add_f32_dpp v26, v26, v26 row_ror:4 row_mask:0xf bank_mask:0xf
	v_add_f32_dpp v27, v27, v27 row_ror:4 row_mask:0xf bank_mask:0xf
	s_nop 0
	v_add_f32_dpp v26, v26, v26 row_ror:2 row_mask:0xf bank_mask:0xf
	v_add_f32_dpp v27, v27, v27 row_ror:2 row_mask:0xf bank_mask:0xf
	s_nop 0
	v_add_f32_dpp v26, v26, v26 row_ror:1 row_mask:0xf bank_mask:0xf
	v_add_f32_dpp v27, v27, v27 row_ror:1 row_mask:0xf bank_mask:0xf
	v_pk_fma_f32 v[188:189], v[156:157], v[174:175], v[188:189]
	v_pk_fma_f32 v[34:35], v[136:137], v[26:27], v[0:1] op_sel_hi:[1,0,1]
	v_pk_mul_f32 v[174:175], v[152:153], v[174:175]
	s_waitcnt lgkmcnt(3)
	v_pk_fma_f32 v[132:133], v[162:163], v[172:173], v[132:133] op_sel_hi:[1,0,1]
	v_pk_fma_f32 v[170:171], v[138:139], v[26:27], v[2:3] op_sel_hi:[1,0,1]
	v_fmac_f32_e32 v27, v33, v26
	v_add_f32_e32 v134, v188, v189
	v_pk_fma_f32 v[174:175], v[164:165], v[172:173], v[174:175] op_sel_hi:[1,0,1]
	s_waitcnt lgkmcnt(2)
	v_pk_mul_f32 v[188:189], v[166:167], v[132:133]
	v_pk_mul_f32 v[154:155], v[154:155], v[34:35]
	v_pk_mul_f32 v[34:35], v[150:151], v[34:35]
	ds_write_b32 v131, v27 offset:50692
	v_pk_fma_f32 v[188:189], v[168:169], v[174:175], v[188:189]
	v_pk_mul_f32 v[150:151], v[152:153], v[170:171]
	v_pk_fma_f32 v[34:35], v[162:163], v[172:173], v[34:35] op_sel:[0,1,0]
	ds_read_b128 v[0:3], v30 offset:15520
	ds_read_b128 v[26:29], v30 offset:15776
	ds_read_b128 v[136:139], v30 offset:16032
	ds_read_b128 v[142:145], v30 offset:16288
	ds_read_b64 v[186:187], v32 offset:16800
	ds_read_b128 v[146:149], v30 offset:16544
	ds_read_b32 v33, v6 offset:17056
	v_add_f32_e32 v179, v188, v189
	v_pk_fma_f32 v[150:151], v[164:165], v[172:173], v[150:151] op_sel:[0,1,0]
	v_pk_mul_f32 v[152:153], v[166:167], v[34:35]
	s_nop 0
	v_add_f32_dpp v134, v134, v134 row_ror:8 row_mask:0xf bank_mask:0xf
	v_add_f32_dpp v179, v179, v179 row_ror:8 row_mask:0xf bank_mask:0xf
	s_nop 0
	v_add_f32_dpp v134, v134, v134 row_ror:4 row_mask:0xf bank_mask:0xf
	v_add_f32_dpp v179, v179, v179 row_ror:4 row_mask:0xf bank_mask:0xf
	s_nop 0
	v_add_f32_dpp v134, v134, v134 row_ror:2 row_mask:0xf bank_mask:0xf
	v_add_f32_dpp v179, v179, v179 row_ror:2 row_mask:0xf bank_mask:0xf
	s_nop 0
	v_add_f32_dpp v134, v134, v134 row_ror:1 row_mask:0xf bank_mask:0xf
	v_add_f32_dpp v179, v179, v179 row_ror:1 row_mask:0xf bank_mask:0xf
	v_pk_fma_f32 v[154:155], v[156:157], v[170:171], v[154:155]
	v_pk_fma_f32 v[132:133], v[158:159], v[134:135], v[132:133] op_sel_hi:[1,0,1]
	v_pk_fma_f32 v[152:153], v[168:169], v[150:151], v[152:153]
	v_pk_fma_f32 v[174:175], v[160:161], v[134:135], v[174:175] op_sel_hi:[1,0,1]
	s_waitcnt lgkmcnt(9)
; DEV void row16_sum2(float& a, float& b) {
;   asm volatile("s_nop 1\n\tv_add_f32_dpp %0, %0, %0 row_ror:8 row_mask:0xf bank_mask:0xf\n\tv_add_f32_dpp %1, %1, %1 row_ror:8 row_mask:0xf bank_mask:0xf\n\t"
;                "s_nop 1\n\tv_add_f32_dpp %0, %0, %0 row_ror:4 row_mask:0xf bank_mask:0xf\n\tv_add_f32_dpp %1, %1, %1 row_ror:4 row_mask:0xf bank_mask:0xf\n\t"
;                "s_nop 1\n\tv_add_f32_dpp %0, %0, %0 row_ror:2 row_mask:0xf bank_mask:0xf\n\tv_add_f32_dpp %1, %1, %1 row_ror:2 row_mask:0xf bank_mask:0xf\n\t"
;                "s_nop 1\n\tv_add_f32_dpp %0, %0, %0 row_ror:1 row_mask:0xf bank_mask:0xf\n\tv_add_f32_dpp %1, %1, %1 row_ror:1 row_mask:0xf bank_mask:0xf\n\t"
;                "s_nop 0"
;                : "+v"(a), "+v"(b));
	v_fmac_f32_e32 v179, v141, v134
	v_add_f32_e32 v134, v154, v155
	v_add_f32_e32 v152, v152, v153
	s_waitcnt lgkmcnt(5)
	v_pk_mul_f32 v[188:189], v[26:27], v[132:133]
	v_pk_mul_f32 v[132:133], v[0:1], v[132:133]
	ds_write_b32 v131, v179 offset:50816
	s_nop 0
	v_add_f32_dpp v134, v134, v134 row_ror:8 row_mask:0xf bank_mask:0xf
	v_add_f32_dpp v152, v152, v152 row_ror:8 row_mask:0xf bank_mask:0xf
	s_nop 0
	v_add_f32_dpp v134, v134, v134 row_ror:4 row_mask:0xf bank_mask:0xf
	v_add_f32_dpp v152, v152, v152 row_ror:4 row_mask:0xf bank_mask:0xf
	s_nop 0
	v_add_f32_dpp v134, v134, v134 row_ror:2 row_mask:0xf bank_mask:0xf
	v_add_f32_dpp v152, v152, v152 row_ror:2 row_mask:0xf bank_mask:0xf
	s_nop 0
	v_add_f32_dpp v134, v134, v134 row_ror:1 row_mask:0xf bank_mask:0xf
	v_add_f32_dpp v152, v152, v152 row_ror:1 row_mask:0xf bank_mask:0xf
	v_pk_fma_f32 v[188:189], v[28:29], v[174:175], v[188:189]
	v_pk_fma_f32 v[34:35], v[158:159], v[134:135], v[34:35] op_sel_hi:[1,0,1]
	v_pk_mul_f32 v[174:175], v[2:3], v[174:175]
	s_waitcnt lgkmcnt(3)
	v_pk_fma_f32 v[132:133], v[142:143], v[186:187], v[132:133] op_sel_hi:[1,0,1]
	v_pk_fma_f32 v[170:171], v[160:161], v[134:135], v[150:151] op_sel_hi:[1,0,1]
	v_fmac_f32_e32 v152, v141, v134
	v_add_f32_e32 v134, v188, v189
	v_pk_fma_f32 v[174:175], v[144:145], v[186:187], v[174:175] op_sel_hi:[1,0,1]
	s_waitcnt lgkmcnt(2)
	v_pk_mul_f32 v[188:189], v[146:147], v[132:133]
	v_pk_mul_f32 v[0:1], v[0:1], v[34:35]
	ds_write_b32 v131, v152 offset:50820
	v_pk_fma_f32 v[188:189], v[148:149], v[174:175], v[188:189]
	v_pk_mul_f32 v[26:27], v[26:27], v[34:35]
	v_pk_mul_f32 v[2:3], v[2:3], v[170:171]
	v_pk_fma_f32 v[0:1], v[142:143], v[186:187], v[0:1] op_sel:[0,1,0]
	ds_read_b128 v[150:153], v30 offset:17072
	ds_read_b128 v[154:157], v30 offset:17328
	ds_read_b128 v[158:161], v30 offset:17584
	ds_read_b128 v[162:165], v30 offset:17840
	ds_read_b64 v[172:173], v32 offset:18352
	ds_read_b128 v[166:169], v30 offset:18096
	ds_read_b32 v141, v6 offset:18608
	v_add_f32_e32 v179, v188, v189
	v_pk_fma_f32 v[26:27], v[28:29], v[170:171], v[26:27]
	v_pk_fma_f32 v[2:3], v[144:145], v[186:187], v[2:3] op_sel:[0,1,0]
	v_pk_mul_f32 v[28:29], v[146:147], v[0:1]
	s_nop 0
	v_add_f32_dpp v134, v134, v134 row_ror:8 row_mask:0xf bank_mask:0xf
	v_add_f32_dpp v179, v179, v179 row_ror:8 row_mask:0xf bank_mask:0xf
	s_nop 0
	v_add_f32_dpp v134, v134, v134 row_ror:4 row_mask:0xf bank_mask:0xf
	v_add_f32_dpp v179, v179, v179 row_ror:4 row_mask:0xf bank_mask:0xf
	s_nop 0
	v_add_f32_dpp v134, v134, v134 row_ror:2 row_mask:0xf bank_mask:0xf
	v_add_f32_dpp v179, v179, v179 row_ror:2 row_mask:0xf bank_mask:0xf
	s_nop 0
	v_add_f32_dpp v134, v134, v134 row_ror:1 row_mask:0xf bank_mask:0xf
	v_add_f32_dpp v179, v179, v179 row_ror:1 row_mask:0xf bank_mask:0xf
	v_add_f32_e32 v26, v26, v27
	v_pk_fma_f32 v[132:133], v[136:137], v[134:135], v[132:133] op_sel_hi:[1,0,1]
	v_pk_fma_f32 v[28:29], v[148:149], v[2:3], v[28:29]
	v_pk_fma_f32 v[174:175], v[138:139], v[134:135], v[174:175] op_sel_hi:[1,0,1]
	s_waitcnt lgkmcnt(9)
	v_fmac_f32_e32 v179, v33, v134
	v_add_f32_e32 v27, v28, v29
	s_waitcnt lgkmcnt(5)
	v_pk_mul_f32 v[188:189], v[154:155], v[132:133]
	v_pk_mul_f32 v[132:133], v[150:151], v[132:133]
	ds_write_b32 v131, v179 offset:50944
	s_nop 0
	v_add_f32_dpp v26, v26, v26 row_ror:8 row_mask:0xf bank_mask:0xf
	v_add_f32_dpp v27, v27, v27 row_ror:8 row_mask:0xf bank_mask:0xf
	s_nop 0
	v_add_f32_dpp v26, v26, v26 row_ror:4 row_mask:0xf bank_mask:0xf
	v_add_f32_dpp v27, v27, v27 row_ror:4 row_mask:0xf bank_mask:0xf
	s_nop 0
	v_add_f32_dpp v26, v26, v26 row_ror:2 row_mask:0xf bank_mask:0xf
	v_add_f32_dpp v27, v27, v27 row_ror:2 row_mask:0xf bank_mask:0xf
	s_nop 0
	v_add_f32_dpp v26, v26, v26 row_ror:1 row_mask:0xf bank_mask:0xf
	v_add_f32_dpp v27, v27, v27 row_ror:1 row_mask:0xf bank_mask:0xf
	v_pk_fma_f32 v[188:189], v[156:157], v[174:175], v[188:189]
	v_pk_fma_f32 v[34:35], v[136:137], v[26:27], v[0:1] op_sel_hi:[1,0,1]
	v_pk_mul_f32 v[174:175], v[152:153], v[174:175]
	s_waitcnt lgkmcnt(3)
	v_pk_fma_f32 v[132:133], v[162:163], v[172:173], v[132:133] op_sel_hi:[1,0,1]
	v_pk_fma_f32 v[170:171], v[138:139], v[26:27], v[2:3] op_sel_hi:[1,0,1]
	v_add_f32_e32 v134, v188, v189
	v_pk_fma_f32 v[174:175], v[164:165], v[172:173], v[174:175] op_sel_hi:[1,0,1]
	s_waitcnt lgkmcnt(2)
	v_pk_mul_f32 v[188:189], v[166:167], v[132:133]
	v_pk_mul_f32 v[154:155], v[154:155], v[34:35]
	v_pk_mul_f32 v[34:35], v[150:151], v[34:35]
	v_fmac_f32_e32 v27, v33, v26
	v_pk_fma_f32 v[188:189], v[168:169], v[174:175], v[188:189]
	v_pk_mul_f32 v[150:151], v[152:153], v[170:171]
	v_pk_fma_f32 v[34:35], v[162:163], v[172:173], v[34:35] op_sel:[0,1,0]
	ds_write_b32 v131, v27 offset:50948
	v_add_f32_e32 v179, v188, v189
	v_pk_fma_f32 v[150:151], v[164:165], v[172:173], v[150:151] op_sel:[0,1,0]
	v_pk_mul_f32 v[152:153], v[166:167], v[34:35]
	ds_read_b128 v[0:3], v30 offset:18624
	ds_read_b128 v[26:29], v30 offset:18880
	ds_read_b128 v[136:139], v30 offset:19136
	ds_read_b128 v[142:145], v30 offset:19392
	ds_read_b64 v[186:187], v32 offset:19904
	ds_read_b128 v[146:149], v30 offset:19648
	ds_read_b32 v33, v6 offset:20160
	s_nop 0
	v_add_f32_dpp v134, v134, v134 row_ror:8 row_mask:0xf bank_mask:0xf
	v_add_f32_dpp v179, v179, v179 row_ror:8 row_mask:0xf bank_mask:0xf
	s_nop 0
	v_add_f32_dpp v134, v134, v134 row_ror:4 row_mask:0xf bank_mask:0xf
	v_add_f32_dpp v179, v179, v179 row_ror:4 row_mask:0xf bank_mask:0xf
	s_nop 0
	v_add_f32_dpp v134, v134, v134 row_ror:2 row_mask:0xf bank_mask:0xf
	v_add_f32_dpp v179, v179, v179 row_ror:2 row_mask:0xf bank_mask:0xf
	s_nop 0
	v_add_f32_dpp v134, v134, v134 row_ror:1 row_mask:0xf bank_mask:0xf
	v_add_f32_dpp v179, v179, v179 row_ror:1 row_mask:0xf bank_mask:0xf
	v_pk_fma_f32 v[154:155], v[156:157], v[170:171], v[154:155]
	v_pk_fma_f32 v[132:133], v[158:159], v[134:135], v[132:133] op_sel_hi:[1,0,1]
	v_pk_fma_f32 v[152:153], v[168:169], v[150:151], v[152:153]
	v_pk_fma_f32 v[174:175], v[160:161], v[134:135], v[174:175] op_sel_hi:[1,0,1]
	s_waitcnt lgkmcnt(9)
; DEV void row16_sum2(float& a, float& b) {
;   asm volatile("s_nop 1\n\tv_add_f32_dpp %0, %0, %0 row_ror:8 row_mask:0xf bank_mask:0xf\n\tv_add_f32_dpp %1, %1, %1 row_ror:8 row_mask:0xf bank_mask:0xf\n\t"
;                "s_nop 1\n\tv_add_f32_dpp %0, %0, %0 row_ror:4 row_mask:0xf bank_mask:0xf\n\tv_add_f32_dpp %1, %1, %1 row_ror:4 row_mask:0xf bank_mask:0xf\n\t"
;                "s_nop 1\n\tv_add_f32_dpp %0, %0, %0 row_ror:2 row_mask:0xf bank_mask:0xf\n\tv_add_f32_dpp %1, %1, %1 row_ror:2 row_mask:0xf bank_mask:0xf\n\t"
;                "s_nop 1\n\tv_add_f32_dpp %0, %0, %0 row_ror:1 row_mask:0xf bank_mask:0xf\n\tv_add_f32_dpp %1, %1, %1 row_ror:1 row_mask:0xf bank_mask:0xf\n\t"
;                "s_nop 0"
;                : "+v"(a), "+v"(b));
	v_fmac_f32_e32 v179, v141, v134
	v_add_f32_e32 v134, v154, v155
	v_add_f32_e32 v152, v152, v153
	s_waitcnt lgkmcnt(5)
	v_pk_mul_f32 v[172:173], v[26:27], v[132:133]
	ds_write_b32 v131, v179 offset:51072
	s_nop 0
	v_add_f32_dpp v134, v134, v134 row_ror:8 row_mask:0xf bank_mask:0xf
	v_add_f32_dpp v152, v152, v152 row_ror:8 row_mask:0xf bank_mask:0xf
	s_nop 0
	v_add_f32_dpp v134, v134, v134 row_ror:4 row_mask:0xf bank_mask:0xf
	v_add_f32_dpp v152, v152, v152 row_ror:4 row_mask:0xf bank_mask:0xf
	s_nop 0
	v_add_f32_dpp v134, v134, v134 row_ror:2 row_mask:0xf bank_mask:0xf
	v_add_f32_dpp v152, v152, v152 row_ror:2 row_mask:0xf bank_mask:0xf
	s_nop 0
	v_add_f32_dpp v134, v134, v134 row_ror:1 row_mask:0xf bank_mask:0xf
	v_add_f32_dpp v152, v152, v152 row_ror:1 row_mask:0xf bank_mask:0xf
	v_pk_fma_f32 v[172:173], v[28:29], v[174:175], v[172:173]
	v_pk_mul_f32 v[132:133], v[0:1], v[132:133]
	v_pk_fma_f32 v[34:35], v[158:159], v[134:135], v[34:35] op_sel_hi:[1,0,1]
	v_pk_fma_f32 v[170:171], v[160:161], v[134:135], v[150:151] op_sel_hi:[1,0,1]
	v_fmac_f32_e32 v152, v141, v134
	v_add_f32_e32 v134, v172, v173
	v_pk_mul_f32 v[172:173], v[2:3], v[174:175]
	s_waitcnt lgkmcnt(3)
	v_pk_fma_f32 v[132:133], v[142:143], v[186:187], v[132:133] op_sel_hi:[1,0,1]
	v_pk_fma_f32 v[172:173], v[144:145], v[186:187], v[172:173] op_sel_hi:[1,0,1]
	s_waitcnt lgkmcnt(2)
	v_pk_mul_f32 v[174:175], v[146:147], v[132:133]
	ds_write_b32 v131, v152 offset:51076
	v_pk_fma_f32 v[174:175], v[148:149], v[172:173], v[174:175]
	v_pk_mul_f32 v[0:1], v[0:1], v[34:35]
	ds_read_b128 v[150:153], v30 offset:20176
	ds_read_b128 v[154:157], v30 offset:20432
	ds_read_b128 v[158:161], v30 offset:20688
	ds_read_b128 v[162:165], v30 offset:20944
	ds_read_b64 v[188:189], v32 offset:21456
	ds_read_b128 v[166:169], v30 offset:21200
	ds_read_b32 v141, v6 offset:21712
	v_add_f32_e32 v179, v174, v175
	v_pk_mul_f32 v[26:27], v[26:27], v[34:35]
	v_pk_mul_f32 v[2:3], v[2:3], v[170:171]
	v_pk_fma_f32 v[0:1], v[142:143], v[186:187], v[0:1] op_sel:[0,1,0]
	s_nop 0
	v_add_f32_dpp v134, v134, v134 row_ror:8 row_mask:0xf bank_mask:0xf
	v_add_f32_dpp v179, v179, v179 row_ror:8 row_mask:0xf bank_mask:0xf
	s_nop 0
	v_add_f32_dpp v134, v134, v134 row_ror:4 row_mask:0xf bank_mask:0xf
	v_add_f32_dpp v179, v179, v179 row_ror:4 row_mask:0xf bank_mask:0xf
	s_nop 0
	v_add_f32_dpp v134, v134, v134 row_ror:2 row_mask:0xf bank_mask:0xf
	v_add_f32_dpp v179, v179, v179 row_ror:2 row_mask:0xf bank_mask:0xf
	s_nop 0
	v_add_f32_dpp v134, v134, v134 row_ror:1 row_mask:0xf bank_mask:0xf
	v_add_f32_dpp v179, v179, v179 row_ror:1 row_mask:0xf bank_mask:0xf
	v_pk_fma_f32 v[26:27], v[28:29], v[170:171], v[26:27]
	v_pk_fma_f32 v[132:133], v[136:137], v[134:135], v[132:133] op_sel_hi:[1,0,1]
	v_pk_fma_f32 v[2:3], v[144:145], v[186:187], v[2:3] op_sel:[0,1,0]
	v_pk_mul_f32 v[28:29], v[146:147], v[0:1]
	v_pk_fma_f32 v[174:175], v[138:139], v[134:135], v[172:173] op_sel_hi:[1,0,1]
	v_pk_fma_f32 v[28:29], v[148:149], v[2:3], v[28:29]
	s_waitcnt lgkmcnt(5)
	v_pk_mul_f32 v[186:187], v[154:155], v[132:133]
	v_pk_mul_f32 v[132:133], v[150:151], v[132:133]
	v_fmac_f32_e32 v179, v33, v134
	v_add_f32_e32 v26, v26, v27
	v_add_f32_e32 v27, v28, v29
	v_pk_fma_f32 v[186:187], v[156:157], v[174:175], v[186:187]
	v_pk_mul_f32 v[174:175], v[152:153], v[174:175]
	s_waitcnt lgkmcnt(2)
	v_pk_fma_f32 v[132:133], v[162:163], v[188:189], v[132:133] op_sel_hi:[1,0,1]
	ds_write_b32 v131, v179 offset:51200
	s_nop 0
	v_add_f32_dpp v26, v26, v26 row_ror:8 row_mask:0xf bank_mask:0xf
	v_add_f32_dpp v27, v27, v27 row_ror:8 row_mask:0xf bank_mask:0xf
	s_nop 0
	v_add_f32_dpp v26, v26, v26 row_ror:4 row_mask:0xf bank_mask:0xf
	v_add_f32_dpp v27, v27, v27 row_ror:4 row_mask:0xf bank_mask:0xf
	s_nop 0
	v_add_f32_dpp v26, v26, v26 row_ror:2 row_mask:0xf bank_mask:0xf
	v_add_f32_dpp v27, v27, v27 row_ror:2 row_mask:0xf bank_mask:0xf
	s_nop 0
	v_add_f32_dpp v26, v26, v26 row_ror:1 row_mask:0xf bank_mask:0xf
	v_add_f32_dpp v27, v27, v27 row_ror:1 row_mask:0xf bank_mask:0xf
	v_add_f32_e32 v134, v186, v187
	v_pk_fma_f32 v[0:1], v[136:137], v[26:27], v[0:1] op_sel_hi:[1,0,1]
	v_pk_fma_f32 v[174:175], v[164:165], v[188:189], v[174:175] op_sel_hi:[1,0,1]
	s_waitcnt lgkmcnt(2)
	v_pk_mul_f32 v[186:187], v[166:167], v[132:133]
	v_pk_fma_f32 v[2:3], v[138:139], v[26:27], v[2:3] op_sel_hi:[1,0,1]
	v_fmac_f32_e32 v27, v33, v26
	v_pk_fma_f32 v[186:187], v[168:169], v[174:175], v[186:187]
	v_pk_mul_f32 v[154:155], v[154:155], v[0:1]
	v_pk_mul_f32 v[0:1], v[150:151], v[0:1]
	ds_write_b32 v131, v27 offset:51204
	v_add_f32_e32 v33, v186, v187
	v_pk_fma_f32 v[154:155], v[156:157], v[2:3], v[154:155]
	v_pk_mul_f32 v[2:3], v[152:153], v[2:3]
	v_pk_fma_f32 v[0:1], v[162:163], v[188:189], v[0:1] op_sel:[0,1,0]
	ds_read_b128 v[26:29], v30 offset:21728
	ds_read_b128 v[136:139], v30 offset:21984
	ds_read_b128 v[142:145], v30 offset:22240
	ds_read_b128 v[146:149], v30 offset:22496
	ds_read_b64 v[34:35], v32 offset:23008
	ds_read_b128 v[170:173], v30 offset:22752
	ds_read_b32 v179, v6 offset:23264
	s_nop 0
	v_add_f32_dpp v134, v134, v134 row_ror:8 row_mask:0xf bank_mask:0xf
	v_add_f32_dpp v33, v33, v33 row_ror:8 row_mask:0xf bank_mask:0xf
	s_nop 0
	v_add_f32_dpp v134, v134, v134 row_ror:4 row_mask:0xf bank_mask:0xf
	v_add_f32_dpp v33, v33, v33 row_ror:4 row_mask:0xf bank_mask:0xf
	s_nop 0
	v_add_f32_dpp v134, v134, v134 row_ror:2 row_mask:0xf bank_mask:0xf
	v_add_f32_dpp v33, v33, v33 row_ror:2 row_mask:0xf bank_mask:0xf
	s_nop 0
	v_add_f32_dpp v134, v134, v134 row_ror:1 row_mask:0xf bank_mask:0xf
	v_add_f32_dpp v33, v33, v33 row_ror:1 row_mask:0xf bank_mask:0xf
	v_pk_fma_f32 v[2:3], v[164:165], v[188:189], v[2:3] op_sel:[0,1,0]
	v_pk_mul_f32 v[150:151], v[166:167], v[0:1]
	s_waitcnt lgkmcnt(9)
; DEV void row16_sum2(float& a, float& b) {
;   asm volatile("s_nop 1\n\tv_add_f32_dpp %0, %0, %0 row_ror:8 row_mask:0xf bank_mask:0xf\n\tv_add_f32_dpp %1, %1, %1 row_ror:8 row_mask:0xf bank_mask:0xf\n\t"
;                "s_nop 1\n\tv_add_f32_dpp %0, %0, %0 row_ror:4 row_mask:0xf bank_mask:0xf\n\tv_add_f32_dpp %1, %1, %1 row_ror:4 row_mask:0xf bank_mask:0xf\n\t"
;                "s_nop 1\n\tv_add_f32_dpp %0, %0, %0 row_ror:2 row_mask:0xf bank_mask:0xf\n\tv_add_f32_dpp %1, %1, %1 row_ror:2 row_mask:0xf bank_mask:0xf\n\t"
;                "s_nop 1\n\tv_add_f32_dpp %0, %0, %0 row_ror:1 row_mask:0xf bank_mask:0xf\n\tv_add_f32_dpp %1, %1, %1 row_ror:1 row_mask:0xf bank_mask:0xf\n\t"
;                "s_nop 0"
;                : "+v"(a), "+v"(b));
	v_fmac_f32_e32 v33, v141, v134
	v_pk_fma_f32 v[150:151], v[168:169], v[2:3], v[150:151]
	v_pk_fma_f32 v[132:133], v[158:159], v[134:135], v[132:133] op_sel_hi:[1,0,1]
	v_pk_fma_f32 v[174:175], v[160:161], v[134:135], v[174:175] op_sel_hi:[1,0,1]
	ds_write_b32 v131, v33 offset:51328
	v_add_f32_e32 v134, v154, v155
	v_add_f32_e32 v33, v150, v151
	s_nop 0
	v_add_f32_dpp v134, v134, v134 row_ror:8 row_mask:0xf bank_mask:0xf
	v_add_f32_dpp v33, v33, v33 row_ror:8 row_mask:0xf bank_mask:0xf
	s_nop 0
	v_add_f32_dpp v134, v134, v134 row_ror:4 row_mask:0xf bank_mask:0xf
	v_add_f32_dpp v33, v33, v33 row_ror:4 row_mask:0xf bank_mask:0xf
	s_nop 0
	v_add_f32_dpp v134, v134, v134 row_ror:2 row_mask:0xf bank_mask:0xf
	v_add_f32_dpp v33, v33, v33 row_ror:2 row_mask:0xf bank_mask:0xf
	s_nop 0
	v_add_f32_dpp v134, v134, v134 row_ror:1 row_mask:0xf bank_mask:0xf
	v_add_f32_dpp v33, v33, v33 row_ror:1 row_mask:0xf bank_mask:0xf
	v_fmac_f32_e32 v33, v141, v134
	ds_write_b32 v131, v33 offset:51332
	v_pk_fma_f32 v[166:167], v[158:159], v[134:135], v[0:1] op_sel_hi:[1,0,1]
	v_pk_fma_f32 v[168:169], v[160:161], v[134:135], v[2:3] op_sel_hi:[1,0,1]
	ds_read_b128 v[150:153], v30 offset:23280
	ds_read_b128 v[154:157], v30 offset:23536
	ds_read_b128 v[0:3], v30 offset:23792
	ds_read_b128 v[158:161], v30 offset:24048
	ds_read_b64 v[186:187], v32 offset:24560
	ds_read_b128 v[162:165], v30 offset:24304
	ds_read_b32 v134, v6 offset:24816
	s_waitcnt lgkmcnt(14)
	v_pk_mul_f32 v[32:33], v[136:137], v[132:133]
	v_pk_mul_f32 v[136:137], v[136:137], v[166:167]
	v_pk_fma_f32 v[32:33], v[138:139], v[174:175], v[32:33]
	v_pk_fma_f32 v[136:137], v[138:139], v[168:169], v[136:137]
	v_add_f32_e32 v6, v32, v33
	v_pk_mul_f32 v[32:33], v[26:27], v[132:133]
	v_pk_mul_f32 v[132:133], v[28:29], v[174:175]
	s_waitcnt lgkmcnt(11)
	v_pk_fma_f32 v[32:33], v[146:147], v[34:35], v[32:33] op_sel_hi:[1,0,1]
	v_pk_fma_f32 v[132:133], v[148:149], v[34:35], v[132:133] op_sel_hi:[1,0,1]
	s_waitcnt lgkmcnt(10)
	v_pk_mul_f32 v[174:175], v[170:171], v[32:33]
	v_pk_mul_f32 v[26:27], v[26:27], v[166:167]
	v_pk_fma_f32 v[174:175], v[172:173], v[132:133], v[174:175]
	v_pk_mul_f32 v[28:29], v[28:29], v[168:169]
	v_add_f32_e32 v30, v174, v175
	v_pk_fma_f32 v[26:27], v[146:147], v[34:35], v[26:27] op_sel:[0,1,0]
	s_nop 0
	v_add_f32_dpp v6, v6, v6 row_ror:8 row_mask:0xf bank_mask:0xf
	v_add_f32_dpp v30, v30, v30 row_ror:8 row_mask:0xf bank_mask:0xf
	s_nop 0
	v_add_f32_dpp v6, v6, v6 row_ror:4 row_mask:0xf bank_mask:0xf
	v_add_f32_dpp v30, v30, v30 row_ror:4 row_mask:0xf bank_mask:0xf
	s_nop 0
	v_add_f32_dpp v6, v6, v6 row_ror:2 row_mask:0xf bank_mask:0xf
	v_add_f32_dpp v30, v30, v30 row_ror:2 row_mask:0xf bank_mask:0xf
	s_nop 0
	v_add_f32_dpp v6, v6, v6 row_ror:1 row_mask:0xf bank_mask:0xf
	v_add_f32_dpp v30, v30, v30 row_ror:1 row_mask:0xf bank_mask:0xf
	v_pk_fma_f32 v[28:29], v[148:149], v[34:35], v[28:29] op_sel:[0,1,0]
	v_pk_mul_f32 v[34:35], v[170:171], v[26:27]
	s_waitcnt lgkmcnt(9)
	v_fmac_f32_e32 v30, v179, v6
	v_pk_fma_f32 v[34:35], v[172:173], v[28:29], v[34:35]
	v_pk_fma_f32 v[32:33], v[142:143], v[6:7], v[32:33] op_sel_hi:[1,0,1]
	v_pk_fma_f32 v[132:133], v[144:145], v[6:7], v[132:133] op_sel_hi:[1,0,1]
	ds_write_b32 v131, v30 offset:51456
	v_add_f32_e32 v6, v136, v137
	v_add_f32_e32 v30, v34, v35
	s_nop 0
	v_add_f32_dpp v6, v6, v6 row_ror:8 row_mask:0xf bank_mask:0xf
	v_add_f32_dpp v30, v30, v30 row_ror:8 row_mask:0xf bank_mask:0xf
	s_nop 0
	v_add_f32_dpp v6, v6, v6 row_ror:4 row_mask:0xf bank_mask:0xf
	v_add_f32_dpp v30, v30, v30 row_ror:4 row_mask:0xf bank_mask:0xf
	s_nop 0
	v_add_f32_dpp v6, v6, v6 row_ror:2 row_mask:0xf bank_mask:0xf
	v_add_f32_dpp v30, v30, v30 row_ror:2 row_mask:0xf bank_mask:0xf
	s_nop 0
	v_add_f32_dpp v6, v6, v6 row_ror:1 row_mask:0xf bank_mask:0xf
	v_add_f32_dpp v30, v30, v30 row_ror:1 row_mask:0xf bank_mask:0xf
	v_pk_fma_f32 v[34:35], v[142:143], v[6:7], v[26:27] op_sel_hi:[1,0,1]
	s_waitcnt lgkmcnt(6)
	v_pk_mul_f32 v[26:27], v[154:155], v[32:33]
	v_pk_fma_f32 v[136:137], v[144:145], v[6:7], v[28:29] op_sel_hi:[1,0,1]
	v_pk_fma_f32 v[26:27], v[156:157], v[132:133], v[26:27]
	v_fmac_f32_e32 v30, v179, v6
	v_add_f32_e32 v6, v26, v27
	v_pk_mul_f32 v[26:27], v[150:151], v[32:33]
	v_pk_mul_f32 v[28:29], v[152:153], v[132:133]
	s_waitcnt lgkmcnt(3)
	v_pk_fma_f32 v[26:27], v[158:159], v[186:187], v[26:27] op_sel_hi:[1,0,1]
	v_pk_fma_f32 v[28:29], v[160:161], v[186:187], v[28:29] op_sel_hi:[1,0,1]
	s_waitcnt lgkmcnt(2)
	v_pk_mul_f32 v[32:33], v[162:163], v[26:27]
	ds_write_b32 v131, v30 offset:51460
	v_pk_fma_f32 v[32:33], v[164:165], v[28:29], v[32:33]
	s_nop 0
	v_add_f32_e32 v30, v32, v33
	s_nop 0
	v_add_f32_dpp v6, v6, v6 row_ror:8 row_mask:0xf bank_mask:0xf
	v_add_f32_dpp v30, v30, v30 row_ror:8 row_mask:0xf bank_mask:0xf
	s_nop 0
	v_add_f32_dpp v6, v6, v6 row_ror:4 row_mask:0xf bank_mask:0xf
	v_add_f32_dpp v30, v30, v30 row_ror:4 row_mask:0xf bank_mask:0xf
	s_nop 0
	v_add_f32_dpp v6, v6, v6 row_ror:2 row_mask:0xf bank_mask:0xf
	v_add_f32_dpp v30, v30, v30 row_ror:2 row_mask:0xf bank_mask:0xf
	s_nop 0
	v_add_f32_dpp v6, v6, v6 row_ror:1 row_mask:0xf bank_mask:0xf
	v_add_f32_dpp v30, v30, v30 row_ror:1 row_mask:0xf bank_mask:0xf
	v_pk_mul_f32 v[32:33], v[154:155], v[34:35]
	s_waitcnt lgkmcnt(2)
	v_fmac_f32_e32 v30, v134, v6
	v_pk_fma_f32 v[32:33], v[156:157], v[136:137], v[32:33]
	ds_write_b32 v131, v30 offset:51584
	v_add_f32_e32 v30, v32, v33
	v_pk_mul_f32 v[32:33], v[150:151], v[34:35]
	v_pk_mul_f32 v[34:35], v[152:153], v[136:137]
	v_pk_fma_f32 v[32:33], v[158:159], v[186:187], v[32:33] op_sel:[0,1,0]
	v_pk_fma_f32 v[34:35], v[160:161], v[186:187], v[34:35] op_sel:[0,1,0]
	v_pk_mul_f32 v[132:133], v[162:163], v[32:33]
	s_nop 0
	v_pk_fma_f32 v[132:133], v[164:165], v[34:35], v[132:133]
	s_nop 0
	v_add_f32_e32 v132, v132, v133
	s_nop 0
	v_add_f32_dpp v30, v30, v30 row_ror:8 row_mask:0xf bank_mask:0xf
	v_add_f32_dpp v132, v132, v132 row_ror:8 row_mask:0xf bank_mask:0xf
	s_nop 0
	v_add_f32_dpp v30, v30, v30 row_ror:4 row_mask:0xf bank_mask:0xf
	v_add_f32_dpp v132, v132, v132 row_ror:4 row_mask:0xf bank_mask:0xf
	s_nop 0
	v_add_f32_dpp v30, v30, v30 row_ror:2 row_mask:0xf bank_mask:0xf
	v_add_f32_dpp v132, v132, v132 row_ror:2 row_mask:0xf bank_mask:0xf
	s_nop 0
	v_add_f32_dpp v30, v30, v30 row_ror:1 row_mask:0xf bank_mask:0xf
	v_add_f32_dpp v132, v132, v132 row_ror:1 row_mask:0xf bank_mask:0xf
	v_fmac_f32_e32 v132, v134, v30
	ds_write_b32 v131, v132 offset:51588
	s_cbranch_vccnz .LBB0_1957
	v_cndmask_b32_e64 v129, v130, v129, s[10:11]
	s_waitcnt vmcnt(46)
	v_lshlrev_b32_e32 v131, 16, v82
	v_cmp_lt_i32_e32 vcc, 0, v129
	v_lshlrev_b32_e32 v130, 16, v13
	s_waitcnt vmcnt(45)
	v_lshlrev_b32_e32 v132, 16, v83
	v_cndmask_b32_e32 v131, 0, v131, vcc
	v_cmp_gt_i32_e64 s[12:13], s35, v129
	v_sub_f32_e32 v131, v131, v130
	s_waitcnt vmcnt(39)
	v_lshlrev_b32_e32 v133, 16, v89
	v_cndmask_b32_e64 v129, 0, v132, s[12:13]
	v_sub_f32_e32 v129, v129, v130
	v_fmac_f32_e32 v130, v9, v131
	v_lshlrev_b32_e32 v131, 16, v85
	v_fmac_f32_e32 v130, v75, v129
	v_lshlrev_b32_e32 v129, 16, v84
	v_cndmask_b32_e32 v131, 0, v131, vcc
	v_lshlrev_b32_e32 v132, 16, v86
	v_sub_f32_e32 v131, v131, v129
	v_cndmask_b32_e64 v132, 0, v132, s[12:13]
	v_sub_f32_e32 v132, v132, v129
	v_fmac_f32_e32 v129, v76, v131
	v_fmac_f32_e32 v129, v77, v132
	v_lshlrev_b32_e32 v132, 16, v88
	v_lshlrev_b32_e32 v131, 16, v87
	v_cndmask_b32_e32 v132, 0, v132, vcc
	v_sub_f32_e32 v132, v132, v131
	v_cndmask_b32_e64 v133, 0, v133, s[12:13]
	v_sub_f32_e32 v133, v133, v131
	v_fmac_f32_e32 v131, v78, v132
	s_waitcnt vmcnt(37)
	v_lshlrev_b32_e32 v132, 16, v91
	v_add_f32_e32 v134, -1.0, v132
	v_fma_f32 v134, v81, v134, 1.0
	v_fmac_f32_e32 v131, v79, v133
	v_mul_f32_e32 v133, v80, v129
	v_mul_f32_e32 v134, v134, v129
	v_lshlrev_b32_e32 v129, 16, v90
	v_mul_f32_e32 v129, 0x3fb8aa3b, v129
	s_bitcmp1_b32 s15, 0
	v_exp_f32_e32 v136, v129
	s_cselect_b32 s22, 0x6100, 0
	v_add_u32_e32 v129, s22, v43
	s_waitcnt vmcnt(36)
	v_mul_f32_e64 v133, v133, -v16
	v_lshl_add_u32 v137, v182, 2, v129
	v_mul_f32_e64 v132, -v133, v132
	ds_write2st64_b32 v137, v136, v133 offset1:1
	ds_write2st64_b32 v137, v132, v134 offset0:2 offset1:3
	ds_write2st64_b32 v137, v130, v131 offset0:4 offset1:5
	s_and_saveexec_b64 s[12:13], s[6:7]
	ds_write_b32 v129, v17 offset:1536
	s_or_b64 exec, exec, s[12:13]
	v_cndmask_b32_e64 v127, v128, v127, s[10:11]
	s_waitcnt vmcnt(34)
	v_lshlrev_b32_e32 v129, 16, v93
	v_cmp_lt_i32_e32 vcc, 0, v127
	v_lshlrev_b32_e32 v128, 16, v92
	s_waitcnt vmcnt(33)
	v_lshlrev_b32_e32 v130, 16, v94
	v_cndmask_b32_e32 v129, 0, v129, vcc
	v_cmp_gt_i32_e64 s[12:13], s35, v127
	v_sub_f32_e32 v129, v129, v128
	s_waitcnt vmcnt(27)
	v_lshlrev_b32_e32 v131, 16, v100
	v_cndmask_b32_e64 v127, 0, v130, s[12:13]
	v_sub_f32_e32 v127, v127, v128
	v_fmac_f32_e32 v128, v9, v129
	v_lshlrev_b32_e32 v129, 16, v96
	v_fmac_f32_e32 v128, v75, v127
	v_lshlrev_b32_e32 v127, 16, v95
	v_cndmask_b32_e32 v129, 0, v129, vcc
	v_lshlrev_b32_e32 v130, 16, v97
	v_sub_f32_e32 v129, v129, v127
	v_cndmask_b32_e64 v130, 0, v130, s[12:13]
	v_sub_f32_e32 v130, v130, v127
	v_fmac_f32_e32 v127, v76, v129
	v_fmac_f32_e32 v127, v77, v130
	v_lshlrev_b32_e32 v130, 16, v99
	v_lshlrev_b32_e32 v129, 16, v98
	v_cndmask_b32_e32 v130, 0, v130, vcc
	v_sub_f32_e32 v130, v130, v129
	v_cndmask_b32_e64 v131, 0, v131, s[12:13]
	v_sub_f32_e32 v131, v131, v129
	v_fmac_f32_e32 v129, v78, v130
	s_waitcnt vmcnt(25)
	v_lshlrev_b32_e32 v130, 16, v102
	v_add_f32_e32 v132, -1.0, v130
	v_fma_f32 v132, v81, v132, 1.0
	v_fmac_f32_e32 v129, v79, v131
	v_mul_f32_e32 v131, v80, v127
	v_mul_f32_e32 v132, v132, v127
	v_lshlrev_b32_e32 v127, 16, v101
	v_mul_f32_e32 v127, 0x3fb8aa3b, v127
	v_exp_f32_e32 v133, v127
	v_add_u32_e32 v127, s22, v45
	s_waitcnt vmcnt(24)
	v_mul_f32_e64 v131, v131, -v18
	v_lshl_add_u32 v134, v182, 2, v127
	v_mul_f32_e64 v130, -v131, v130
	ds_write2st64_b32 v134, v133, v131 offset1:1
	ds_write2st64_b32 v134, v130, v132 offset0:2 offset1:3
	ds_write2st64_b32 v134, v128, v129 offset0:4 offset1:5
	s_and_saveexec_b64 s[12:13], s[6:7]
	ds_write_b32 v127, v19 offset:1536
	s_or_b64 exec, exec, s[12:13]
	v_cndmask_b32_e64 v11, v126, v11, s[10:11]
	s_waitcnt vmcnt(22)
	v_lshlrev_b32_e32 v127, 16, v104
	v_cmp_lt_i32_e32 vcc, 0, v11
	v_lshlrev_b32_e32 v126, 16, v103
	s_waitcnt vmcnt(21)
	v_lshlrev_b32_e32 v128, 16, v105
	v_cndmask_b32_e32 v127, 0, v127, vcc
	v_cmp_gt_i32_e64 s[12:13], s35, v11
	v_sub_f32_e32 v127, v127, v126
	s_waitcnt vmcnt(15)
	v_lshlrev_b32_e32 v129, 16, v111
	v_cndmask_b32_e64 v11, 0, v128, s[12:13]
	v_sub_f32_e32 v11, v11, v126
	v_fmac_f32_e32 v126, v9, v127
	v_lshlrev_b32_e32 v127, 16, v107
	v_fmac_f32_e32 v126, v75, v11
	v_lshlrev_b32_e32 v11, 16, v106
	v_cndmask_b32_e32 v127, 0, v127, vcc
	v_lshlrev_b32_e32 v128, 16, v108
	v_sub_f32_e32 v127, v127, v11
	v_cndmask_b32_e64 v128, 0, v128, s[12:13]
	v_sub_f32_e32 v128, v128, v11
	v_fmac_f32_e32 v11, v76, v127
	v_fmac_f32_e32 v11, v77, v128
	v_lshlrev_b32_e32 v128, 16, v110
	v_lshlrev_b32_e32 v127, 16, v109
	v_cndmask_b32_e32 v128, 0, v128, vcc
	v_sub_f32_e32 v128, v128, v127
	v_cndmask_b32_e64 v129, 0, v129, s[12:13]
	v_sub_f32_e32 v129, v129, v127
	v_fmac_f32_e32 v127, v78, v128
	s_waitcnt vmcnt(13)
	v_lshlrev_b32_e32 v128, 16, v113
	v_add_f32_e32 v130, -1.0, v128
	v_fma_f32 v130, v81, v130, 1.0
	v_fmac_f32_e32 v127, v79, v129
	v_mul_f32_e32 v129, v80, v11
	v_mul_f32_e32 v130, v130, v11
	v_lshlrev_b32_e32 v11, 16, v112
	v_mul_f32_e32 v11, 0x3fb8aa3b, v11
	v_exp_f32_e32 v131, v11
	v_add_u32_e32 v11, s22, v47
	s_waitcnt vmcnt(12)
	v_mul_f32_e64 v129, v129, -v20
	v_lshl_add_u32 v132, v182, 2, v11
	v_mul_f32_e64 v128, -v129, v128
	ds_write2st64_b32 v132, v131, v129 offset1:1
	ds_write2st64_b32 v132, v128, v130 offset0:2 offset1:3
	ds_write2st64_b32 v132, v126, v127 offset0:4 offset1:5
	s_and_saveexec_b64 s[12:13], s[6:7]
	ds_write_b32 v11, v21 offset:1536
	s_or_b64 exec, exec, s[12:13]
	v_add_u32_e32 v11, s14, v64
	v_add_u32_e32 v126, s3, v65
	v_cndmask_b32_e64 v11, v126, v11, s[10:11]
	s_waitcnt vmcnt(10)
	v_lshlrev_b32_e32 v127, 16, v115
	v_cmp_lt_i32_e32 vcc, 0, v11
	v_lshlrev_b32_e32 v126, 16, v114
	s_waitcnt vmcnt(9)
	v_lshlrev_b32_e32 v128, 16, v116
	v_cndmask_b32_e32 v127, 0, v127, vcc
	v_cmp_gt_i32_e64 s[12:13], s35, v11
	v_sub_f32_e32 v127, v127, v126
	s_waitcnt vmcnt(3)
	v_lshlrev_b32_e32 v129, 16, v122
	v_cndmask_b32_e64 v11, 0, v128, s[12:13]
	v_sub_f32_e32 v11, v11, v126
	v_fmac_f32_e32 v126, v9, v127
	v_lshlrev_b32_e32 v127, 16, v118
	v_fmac_f32_e32 v126, v75, v11
	v_lshlrev_b32_e32 v11, 16, v117
	v_cndmask_b32_e32 v127, 0, v127, vcc
	v_lshlrev_b32_e32 v128, 16, v119
	v_sub_f32_e32 v127, v127, v11
	v_cndmask_b32_e64 v128, 0, v128, s[12:13]
	v_sub_f32_e32 v128, v128, v11
	v_fmac_f32_e32 v11, v76, v127
	v_fmac_f32_e32 v11, v77, v128
	v_lshlrev_b32_e32 v128, 16, v121
	v_lshlrev_b32_e32 v127, 16, v120
	v_cndmask_b32_e32 v128, 0, v128, vcc
	v_sub_f32_e32 v128, v128, v127
	v_cndmask_b32_e64 v129, 0, v129, s[12:13]
	v_sub_f32_e32 v129, v129, v127
	v_fmac_f32_e32 v127, v78, v128
	s_waitcnt vmcnt(1)
	v_lshlrev_b32_e32 v128, 16, v124
	v_add_f32_e32 v130, -1.0, v128
	v_fma_f32 v130, v81, v130, 1.0
	v_fmac_f32_e32 v127, v79, v129
	v_mul_f32_e32 v129, v80, v11
	v_mul_f32_e32 v130, v11, v130
	v_lshlrev_b32_e32 v11, 16, v123
	v_mul_f32_e32 v11, 0x3fb8aa3b, v11
	v_exp_f32_e32 v131, v11
	v_add_u32_e32 v11, s22, v49
	s_waitcnt vmcnt(0)
	v_mul_f32_e64 v129, v129, -v22
	v_lshl_add_u32 v132, v182, 2, v11
	v_mul_f32_e64 v128, -v129, v128
	ds_write2st64_b32 v132, v131, v129 offset1:1
	ds_write2st64_b32 v132, v128, v130 offset0:2 offset1:3
	ds_write2st64_b32 v132, v126, v127 offset0:4 offset1:5
	s_and_saveexec_b64 s[12:13], s[6:7]
	s_cbranch_execz .LBB0_1956
	ds_write_b32 v11, v23 offset:1536
	s_branch .LBB0_1956

.LBB0_1983:
	v_add_u32_e32 v9, s29, v5
	v_add_u32_e32 v77, s28, v66
	v_add_u32_e32 v6, 16, v9
	v_add_u32_e32 v18, 0x1fef, v77
	v_cndmask_b32_e32 v6, v18, v6, vcc
	v_add_u32_e32 v18, s3, v6
	v_cmp_lt_i32_e64 s[18:19], 0, v6
	v_ashrrev_i32_e32 v19, 31, v18
	v_mad_i64_i32 v[28:29], s[10:11], v18, s88, v[16:17]
	v_cndmask_b32_e64 v21, 0, -1, s[18:19]
	v_cndmask_b32_e64 v20, 0, v73, s[18:19]
	v_cmp_gt_i32_e64 s[20:21], s94, v6
	v_lshl_add_u64 v[154:155], v[28:29], 0, v[20:21]
	v_lshlrev_b64 v[20:21], 10, v[18:19]
	v_lshlrev_b64 v[18:19], 7, v[18:19]
	v_cndmask_b32_e64 v6, 0, v74, s[20:21]
	v_lshl_add_u64 v[18:19], s[92:93], 0, v[18:19]
	v_lshl_add_u64 v[156:157], v[28:29], 0, v[6:7]
	global_load_dwordx2 v[22:23], v[18:19], off
	v_add_u32_e32 v6, 17, v9
	v_add_u32_e32 v18, 0x1fee, v77
	v_cndmask_b32_e32 v6, v18, v6, vcc
	v_or_b32_e32 v20, v20, v14
	v_add_u32_e32 v18, s3, v6
	v_lshl_add_u64 v[158:159], s[90:91], 0, v[20:21]
	v_lshl_add_u64 v[160:161], s[24:25], 0, v[20:21]
	v_mad_i64_i32 v[20:21], s[10:11], v18, s88, v[16:17]
	v_cmp_lt_i32_e64 s[10:11], 0, v6
	v_cmp_gt_i32_e64 s[14:15], s94, v6
	v_ashrrev_i32_e32 v19, 31, v18
	v_cndmask_b32_e64 v25, 0, -1, s[10:11]
	v_cndmask_b32_e64 v24, 0, v73, s[10:11]
	v_cndmask_b32_e64 v6, 0, v74, s[14:15]
	v_lshl_add_u64 v[24:25], v[20:21], 0, v[24:25]
	v_lshl_add_u64 v[26:27], v[20:21], 0, v[6:7]
	global_load_ushort v101, v[20:21], off
	global_load_ushort v98, v[20:21], off offset:1024
	global_load_ushort v86, v[20:21], off offset:2048
	v_lshlrev_b64 v[20:21], 10, v[18:19]
	v_or_b32_e32 v20, v20, v14
	v_lshlrev_b64 v[18:19], 7, v[18:19]
	v_lshl_add_u64 v[24:25], s[90:91], 0, v[20:21]
	v_lshl_add_u64 v[20:21], s[24:25], 0, v[20:21]
	v_lshl_add_u64 v[18:19], s[92:93], 0, v[18:19]
	global_load_ushort v85, v[24:25], off
	global_load_ushort v97, v[20:21], off
	v_add_u32_e32 v6, 18, v9
	global_load_dwordx2 v[24:25], v[18:19], off
	v_add_u32_e32 v18, 0x1fed, v77
	v_cndmask_b32_e32 v6, v18, v6, vcc
	v_add_u32_e32 v18, s3, v6
	v_mad_i64_i32 v[20:21], s[12:13], v18, s88, v[16:17]
	v_cmp_lt_i32_e64 s[12:13], 0, v6
	v_cmp_gt_i32_e64 s[16:17], s94, v6
	v_ashrrev_i32_e32 v19, 31, v18
	v_cndmask_b32_e64 v27, 0, -1, s[12:13]
	v_cndmask_b32_e64 v26, 0, v73, s[12:13]
	v_cndmask_b32_e64 v6, 0, v74, s[16:17]
	v_lshl_add_u64 v[26:27], v[20:21], 0, v[26:27]
	v_lshl_add_u64 v[78:79], v[20:21], 0, v[6:7]
	global_load_ushort v102, v[20:21], off
	global_load_ushort v103, v[20:21], off offset:1024
	global_load_ushort v93, v[20:21], off offset:2048
	v_lshlrev_b64 v[20:21], 10, v[18:19]
	v_or_b32_e32 v20, v20, v14
	v_lshlrev_b64 v[18:19], 7, v[18:19]
	v_add_u32_e32 v6, 19, v9
	v_add_u32_e32 v9, 0x1fec, v77
	v_lshl_add_u64 v[26:27], s[90:91], 0, v[20:21]
	v_lshl_add_u64 v[20:21], s[24:25], 0, v[20:21]
	v_lshl_add_u64 v[18:19], s[92:93], 0, v[18:19]
	v_cndmask_b32_e32 v6, v9, v6, vcc
	global_load_ushort v81, v[26:27], off
	global_load_ushort v95, v[20:21], off
	s_mov_b32 s31, s30
	global_load_dwordx2 v[20:21], v[18:19], off
	v_add_u32_e32 v18, s3, v6
	v_mad_i64_i32 v[26:27], s[22:23], v18, s88, v[16:17]
	v_cmp_lt_i32_e64 s[22:23], 0, v6
	v_ashrrev_i32_e32 v19, 31, v18
	global_load_ushort v82, v[26:27], off
	v_cndmask_b32_e64 v79, 0, -1, s[22:23]
	v_cndmask_b32_e64 v78, 0, v73, s[22:23]
	v_cmp_gt_i32_e64 s[22:23], s94, v6
	v_lshl_add_u64 v[110:111], v[26:27], 0, v[78:79]
	global_load_ushort v92, v[110:111], off
	v_cndmask_b32_e64 v6, 0, v74, s[22:23]
	v_lshl_add_u64 v[112:113], v[26:27], 0, v[6:7]
	global_load_ushort v88, v[112:113], off
	global_load_ushort v89, v[26:27], off offset:1024
	global_load_ushort v90, v[110:111], off offset:1024
	global_load_ushort v84, v[112:113], off offset:1024
	global_load_ushort v78, v[26:27], off offset:2048
	global_load_ushort v79, v[110:111], off offset:2048
	global_load_ushort v77, v[112:113], off offset:2048
	v_lshlrev_b64 v[26:27], 10, v[18:19]
	v_or_b32_e32 v26, v26, v14
	v_lshlrev_b64 v[18:19], 7, v[18:19]
	s_and_b32 s22, s31, 1
	v_lshl_add_u64 v[110:111], s[90:91], 0, v[26:27]
	v_lshl_add_u64 v[26:27], s[24:25], 0, v[26:27]
	v_lshl_add_u64 v[18:19], s[92:93], 0, v[18:19]
	s_mul_i32 s23, s22, 0x6100
	global_load_ushort v9, v[110:111], off
	global_load_ushort v80, v[26:27], off
	v_mov_b32_e32 v6, s23
	global_load_dwordx2 v[18:19], v[18:19], off
	v_lshl_or_b32 v26, v52, 2, s23
	v_lshl_add_u32 v27, v15, 2, s23
	ds_read_b128 v[110:113], v26
	ds_read_b128 v[114:117], v26 offset:256
	ds_read_b128 v[122:125], v26 offset:512
	ds_read_b128 v[118:121], v26 offset:768
	ds_read_b128 v[126:129], v26 offset:1024
	ds_read_b32 v134, v27 offset:1280
	ds_read_b32 v141, v6 offset:1536
	s_waitcnt lgkmcnt(5)
	v_pk_mul_f32 v[114:115], v[0:1], v[114:115]
	ds_read_b128 v[130:133], v26 offset:1552
	ds_read_b128 v[136:139], v26 offset:1808
	ds_read_b128 v[142:145], v26 offset:2064
	ds_read_b128 v[146:149], v26 offset:2320
	ds_read_b128 v[150:153], v26 offset:2576
	ds_read_b32 v162, v27 offset:2832
	ds_read_b32 v166, v6 offset:3088
	v_pk_fma_f32 v[114:115], v[2:3], v[116:117], v[114:115]
	s_waitcnt lgkmcnt(8)
	v_pk_mul_f32 v[118:119], v[118:119], v[134:135] op_sel_hi:[1,0]
	v_pk_mul_f32 v[120:121], v[120:121], v[134:135] op_sel_hi:[1,0]
	v_pk_fma_f32 v[0:1], v[0:1], v[110:111], v[118:119]
	v_pk_fma_f32 v[2:3], v[2:3], v[112:113], v[120:121]
	v_pk_mul_f32 v[110:111], v[126:127], v[0:1]
	v_add_f32_e32 v134, v114, v115
	v_pk_fma_f32 v[110:111], v[128:129], v[2:3], v[110:111]
	s_mulk_i32 s22, 0xa300
	v_add_f32_e32 v121, v110, v111
	global_load_ushort v119, v[28:29], off
	global_load_ushort v120, v[154:155], off
	global_load_ushort v118, v[156:157], off
	global_load_ushort v116, v[28:29], off offset:1024
	global_load_ushort v117, v[154:155], off offset:1024
	global_load_ushort v115, v[156:157], off offset:1024
	global_load_ushort v112, v[28:29], off offset:2048
	global_load_ushort v113, v[154:155], off offset:2048
	global_load_ushort v114, v[156:157], off offset:2048
	global_load_ushort v111, v[160:161], off
	global_load_ushort v110, v[158:159], off
	s_nop 0
	v_add_f32_dpp v134, v134, v134 row_ror:8 row_mask:0xf bank_mask:0xf
	v_add_f32_dpp v121, v121, v121 row_ror:8 row_mask:0xf bank_mask:0xf
	s_nop 0
	v_add_f32_dpp v134, v134, v134 row_ror:4 row_mask:0xf bank_mask:0xf
	v_add_f32_dpp v121, v121, v121 row_ror:4 row_mask:0xf bank_mask:0xf
	s_nop 0
	v_add_f32_dpp v134, v134, v134 row_ror:2 row_mask:0xf bank_mask:0xf
	v_add_f32_dpp v121, v121, v121 row_ror:2 row_mask:0xf bank_mask:0xf
	s_nop 0
	v_add_f32_dpp v134, v134, v134 row_ror:1 row_mask:0xf bank_mask:0xf
	v_add_f32_dpp v121, v121, v121 row_ror:1 row_mask:0xf bank_mask:0xf
	s_add_i32 s22, s23, s22
	v_pk_fma_f32 v[28:29], v[122:123], v[134:135], v[0:1] op_sel_hi:[1,0,1]
	v_pk_fma_f32 v[164:165], v[124:125], v[134:135], v[2:3] op_sel_hi:[1,0,1]
	s_waitcnt lgkmcnt(5)
	v_pk_mul_f32 v[136:137], v[136:137], v[28:29]
	v_pk_mul_f32 v[28:29], v[130:131], v[28:29]
	v_lshl_add_u32 v109, v58, 2, s22
	v_fmac_f32_e32 v121, v141, v134
	v_pk_mul_f32 v[130:131], v[132:133], v[164:165]
	s_waitcnt lgkmcnt(1)
	v_pk_fma_f32 v[28:29], v[146:147], v[162:163], v[28:29] op_sel_hi:[1,0,1]
	ds_write_b32 v109, v121 offset:49664
	v_pk_fma_f32 v[130:131], v[148:149], v[162:163], v[130:131] op_sel_hi:[1,0,1]
	v_pk_mul_f32 v[132:133], v[150:151], v[28:29]
	ds_read_b128 v[0:3], v26 offset:3104
	ds_read_b128 v[122:125], v26 offset:3360
	ds_read_b128 v[126:129], v26 offset:3616
	ds_read_b128 v[154:157], v26 offset:3872
	ds_read_b128 v[158:161], v26 offset:4128
	ds_read_b32 v134, v27 offset:4384
	ds_read_b32 v121, v6 offset:4640
	v_pk_fma_f32 v[136:137], v[138:139], v[164:165], v[136:137]
	v_pk_fma_f32 v[132:133], v[152:153], v[130:131], v[132:133]
	v_add_f32_e32 v136, v136, v137
	v_add_f32_e32 v132, v132, v133
	s_nop 0
	v_add_f32_dpp v136, v136, v136 row_ror:8 row_mask:0xf bank_mask:0xf
	v_add_f32_dpp v132, v132, v132 row_ror:8 row_mask:0xf bank_mask:0xf
	s_nop 0
	v_add_f32_dpp v136, v136, v136 row_ror:4 row_mask:0xf bank_mask:0xf
	v_add_f32_dpp v132, v132, v132 row_ror:4 row_mask:0xf bank_mask:0xf
	s_nop 0
	v_add_f32_dpp v136, v136, v136 row_ror:2 row_mask:0xf bank_mask:0xf
	v_add_f32_dpp v132, v132, v132 row_ror:2 row_mask:0xf bank_mask:0xf
	s_nop 0
	v_add_f32_dpp v136, v136, v136 row_ror:1 row_mask:0xf bank_mask:0xf
	v_add_f32_dpp v132, v132, v132 row_ror:1 row_mask:0xf bank_mask:0xf
	s_add_i32 s30, s30, 1
	v_pk_fma_f32 v[28:29], v[142:143], v[136:137], v[28:29] op_sel_hi:[1,0,1]
	v_pk_fma_f32 v[162:163], v[144:145], v[136:137], v[130:131] op_sel_hi:[1,0,1]
	s_waitcnt lgkmcnt(6)
	v_pk_mul_f32 v[0:1], v[0:1], v[28:29]
	v_fmac_f32_e32 v132, v166, v136
	v_pk_mul_f32 v[2:3], v[2:3], v[162:163]
	s_waitcnt lgkmcnt(1)
	v_pk_fma_f32 v[0:1], v[154:155], v[134:135], v[0:1] op_sel_hi:[1,0,1]
	ds_write_b32 v109, v132 offset:49728
	v_pk_mul_f32 v[122:123], v[122:123], v[28:29]
	v_pk_fma_f32 v[2:3], v[156:157], v[134:135], v[2:3] op_sel_hi:[1,0,1]
	v_pk_mul_f32 v[28:29], v[158:159], v[0:1]
	ds_read_b128 v[130:133], v26 offset:4656
	ds_read_b128 v[136:139], v26 offset:4912
	ds_read_b128 v[142:145], v26 offset:5168
	ds_read_b128 v[146:149], v26 offset:5424
	ds_read_b128 v[150:153], v26 offset:5680
	ds_read_b32 v164, v27 offset:5936
	ds_read_b32 v141, v6 offset:6192
	v_pk_fma_f32 v[122:123], v[124:125], v[162:163], v[122:123]
	v_pk_fma_f32 v[28:29], v[160:161], v[2:3], v[28:29]
	v_add_f32_e32 v122, v122, v123
	v_add_f32_e32 v123, v28, v29
	s_nop 0
	v_add_f32_dpp v122, v122, v122 row_ror:8 row_mask:0xf bank_mask:0xf
	v_add_f32_dpp v123, v123, v123 row_ror:8 row_mask:0xf bank_mask:0xf
	s_nop 0
	v_add_f32_dpp v122, v122, v122 row_ror:4 row_mask:0xf bank_mask:0xf
	v_add_f32_dpp v123, v123, v123 row_ror:4 row_mask:0xf bank_mask:0xf
	s_nop 0
	v_add_f32_dpp v122, v122, v122 row_ror:2 row_mask:0xf bank_mask:0xf
	v_add_f32_dpp v123, v123, v123 row_ror:2 row_mask:0xf bank_mask:0xf
	s_nop 0
	v_add_f32_dpp v122, v122, v122 row_ror:1 row_mask:0xf bank_mask:0xf
	v_add_f32_dpp v123, v123, v123 row_ror:1 row_mask:0xf bank_mask:0xf
	s_bitcmp1_b32 s30, 0
	v_pk_fma_f32 v[28:29], v[126:127], v[122:123], v[0:1] op_sel_hi:[1,0,1]
	v_pk_fma_f32 v[162:163], v[128:129], v[122:123], v[2:3] op_sel_hi:[1,0,1]
	s_waitcnt lgkmcnt(5)
	v_pk_mul_f32 v[136:137], v[136:137], v[28:29]
	v_pk_mul_f32 v[28:29], v[130:131], v[28:29]
	v_fmac_f32_e32 v123, v121, v122
	v_pk_mul_f32 v[130:131], v[132:133], v[162:163]
	s_waitcnt lgkmcnt(1)
	v_pk_fma_f32 v[28:29], v[146:147], v[164:165], v[28:29] op_sel_hi:[1,0,1]
	ds_write_b32 v109, v123 offset:49792
	v_pk_fma_f32 v[130:131], v[148:149], v[164:165], v[130:131] op_sel_hi:[1,0,1]
	v_pk_mul_f32 v[132:133], v[150:151], v[28:29]
	ds_read_b128 v[0:3], v26 offset:6208
	ds_read_b128 v[122:125], v26 offset:6464
	ds_read_b128 v[126:129], v26 offset:6720
	ds_read_b128 v[154:157], v26 offset:6976
	ds_read_b128 v[158:161], v26 offset:7232
	ds_read_b32 v134, v27 offset:7488
	ds_read_b32 v121, v6 offset:7744
	v_pk_fma_f32 v[136:137], v[138:139], v[162:163], v[136:137]
	v_pk_fma_f32 v[132:133], v[152:153], v[130:131], v[132:133]
	v_add_f32_e32 v136, v136, v137
	v_add_f32_e32 v132, v132, v133
	s_nop 0
	v_add_f32_dpp v136, v136, v136 row_ror:8 row_mask:0xf bank_mask:0xf
	v_add_f32_dpp v132, v132, v132 row_ror:8 row_mask:0xf bank_mask:0xf
	s_nop 0
	v_add_f32_dpp v136, v136, v136 row_ror:4 row_mask:0xf bank_mask:0xf
	v_add_f32_dpp v132, v132, v132 row_ror:4 row_mask:0xf bank_mask:0xf
	s_nop 0
	v_add_f32_dpp v136, v136, v136 row_ror:2 row_mask:0xf bank_mask:0xf
	v_add_f32_dpp v132, v132, v132 row_ror:2 row_mask:0xf bank_mask:0xf
	s_nop 0
	v_add_f32_dpp v136, v136, v136 row_ror:1 row_mask:0xf bank_mask:0xf
	v_add_f32_dpp v132, v132, v132 row_ror:1 row_mask:0xf bank_mask:0xf
	s_cselect_b32 s23, 0x6100, 0
	v_pk_fma_f32 v[28:29], v[142:143], v[136:137], v[28:29] op_sel_hi:[1,0,1]
	v_pk_fma_f32 v[162:163], v[144:145], v[136:137], v[130:131] op_sel_hi:[1,0,1]
	s_waitcnt lgkmcnt(6)
	v_pk_mul_f32 v[0:1], v[0:1], v[28:29]
	v_fmac_f32_e32 v132, v141, v136
	v_pk_mul_f32 v[2:3], v[2:3], v[162:163]
	s_waitcnt lgkmcnt(1)
	v_pk_fma_f32 v[0:1], v[154:155], v[134:135], v[0:1] op_sel_hi:[1,0,1]
	ds_write_b32 v109, v132 offset:49856
	v_pk_mul_f32 v[122:123], v[122:123], v[28:29]
	v_pk_fma_f32 v[2:3], v[156:157], v[134:135], v[2:3] op_sel_hi:[1,0,1]
	v_pk_mul_f32 v[28:29], v[158:159], v[0:1]
	ds_read_b128 v[130:133], v26 offset:7760
	ds_read_b128 v[136:139], v26 offset:8016
	ds_read_b128 v[142:145], v26 offset:8272
	ds_read_b128 v[146:149], v26 offset:8528
	ds_read_b128 v[150:153], v26 offset:8784
	ds_read_b32 v164, v27 offset:9040
	ds_read_b32 v141, v6 offset:9296
	v_pk_fma_f32 v[122:123], v[124:125], v[162:163], v[122:123]
	v_pk_fma_f32 v[28:29], v[160:161], v[2:3], v[28:29]
	v_add_f32_e32 v122, v122, v123
	v_add_f32_e32 v123, v28, v29
	s_nop 0
	v_add_f32_dpp v122, v122, v122 row_ror:8 row_mask:0xf bank_mask:0xf
	v_add_f32_dpp v123, v123, v123 row_ror:8 row_mask:0xf bank_mask:0xf
	s_nop 0
	v_add_f32_dpp v122, v122, v122 row_ror:4 row_mask:0xf bank_mask:0xf
	v_add_f32_dpp v123, v123, v123 row_ror:4 row_mask:0xf bank_mask:0xf
	s_nop 0
	v_add_f32_dpp v122, v122, v122 row_ror:2 row_mask:0xf bank_mask:0xf
	v_add_f32_dpp v123, v123, v123 row_ror:2 row_mask:0xf bank_mask:0xf
	s_nop 0
	v_add_f32_dpp v122, v122, v122 row_ror:1 row_mask:0xf bank_mask:0xf
	v_add_f32_dpp v123, v123, v123 row_ror:1 row_mask:0xf bank_mask:0xf
	s_waitcnt vmcnt(10)
	v_mov_b32_e32 v251, v119
	v_lshlrev_b32_e32 v119, 16, v119
	v_pk_fma_f32 v[28:29], v[126:127], v[122:123], v[0:1] op_sel_hi:[1,0,1]
	v_pk_fma_f32 v[162:163], v[128:129], v[122:123], v[2:3] op_sel_hi:[1,0,1]
	s_waitcnt lgkmcnt(5)
	v_pk_mul_f32 v[136:137], v[136:137], v[28:29]
	v_pk_mul_f32 v[28:29], v[130:131], v[28:29]
	v_fmac_f32_e32 v123, v121, v122
	v_pk_mul_f32 v[130:131], v[132:133], v[162:163]
	s_waitcnt lgkmcnt(1)
	v_pk_fma_f32 v[28:29], v[146:147], v[164:165], v[28:29] op_sel_hi:[1,0,1]
	ds_write_b32 v109, v123 offset:49920
	v_pk_fma_f32 v[130:131], v[148:149], v[164:165], v[130:131] op_sel_hi:[1,0,1]
	v_pk_mul_f32 v[132:133], v[150:151], v[28:29]
	ds_read_b128 v[0:3], v26 offset:9312
	ds_read_b128 v[122:125], v26 offset:9568
	ds_read_b128 v[126:129], v26 offset:9824
	ds_read_b128 v[154:157], v26 offset:10080
	ds_read_b128 v[158:161], v26 offset:10336
	ds_read_b32 v134, v27 offset:10592
	ds_read_b32 v121, v6 offset:10848
	v_pk_fma_f32 v[136:137], v[138:139], v[162:163], v[136:137]
	v_pk_fma_f32 v[132:133], v[152:153], v[130:131], v[132:133]
	v_add_f32_e32 v136, v136, v137
	v_add_f32_e32 v132, v132, v133
	s_nop 0
	v_add_f32_dpp v136, v136, v136 row_ror:8 row_mask:0xf bank_mask:0xf
	v_add_f32_dpp v132, v132, v132 row_ror:8 row_mask:0xf bank_mask:0xf
	s_nop 0
	v_add_f32_dpp v136, v136, v136 row_ror:4 row_mask:0xf bank_mask:0xf
	v_add_f32_dpp v132, v132, v132 row_ror:4 row_mask:0xf bank_mask:0xf
	s_nop 0
	v_add_f32_dpp v136, v136, v136 row_ror:2 row_mask:0xf bank_mask:0xf
	v_add_f32_dpp v132, v132, v132 row_ror:2 row_mask:0xf bank_mask:0xf
	s_nop 0
	v_add_f32_dpp v136, v136, v136 row_ror:1 row_mask:0xf bank_mask:0xf
	v_add_f32_dpp v132, v132, v132 row_ror:1 row_mask:0xf bank_mask:0xf
	s_waitcnt vmcnt(8)
	v_lshlrev_b32_e32 v118, 16, v118
	v_pk_fma_f32 v[28:29], v[142:143], v[136:137], v[28:29] op_sel_hi:[1,0,1]
	v_pk_fma_f32 v[162:163], v[144:145], v[136:137], v[130:131] op_sel_hi:[1,0,1]
	s_waitcnt lgkmcnt(6)
	v_pk_mul_f32 v[0:1], v[0:1], v[28:29]
	v_fmac_f32_e32 v132, v141, v136
	v_pk_mul_f32 v[2:3], v[2:3], v[162:163]
	s_waitcnt lgkmcnt(1)
	v_pk_fma_f32 v[0:1], v[154:155], v[134:135], v[0:1] op_sel_hi:[1,0,1]
	ds_write_b32 v109, v132 offset:49984
	v_pk_mul_f32 v[122:123], v[122:123], v[28:29]
	v_pk_fma_f32 v[2:3], v[156:157], v[134:135], v[2:3] op_sel_hi:[1,0,1]
	v_pk_mul_f32 v[28:29], v[158:159], v[0:1]
	ds_read_b128 v[130:133], v26 offset:10864
	ds_read_b128 v[136:139], v26 offset:11120
	ds_read_b128 v[142:145], v26 offset:11376
	ds_read_b128 v[146:149], v26 offset:11632
	ds_read_b128 v[150:153], v26 offset:11888
	ds_read_b32 v164, v27 offset:12144
	ds_read_b32 v141, v6 offset:12400
	v_pk_fma_f32 v[122:123], v[124:125], v[162:163], v[122:123]
	v_pk_fma_f32 v[28:29], v[160:161], v[2:3], v[28:29]
	v_add_f32_e32 v122, v122, v123
	v_add_f32_e32 v123, v28, v29
	s_nop 0
	v_add_f32_dpp v122, v122, v122 row_ror:8 row_mask:0xf bank_mask:0xf
	v_add_f32_dpp v123, v123, v123 row_ror:8 row_mask:0xf bank_mask:0xf
	s_nop 0
	v_add_f32_dpp v122, v122, v122 row_ror:4 row_mask:0xf bank_mask:0xf
	v_add_f32_dpp v123, v123, v123 row_ror:4 row_mask:0xf bank_mask:0xf
	s_nop 0
	v_add_f32_dpp v122, v122, v122 row_ror:2 row_mask:0xf bank_mask:0xf
	v_add_f32_dpp v123, v123, v123 row_ror:2 row_mask:0xf bank_mask:0xf
	s_nop 0
	v_add_f32_dpp v122, v122, v122 row_ror:1 row_mask:0xf bank_mask:0xf
	v_add_f32_dpp v123, v123, v123 row_ror:1 row_mask:0xf bank_mask:0xf
	v_cndmask_b32_e64 v118, 0, v118, s[20:21]
	v_pk_fma_f32 v[28:29], v[126:127], v[122:123], v[0:1] op_sel_hi:[1,0,1]
	v_pk_fma_f32 v[162:163], v[128:129], v[122:123], v[2:3] op_sel_hi:[1,0,1]
	s_waitcnt lgkmcnt(5)
	v_pk_mul_f32 v[136:137], v[136:137], v[28:29]
	v_pk_mul_f32 v[28:29], v[130:131], v[28:29]
	v_fmac_f32_e32 v123, v121, v122
	v_pk_mul_f32 v[130:131], v[132:133], v[162:163]
	s_waitcnt lgkmcnt(1)
	v_pk_fma_f32 v[28:29], v[146:147], v[164:165], v[28:29] op_sel_hi:[1,0,1]
	ds_write_b32 v109, v123 offset:50048
	v_pk_fma_f32 v[130:131], v[148:149], v[164:165], v[130:131] op_sel_hi:[1,0,1]
	v_pk_mul_f32 v[132:133], v[150:151], v[28:29]
	ds_read_b128 v[0:3], v26 offset:12416
	ds_read_b128 v[122:125], v26 offset:12672
	ds_read_b128 v[126:129], v26 offset:12928
	ds_read_b128 v[154:157], v26 offset:13184
	ds_read_b128 v[158:161], v26 offset:13440
	ds_read_b32 v134, v27 offset:13696
	ds_read_b32 v121, v6 offset:13952
	v_pk_fma_f32 v[136:137], v[138:139], v[162:163], v[136:137]
	v_pk_fma_f32 v[132:133], v[152:153], v[130:131], v[132:133]
	v_add_f32_e32 v136, v136, v137
	v_add_f32_e32 v132, v132, v133
	s_nop 0
	v_add_f32_dpp v136, v136, v136 row_ror:8 row_mask:0xf bank_mask:0xf
	v_add_f32_dpp v132, v132, v132 row_ror:8 row_mask:0xf bank_mask:0xf
	s_nop 0
	v_add_f32_dpp v136, v136, v136 row_ror:4 row_mask:0xf bank_mask:0xf
	v_add_f32_dpp v132, v132, v132 row_ror:4 row_mask:0xf bank_mask:0xf
	s_nop 0
	v_add_f32_dpp v136, v136, v136 row_ror:2 row_mask:0xf bank_mask:0xf
	v_add_f32_dpp v132, v132, v132 row_ror:2 row_mask:0xf bank_mask:0xf
	s_nop 0
	v_add_f32_dpp v136, v136, v136 row_ror:1 row_mask:0xf bank_mask:0xf
	v_add_f32_dpp v132, v132, v132 row_ror:1 row_mask:0xf bank_mask:0xf
	v_sub_f32_e32 v118, v118, v119
	v_pk_fma_f32 v[28:29], v[142:143], v[136:137], v[28:29] op_sel_hi:[1,0,1]
	v_pk_fma_f32 v[162:163], v[144:145], v[136:137], v[130:131] op_sel_hi:[1,0,1]
	s_waitcnt lgkmcnt(6)
	v_pk_mul_f32 v[0:1], v[0:1], v[28:29]
	v_fmac_f32_e32 v132, v141, v136
	v_pk_mul_f32 v[2:3], v[2:3], v[162:163]
	s_waitcnt lgkmcnt(1)
	v_pk_fma_f32 v[0:1], v[154:155], v[134:135], v[0:1] op_sel_hi:[1,0,1]
	ds_write_b32 v109, v132 offset:50112
	v_pk_mul_f32 v[122:123], v[122:123], v[28:29]
	v_pk_fma_f32 v[2:3], v[156:157], v[134:135], v[2:3] op_sel_hi:[1,0,1]
	v_pk_mul_f32 v[28:29], v[158:159], v[0:1]
	ds_read_b128 v[130:133], v26 offset:13968
	ds_read_b128 v[136:139], v26 offset:14224
	ds_read_b128 v[142:145], v26 offset:14480
	ds_read_b128 v[146:149], v26 offset:14736
	ds_read_b128 v[150:153], v26 offset:14992
	ds_read_b32 v164, v27 offset:15248
	ds_read_b32 v141, v6 offset:15504
	v_pk_fma_f32 v[122:123], v[124:125], v[162:163], v[122:123]
	v_pk_fma_f32 v[28:29], v[160:161], v[2:3], v[28:29]
	v_add_f32_e32 v122, v122, v123
	v_add_f32_e32 v123, v28, v29
	s_nop 0
	v_add_f32_dpp v122, v122, v122 row_ror:8 row_mask:0xf bank_mask:0xf
	v_add_f32_dpp v123, v123, v123 row_ror:8 row_mask:0xf bank_mask:0xf
	s_nop 0
	v_add_f32_dpp v122, v122, v122 row_ror:4 row_mask:0xf bank_mask:0xf
	v_add_f32_dpp v123, v123, v123 row_ror:4 row_mask:0xf bank_mask:0xf
	s_nop 0
	v_add_f32_dpp v122, v122, v122 row_ror:2 row_mask:0xf bank_mask:0xf
	v_add_f32_dpp v123, v123, v123 row_ror:2 row_mask:0xf bank_mask:0xf
	s_nop 0
	v_add_f32_dpp v122, v122, v122 row_ror:1 row_mask:0xf bank_mask:0xf
	v_add_f32_dpp v123, v123, v123 row_ror:1 row_mask:0xf bank_mask:0xf
	s_waitcnt vmcnt(7)
	v_mov_b32_e32 v252, v116
	v_lshlrev_b32_e32 v116, 16, v116
	v_pk_fma_f32 v[28:29], v[126:127], v[122:123], v[0:1] op_sel_hi:[1,0,1]
	v_pk_fma_f32 v[162:163], v[128:129], v[122:123], v[2:3] op_sel_hi:[1,0,1]
	s_waitcnt lgkmcnt(5)
	v_pk_mul_f32 v[136:137], v[136:137], v[28:29]
	v_pk_mul_f32 v[28:29], v[130:131], v[28:29]
	v_fmac_f32_e32 v123, v121, v122
	v_pk_mul_f32 v[130:131], v[132:133], v[162:163]
	s_waitcnt lgkmcnt(1)
	v_pk_fma_f32 v[28:29], v[146:147], v[164:165], v[28:29] op_sel_hi:[1,0,1]
	ds_write_b32 v109, v123 offset:50176
	v_pk_fma_f32 v[130:131], v[148:149], v[164:165], v[130:131] op_sel_hi:[1,0,1]
	v_pk_mul_f32 v[132:133], v[150:151], v[28:29]
	ds_read_b128 v[0:3], v26 offset:15520
	ds_read_b128 v[122:125], v26 offset:15776
	ds_read_b128 v[126:129], v26 offset:16032
	ds_read_b128 v[154:157], v26 offset:16288
	ds_read_b128 v[158:161], v26 offset:16544
	ds_read_b32 v134, v27 offset:16800
	ds_read_b32 v121, v6 offset:17056
	v_pk_fma_f32 v[136:137], v[138:139], v[162:163], v[136:137]
	v_pk_fma_f32 v[132:133], v[152:153], v[130:131], v[132:133]
	v_add_f32_e32 v136, v136, v137
	v_add_f32_e32 v132, v132, v133
	s_nop 0
	v_add_f32_dpp v136, v136, v136 row_ror:8 row_mask:0xf bank_mask:0xf
	v_add_f32_dpp v132, v132, v132 row_ror:8 row_mask:0xf bank_mask:0xf
	s_nop 0
	v_add_f32_dpp v136, v136, v136 row_ror:4 row_mask:0xf bank_mask:0xf
	v_add_f32_dpp v132, v132, v132 row_ror:4 row_mask:0xf bank_mask:0xf
	s_nop 0
	v_add_f32_dpp v136, v136, v136 row_ror:2 row_mask:0xf bank_mask:0xf
	v_add_f32_dpp v132, v132, v132 row_ror:2 row_mask:0xf bank_mask:0xf
	s_nop 0
	v_add_f32_dpp v136, v136, v136 row_ror:1 row_mask:0xf bank_mask:0xf
	v_add_f32_dpp v132, v132, v132 row_ror:1 row_mask:0xf bank_mask:0xf
	s_waitcnt vmcnt(5)
	v_lshlrev_b32_e32 v115, 16, v115
	v_pk_fma_f32 v[28:29], v[142:143], v[136:137], v[28:29] op_sel_hi:[1,0,1]
	v_pk_fma_f32 v[162:163], v[144:145], v[136:137], v[130:131] op_sel_hi:[1,0,1]
	s_waitcnt lgkmcnt(6)
	v_pk_mul_f32 v[0:1], v[0:1], v[28:29]
	v_fmac_f32_e32 v132, v141, v136
	v_pk_mul_f32 v[2:3], v[2:3], v[162:163]
	s_waitcnt lgkmcnt(1)
	v_pk_fma_f32 v[0:1], v[154:155], v[134:135], v[0:1] op_sel_hi:[1,0,1]
	ds_write_b32 v109, v132 offset:50240
	v_pk_mul_f32 v[122:123], v[122:123], v[28:29]
	v_pk_fma_f32 v[2:3], v[156:157], v[134:135], v[2:3] op_sel_hi:[1,0,1]
	v_pk_mul_f32 v[28:29], v[158:159], v[0:1]
	ds_read_b128 v[130:133], v26 offset:17072
	ds_read_b128 v[136:139], v26 offset:17328
	ds_read_b128 v[142:145], v26 offset:17584
	ds_read_b128 v[146:149], v26 offset:17840
	ds_read_b128 v[150:153], v26 offset:18096
	ds_read_b32 v164, v27 offset:18352
	ds_read_b32 v141, v6 offset:18608
	v_pk_fma_f32 v[122:123], v[124:125], v[162:163], v[122:123]
	v_pk_fma_f32 v[28:29], v[160:161], v[2:3], v[28:29]
	v_add_f32_e32 v122, v122, v123
	v_add_f32_e32 v123, v28, v29
	s_nop 0
	v_add_f32_dpp v122, v122, v122 row_ror:8 row_mask:0xf bank_mask:0xf
	v_add_f32_dpp v123, v123, v123 row_ror:8 row_mask:0xf bank_mask:0xf
	s_nop 0
	v_add_f32_dpp v122, v122, v122 row_ror:4 row_mask:0xf bank_mask:0xf
	v_add_f32_dpp v123, v123, v123 row_ror:4 row_mask:0xf bank_mask:0xf
	s_nop 0
	v_add_f32_dpp v122, v122, v122 row_ror:2 row_mask:0xf bank_mask:0xf
	v_add_f32_dpp v123, v123, v123 row_ror:2 row_mask:0xf bank_mask:0xf
	s_nop 0
	v_add_f32_dpp v122, v122, v122 row_ror:1 row_mask:0xf bank_mask:0xf
	v_add_f32_dpp v123, v123, v123 row_ror:1 row_mask:0xf bank_mask:0xf
	v_cndmask_b32_e64 v115, 0, v115, s[20:21]
	v_pk_fma_f32 v[28:29], v[126:127], v[122:123], v[0:1] op_sel_hi:[1,0,1]
	v_pk_fma_f32 v[162:163], v[128:129], v[122:123], v[2:3] op_sel_hi:[1,0,1]
	s_waitcnt lgkmcnt(5)
	v_pk_mul_f32 v[136:137], v[136:137], v[28:29]
	v_pk_mul_f32 v[28:29], v[130:131], v[28:29]
	v_fmac_f32_e32 v123, v121, v122
	v_pk_mul_f32 v[130:131], v[132:133], v[162:163]
	s_waitcnt lgkmcnt(1)
	v_pk_fma_f32 v[28:29], v[146:147], v[164:165], v[28:29] op_sel_hi:[1,0,1]
	ds_write_b32 v109, v123 offset:50304
	v_pk_fma_f32 v[130:131], v[148:149], v[164:165], v[130:131] op_sel_hi:[1,0,1]
	v_pk_mul_f32 v[132:133], v[150:151], v[28:29]
	ds_read_b128 v[0:3], v26 offset:18624
	ds_read_b128 v[122:125], v26 offset:18880
	ds_read_b128 v[126:129], v26 offset:19136
	ds_read_b128 v[154:157], v26 offset:19392
	ds_read_b128 v[158:161], v26 offset:19648
	ds_read_b32 v134, v27 offset:19904
	ds_read_b32 v121, v6 offset:20160
	v_pk_fma_f32 v[136:137], v[138:139], v[162:163], v[136:137]
	v_pk_fma_f32 v[132:133], v[152:153], v[130:131], v[132:133]
	v_add_f32_e32 v136, v136, v137
	v_add_f32_e32 v132, v132, v133
	s_nop 0
	v_add_f32_dpp v136, v136, v136 row_ror:8 row_mask:0xf bank_mask:0xf
	v_add_f32_dpp v132, v132, v132 row_ror:8 row_mask:0xf bank_mask:0xf
	s_nop 0
	v_add_f32_dpp v136, v136, v136 row_ror:4 row_mask:0xf bank_mask:0xf
	v_add_f32_dpp v132, v132, v132 row_ror:4 row_mask:0xf bank_mask:0xf
	s_nop 0
	v_add_f32_dpp v136, v136, v136 row_ror:2 row_mask:0xf bank_mask:0xf
	v_add_f32_dpp v132, v132, v132 row_ror:2 row_mask:0xf bank_mask:0xf
	s_nop 0
	v_add_f32_dpp v136, v136, v136 row_ror:1 row_mask:0xf bank_mask:0xf
	v_add_f32_dpp v132, v132, v132 row_ror:1 row_mask:0xf bank_mask:0xf
	v_sub_f32_e32 v115, v115, v116
	v_pk_fma_f32 v[28:29], v[142:143], v[136:137], v[28:29] op_sel_hi:[1,0,1]
	v_pk_fma_f32 v[162:163], v[144:145], v[136:137], v[130:131] op_sel_hi:[1,0,1]
	s_waitcnt lgkmcnt(6)
	v_pk_mul_f32 v[0:1], v[0:1], v[28:29]
	v_fmac_f32_e32 v132, v141, v136
	v_pk_mul_f32 v[2:3], v[2:3], v[162:163]
	s_waitcnt lgkmcnt(1)
	v_pk_fma_f32 v[0:1], v[154:155], v[134:135], v[0:1] op_sel_hi:[1,0,1]
	ds_write_b32 v109, v132 offset:50368
	v_pk_mul_f32 v[122:123], v[122:123], v[28:29]
	v_pk_fma_f32 v[2:3], v[156:157], v[134:135], v[2:3] op_sel_hi:[1,0,1]
	v_pk_mul_f32 v[28:29], v[158:159], v[0:1]
	ds_read_b128 v[130:133], v26 offset:20176
	ds_read_b128 v[136:139], v26 offset:20432
	ds_read_b128 v[142:145], v26 offset:20688
	ds_read_b128 v[146:149], v26 offset:20944
	ds_read_b128 v[150:153], v26 offset:21200
	ds_read_b32 v166, v27 offset:21456
	ds_read_b32 v141, v6 offset:21712
	v_pk_fma_f32 v[122:123], v[124:125], v[162:163], v[122:123]
	v_pk_fma_f32 v[28:29], v[160:161], v[2:3], v[28:29]
	v_add_f32_e32 v122, v122, v123
	v_add_f32_e32 v28, v28, v29
	s_nop 0
	v_add_f32_dpp v122, v122, v122 row_ror:8 row_mask:0xf bank_mask:0xf
	v_add_f32_dpp v28, v28, v28 row_ror:8 row_mask:0xf bank_mask:0xf
	s_nop 0
	v_add_f32_dpp v122, v122, v122 row_ror:4 row_mask:0xf bank_mask:0xf
	v_add_f32_dpp v28, v28, v28 row_ror:4 row_mask:0xf bank_mask:0xf
	s_nop 0
	v_add_f32_dpp v122, v122, v122 row_ror:2 row_mask:0xf bank_mask:0xf
	v_add_f32_dpp v28, v28, v28 row_ror:2 row_mask:0xf bank_mask:0xf
	s_nop 0
	v_add_f32_dpp v122, v122, v122 row_ror:1 row_mask:0xf bank_mask:0xf
	v_add_f32_dpp v28, v28, v28 row_ror:1 row_mask:0xf bank_mask:0xf
	s_waitcnt vmcnt(4)
	v_mov_b32_e32 v253, v112
	v_lshlrev_b32_e32 v112, 16, v112
	v_pk_fma_f32 v[0:1], v[126:127], v[122:123], v[0:1] op_sel_hi:[1,0,1]
	v_pk_fma_f32 v[2:3], v[128:129], v[122:123], v[2:3] op_sel_hi:[1,0,1]
	s_waitcnt lgkmcnt(5)
	v_pk_mul_f32 v[136:137], v[136:137], v[0:1]
	v_pk_mul_f32 v[0:1], v[130:131], v[0:1]
	v_pk_fma_f32 v[136:137], v[138:139], v[2:3], v[136:137]
	v_pk_mul_f32 v[2:3], v[132:133], v[2:3]
	s_waitcnt lgkmcnt(1)
	v_pk_fma_f32 v[0:1], v[146:147], v[166:167], v[0:1] op_sel_hi:[1,0,1]
	v_pk_fma_f32 v[2:3], v[148:149], v[166:167], v[2:3] op_sel_hi:[1,0,1]
	v_pk_mul_f32 v[130:131], v[150:151], v[0:1]
	v_fmac_f32_e32 v28, v121, v122
	v_pk_fma_f32 v[130:131], v[152:153], v[2:3], v[130:131]
	ds_write_b32 v109, v28 offset:50432
	v_add_f32_e32 v134, v136, v137
	v_add_f32_e32 v29, v130, v131
	ds_read_b128 v[122:125], v26 offset:21728
	ds_read_b128 v[126:129], v26 offset:21984
	ds_read_b128 v[154:157], v26 offset:22240
	ds_read_b128 v[158:161], v26 offset:22496
	ds_read_b128 v[162:165], v26 offset:22752
	ds_read_b32 v28, v27 offset:23008
	ds_read_b32 v121, v6 offset:23264
	s_nop 0
	v_add_f32_dpp v134, v134, v134 row_ror:8 row_mask:0xf bank_mask:0xf
	v_add_f32_dpp v29, v29, v29 row_ror:8 row_mask:0xf bank_mask:0xf
	s_nop 0
	v_add_f32_dpp v134, v134, v134 row_ror:4 row_mask:0xf bank_mask:0xf
	v_add_f32_dpp v29, v29, v29 row_ror:4 row_mask:0xf bank_mask:0xf
	s_nop 0
	v_add_f32_dpp v134, v134, v134 row_ror:2 row_mask:0xf bank_mask:0xf
	v_add_f32_dpp v29, v29, v29 row_ror:2 row_mask:0xf bank_mask:0xf
	s_nop 0
	v_add_f32_dpp v134, v134, v134 row_ror:1 row_mask:0xf bank_mask:0xf
	v_add_f32_dpp v29, v29, v29 row_ror:1 row_mask:0xf bank_mask:0xf
	s_waitcnt vmcnt(0)
	v_lshlrev_b32_e32 v110, 16, v110
	s_waitcnt lgkmcnt(8)
	v_fmac_f32_e32 v29, v141, v134
	v_pk_fma_f32 v[150:151], v[142:143], v[134:135], v[0:1] op_sel_hi:[1,0,1]
	ds_write_b32 v109, v29 offset:50496
	v_pk_fma_f32 v[152:153], v[144:145], v[134:135], v[2:3] op_sel_hi:[1,0,1]
	ds_read_b128 v[130:133], v26 offset:23280
	ds_read_b128 v[136:139], v26 offset:23536
	ds_read_b128 v[0:3], v26 offset:23792
	ds_read_b128 v[142:145], v26 offset:24048
	ds_read_b128 v[146:149], v26 offset:24304
	ds_read_b32 v134, v27 offset:24560
	ds_read_b32 v141, v6 offset:24816
	s_waitcnt lgkmcnt(13)
	v_pk_mul_f32 v[26:27], v[126:127], v[150:151]
	v_lshlrev_b32_e32 v111, 16, v111
	v_pk_fma_f32 v[26:27], v[128:129], v[152:153], v[26:27]
	v_mul_f32_e32 v110, 0x3fb8aa3b, v110
	v_add_f32_e32 v6, v26, v27
	v_pk_mul_f32 v[26:27], v[122:123], v[150:151]
	v_pk_mul_f32 v[122:123], v[124:125], v[152:153]
	s_waitcnt lgkmcnt(9)
	v_pk_fma_f32 v[26:27], v[158:159], v[28:29], v[26:27] op_sel_hi:[1,0,1]
	v_pk_fma_f32 v[28:29], v[160:161], v[28:29], v[122:123] op_sel_hi:[1,0,1]
	v_pk_mul_f32 v[122:123], v[162:163], v[26:27]
	v_exp_f32_e32 v110, v110
	v_pk_fma_f32 v[122:123], v[164:165], v[28:29], v[122:123]
	s_nop 0
	v_add_f32_e32 v122, v122, v123
	s_nop 0
	v_add_f32_dpp v6, v6, v6 row_ror:8 row_mask:0xf bank_mask:0xf
	v_add_f32_dpp v122, v122, v122 row_ror:8 row_mask:0xf bank_mask:0xf
	s_nop 0
	v_add_f32_dpp v6, v6, v6 row_ror:4 row_mask:0xf bank_mask:0xf
	v_add_f32_dpp v122, v122, v122 row_ror:4 row_mask:0xf bank_mask:0xf
	s_nop 0
	v_add_f32_dpp v6, v6, v6 row_ror:2 row_mask:0xf bank_mask:0xf
	v_add_f32_dpp v122, v122, v122 row_ror:2 row_mask:0xf bank_mask:0xf
	s_nop 0
	v_add_f32_dpp v6, v6, v6 row_ror:1 row_mask:0xf bank_mask:0xf
	v_add_f32_dpp v122, v122, v122 row_ror:1 row_mask:0xf bank_mask:0xf
	v_pk_fma_f32 v[26:27], v[154:155], v[6:7], v[26:27] op_sel_hi:[1,0,1]
	s_waitcnt lgkmcnt(8)
	v_fmac_f32_e32 v122, v121, v6
	v_pk_fma_f32 v[28:29], v[156:157], v[6:7], v[28:29] op_sel_hi:[1,0,1]
	ds_write_b32 v109, v122 offset:50560
	s_waitcnt lgkmcnt(6)
	v_pk_mul_f32 v[122:123], v[136:137], v[26:27]
	v_pk_mul_f32 v[26:27], v[130:131], v[26:27]
	v_pk_fma_f32 v[122:123], v[138:139], v[28:29], v[122:123]
	v_pk_mul_f32 v[28:29], v[132:133], v[28:29]
	s_waitcnt lgkmcnt(2)
; DEV void row16_sum2(float& a, float& b) {
;   asm volatile("s_nop 1\n\tv_add_f32_dpp %0, %0, %0 row_ror:8 row_mask:0xf bank_mask:0xf\n\tv_add_f32_dpp %1, %1, %1 row_ror:8 row_mask:0xf bank_mask:0xf\n\t"
;                "s_nop 1\n\tv_add_f32_dpp %0, %0, %0 row_ror:4 row_mask:0xf bank_mask:0xf\n\tv_add_f32_dpp %1, %1, %1 row_ror:4 row_mask:0xf bank_mask:0xf\n\t"
;                "s_nop 1\n\tv_add_f32_dpp %0, %0, %0 row_ror:2 row_mask:0xf bank_mask:0xf\n\tv_add_f32_dpp %1, %1, %1 row_ror:2 row_mask:0xf bank_mask:0xf\n\t"
;                "s_nop 1\n\tv_add_f32_dpp %0, %0, %0 row_ror:1 row_mask:0xf bank_mask:0xf\n\tv_add_f32_dpp %1, %1, %1 row_ror:1 row_mask:0xf bank_mask:0xf\n\t"
;                "s_nop 0"
;                : "+v"(a), "+v"(b));
	v_pk_fma_f32 v[26:27], v[142:143], v[134:135], v[26:27] op_sel_hi:[1,0,1]
	v_add_f32_e32 v6, v122, v123
	v_pk_fma_f32 v[28:29], v[144:145], v[134:135], v[28:29] op_sel_hi:[1,0,1]
	v_pk_mul_f32 v[122:123], v[146:147], v[26:27]
	s_nop 0
	v_pk_fma_f32 v[122:123], v[148:149], v[28:29], v[122:123]
	s_nop 0
	v_add_f32_e32 v121, v122, v123
	s_nop 0
	v_add_f32_dpp v6, v6, v6 row_ror:8 row_mask:0xf bank_mask:0xf
	v_add_f32_dpp v121, v121, v121 row_ror:8 row_mask:0xf bank_mask:0xf
	s_nop 0
	v_add_f32_dpp v6, v6, v6 row_ror:4 row_mask:0xf bank_mask:0xf
	v_add_f32_dpp v121, v121, v121 row_ror:4 row_mask:0xf bank_mask:0xf
	s_nop 0
	v_add_f32_dpp v6, v6, v6 row_ror:2 row_mask:0xf bank_mask:0xf
	v_add_f32_dpp v121, v121, v121 row_ror:2 row_mask:0xf bank_mask:0xf
	s_nop 0
	v_add_f32_dpp v6, v6, v6 row_ror:1 row_mask:0xf bank_mask:0xf
	v_add_f32_dpp v121, v121, v121 row_ror:1 row_mask:0xf bank_mask:0xf
	s_waitcnt lgkmcnt(1)
	v_fmac_f32_e32 v121, v141, v6
	ds_write_b32 v109, v121 offset:50624
	v_lshlrev_b32_e32 v109, 16, v120
	v_cndmask_b32_e64 v109, 0, v109, s[18:19]
	v_sub_f32_e32 v109, v109, v119
	v_fmac_f32_e32 v119, v32, v109
	v_lshlrev_b32_e32 v109, 16, v117
	v_cndmask_b32_e64 v109, 0, v109, s[18:19]
	v_sub_f32_e32 v109, v109, v116
	v_fmac_f32_e32 v116, v34, v109
	v_lshlrev_b32_e32 v109, 16, v113
	v_cndmask_b32_e64 v109, 0, v109, s[18:19]
	v_lshlrev_b32_e32 v113, 16, v114
	v_sub_f32_e32 v109, v109, v112
	v_cndmask_b32_e64 v113, 0, v113, s[20:21]
	v_sub_f32_e32 v113, v113, v112
	v_fmac_f32_e32 v112, v11, v109
	v_add_f32_e32 v109, -1.0, v111
	v_fmac_f32_e32 v116, v35, v115
	v_fma_f32 v109, v76, v109, 1.0
	v_fmac_f32_e32 v112, v30, v113
	v_mul_f32_e32 v113, v116, v109
	v_add_u32_e32 v109, s23, v43
	v_mul_f32_e64 v115, v75, -v116
	v_lshl_add_u32 v114, v182, 2, v109
	v_mul_f32_e32 v22, v22, v115
	ds_write2st64_b32 v114, v110, v22 offset1:1
	v_mul_f32_e64 v22, -v22, v111
	v_fmac_f32_e32 v119, v33, v118
	ds_write2st64_b32 v114, v22, v113 offset0:2 offset1:3
	ds_write2st64_b32 v114, v119, v112 offset0:4 offset1:5
	s_and_saveexec_b64 s[18:19], s[6:7]
	ds_write_b32 v109, v23 offset:1536
	s_or_b64 exec, exec, s[18:19]
	v_cndmask_b32_e32 v105, v102, v251, vcc
	v_cndmask_b32_e32 v106, v251, v102, vcc
	v_cndmask_b32_e32 v99, v103, v252, vcc
	v_cndmask_b32_e32 v96, v252, v103, vcc
	v_cndmask_b32_e32 v87, v93, v253, vcc
	v_cndmask_b32_e32 v83, v253, v93, vcc
	v_cndmask_b32_e32 v107, v82, v101, vcc
	v_cndmask_b32_e32 v108, v101, v82, vcc
	v_cndmask_b32_e32 v104, v89, v98, vcc
	v_cndmask_b32_e32 v100, v98, v89, vcc
	v_cndmask_b32_e32 v94, v78, v86, vcc
	v_cndmask_b32_e32 v91, v86, v78, vcc
	v_lshlrev_b32_e32 v22, 16, v105
	v_lshlrev_b32_e32 v23, 16, v101
	v_cndmask_b32_e64 v22, 0, v22, s[10:11]
	v_lshlrev_b32_e32 v101, 16, v106
	v_sub_f32_e32 v22, v22, v23
	v_cndmask_b32_e64 v101, 0, v101, s[14:15]
	v_sub_f32_e32 v101, v101, v23
	v_fmac_f32_e32 v23, v32, v22
	v_lshlrev_b32_e32 v22, 16, v99
	v_lshlrev_b32_e32 v98, 16, v98
	v_cndmask_b32_e64 v22, 0, v22, s[10:11]
	v_lshlrev_b32_e32 v96, 16, v96
	v_sub_f32_e32 v22, v22, v98
	v_cndmask_b32_e64 v96, 0, v96, s[14:15]
	v_sub_f32_e32 v96, v96, v98
	v_fmac_f32_e32 v98, v34, v22
	v_lshlrev_b32_e32 v22, 16, v87
	v_lshlrev_b32_e32 v86, 16, v86
	v_cndmask_b32_e64 v22, 0, v22, s[10:11]
	v_lshlrev_b32_e32 v83, 16, v83
	v_sub_f32_e32 v22, v22, v86
	v_cndmask_b32_e64 v83, 0, v83, s[14:15]
	v_sub_f32_e32 v83, v83, v86
	v_fmac_f32_e32 v86, v11, v22
	v_lshlrev_b32_e32 v85, 16, v85
	v_fmac_f32_e32 v86, v30, v83
	v_lshlrev_b32_e32 v83, 16, v97
	v_mul_f32_e32 v85, 0x3fb8aa3b, v85
	v_add_f32_e32 v22, -1.0, v83
	v_exp_f32_e32 v85, v85
	v_fmac_f32_e32 v98, v35, v96
	v_fma_f32 v22, v76, v22, 1.0
	v_mul_f32_e32 v87, v98, v22
	v_add_u32_e32 v22, s23, v45
	v_mul_f32_e64 v97, v75, -v98
	v_lshl_add_u32 v96, v182, 2, v22
	v_mul_f32_e32 v24, v24, v97
	ds_write2st64_b32 v96, v85, v24 offset1:1
	v_mul_f32_e64 v24, -v24, v83
	v_fmac_f32_e32 v23, v33, v101
	ds_write2st64_b32 v96, v24, v87 offset0:2 offset1:3
	ds_write2st64_b32 v96, v23, v86 offset0:4 offset1:5
	s_and_saveexec_b64 s[10:11], s[6:7]
	ds_write_b32 v22, v25 offset:1536
	s_or_b64 exec, exec, s[10:11]
	v_lshlrev_b32_e32 v22, 16, v107
	v_lshlrev_b32_e32 v23, 16, v102
	v_cndmask_b32_e64 v22, 0, v22, s[12:13]
	v_lshlrev_b32_e32 v24, 16, v108
	v_sub_f32_e32 v22, v22, v23
	v_cndmask_b32_e64 v24, 0, v24, s[16:17]
	v_sub_f32_e32 v24, v24, v23
	v_fmac_f32_e32 v23, v32, v22
	v_lshlrev_b32_e32 v22, 16, v104
	v_fmac_f32_e32 v23, v33, v24
	v_lshlrev_b32_e32 v24, 16, v103
	v_cndmask_b32_e64 v22, 0, v22, s[12:13]
	v_lshlrev_b32_e32 v25, 16, v100
	v_sub_f32_e32 v22, v22, v24
	v_cndmask_b32_e64 v25, 0, v25, s[16:17]
	v_sub_f32_e32 v25, v25, v24
	v_fmac_f32_e32 v24, v34, v22
	v_lshlrev_b32_e32 v22, 16, v94
	v_fmac_f32_e32 v24, v35, v25
	v_lshlrev_b32_e32 v25, 16, v93
	v_cndmask_b32_e64 v22, 0, v22, s[12:13]
	v_lshlrev_b32_e32 v83, 16, v91
	v_sub_f32_e32 v22, v22, v25
	v_cndmask_b32_e64 v83, 0, v83, s[16:17]
	v_sub_f32_e32 v83, v83, v25
	v_fmac_f32_e32 v25, v11, v22
	v_lshlrev_b32_e32 v81, 16, v81
	v_fmac_f32_e32 v25, v30, v83
	v_lshlrev_b32_e32 v83, 16, v95
	v_mul_f32_e32 v81, 0x3fb8aa3b, v81
	v_add_f32_e32 v22, -1.0, v83
	v_exp_f32_e32 v81, v81
	v_fma_f32 v22, v76, v22, 1.0
	v_mul_f32_e32 v85, v24, v22
	v_add_u32_e32 v22, s23, v47
	v_mul_f32_e64 v24, v75, -v24
	v_lshl_add_u32 v86, v182, 2, v22
	v_mul_f32_e32 v20, v20, v24
	ds_write2st64_b32 v86, v81, v20 offset1:1
	v_mul_f32_e64 v20, -v20, v83
	ds_write2st64_b32 v86, v20, v85 offset0:2 offset1:3
	ds_write2st64_b32 v86, v23, v25 offset0:4 offset1:5
	s_and_saveexec_b64 s[10:11], s[6:7]
	ds_write_b32 v22, v21 offset:1536
	s_or_b64 exec, exec, s[10:11]
	v_add_u32_e32 v20, s29, v64
	v_add_u32_e32 v21, s28, v68
	v_cndmask_b32_e32 v20, v21, v20, vcc
	v_lshlrev_b32_e32 v22, 16, v92
	v_cmp_lt_i32_e64 s[10:11], 0, v20
	v_lshlrev_b32_e32 v21, 16, v82
	v_lshlrev_b32_e32 v23, 16, v88
	v_cndmask_b32_e64 v22, 0, v22, s[10:11]
	v_cmp_gt_i32_e64 s[12:13], s94, v20
	v_sub_f32_e32 v22, v22, v21
	v_lshlrev_b32_e32 v24, 16, v77
	v_cndmask_b32_e64 v20, 0, v23, s[12:13]
	v_sub_f32_e32 v20, v20, v21
	v_fmac_f32_e32 v21, v32, v22
	v_fmac_f32_e32 v21, v33, v20
	v_lshlrev_b32_e32 v20, 16, v90
	v_lshlrev_b32_e32 v22, 16, v89
	v_cndmask_b32_e64 v20, 0, v20, s[10:11]
	v_lshlrev_b32_e32 v23, 16, v84
	v_sub_f32_e32 v20, v20, v22
	v_cndmask_b32_e64 v23, 0, v23, s[12:13]
	v_sub_f32_e32 v23, v23, v22
	v_fmac_f32_e32 v22, v34, v20
	v_lshlrev_b32_e32 v20, 16, v79
	v_fmac_f32_e32 v22, v35, v23
	v_lshlrev_b32_e32 v23, 16, v78
	v_cndmask_b32_e64 v20, 0, v20, s[10:11]
	v_sub_f32_e32 v20, v20, v23
	v_cndmask_b32_e64 v24, 0, v24, s[12:13]
	v_sub_f32_e32 v24, v24, v23
	v_fmac_f32_e32 v23, v11, v20
	v_lshlrev_b32_e32 v9, 16, v9
	v_fmac_f32_e32 v23, v30, v24
	v_lshlrev_b32_e32 v24, 16, v80
	v_mul_f32_e32 v9, 0x3fb8aa3b, v9
	v_add_f32_e32 v20, -1.0, v24
	v_exp_f32_e32 v9, v9
	v_fma_f32 v20, v76, v20, 1.0
	v_mul_f32_e32 v25, v22, v20
	v_add_u32_e32 v20, s23, v49
	v_mul_f32_e64 v22, v75, -v22
	v_lshl_add_u32 v77, v182, 2, v20
	v_mul_f32_e32 v18, v18, v22
	ds_write2st64_b32 v77, v9, v18 offset1:1
	v_mul_f32_e64 v9, -v18, v24
	ds_write2st64_b32 v77, v9, v25 offset0:2 offset1:3
	ds_write2st64_b32 v77, v21, v23 offset0:4 offset1:5
	s_and_saveexec_b64 s[10:11], s[6:7]
	s_cbranch_execz .LBB0_1982
	ds_write_b32 v20, v19 offset:1536
	s_branch .LBB0_1982

; template <bool RES, class Epi>
; DEV void gemm_tile_x(const bf16_t* A0, int lda0, const bf16_t* A1, int lda1, int ksplit,
;                      const bf16_t* Bt, int ldb, int K, char* smem, const float* resb, Epi epi) {
;   bf16_t* sbase = (bf16_t*)smem;
;   const int tid = threadIdx.x, lane = tid & 63, wv = tid >> 6;
;   const int wm = wv >> 1, wn = wv & 1;
;   f32x16 acc[4][2];
; #pragma unroll
;   for (int i = 0; i < 4; ++i)
; #pragma unroll
;     for (int j = 0; j < 2; ++j)
; #pragma unroll
;       for (int r = 0; r < 16; ++r) acc[i][j][r] = 0.f;
;   GRegs g, g1;
;   const int nk = K >> 5;
;   const int woff = (tid >> 2) * 32 + (((tid & 3) ^ ((tid >> 4) & 3)) << 3);
;   const int swz = (lane >> 2) & 3, hh = lane >> 5;
;   const int raoff = (wm * 128 + (lane & 31)) * 32;
;   const int rboff = GSA + (wn * 64 + (lane & 31)) * 32;
;   const int ko0 = ((0 + hh) ^ swz) << 3, ko1 = ((2 + hh) ^ swz) << 3;
;   __syncthreads();
;   gemm_gload(g, A0, lda0, A1, lda1, ksplit, Bt, ldb, 0, tid);
;   if (nk > 1) gemm_gload(g1, A0, lda0, A1, lda1, ksplit, Bt, ldb, 32, tid);
;   gemm_lds_write(g, sbase + woff, sbase + GSA + woff);
;   if (nk > 2) gemm_gload(g, A0, lda0, A1, lda1, ksplit, Bt, ldb, 64, tid);
;   __syncthreads();
; DEV bool tile_map(int it, int nct, int& rt, int& ct) {
;   const int bpx = gridDim.x >> 3, xcd = blockIdx.x & 7, j = blockIdx.x >> 3;
;   const int q = j + it * bpx;
;   if (q >= 24 * nct) return false;
;   const int band = q / (4 * nct), qq = q - band * 4 * nct;
;   rt = xcd * 24 + band * 4 + (qq & 3);
;   ct = qq >> 2;
.LBB0_3201:
	s_mul_hi_u32 s52, s48, 0xba2e8ba3
	s_lshr_b32 s52, s52, 7
	s_lshl_b32 s53, s52, 2
	s_mulk_i32 s52, 0xff50
	s_add_i32 s52, s52, s48
	s_add_i32 s53, s53, s74
	s_and_b32 s48, s48, 3
	s_or_b32 s48, s53, s48
	s_lshl_b64 s[54:55], s[48:49], 19
	s_ashr_i32 s52, s52, 2
	v_lshl_add_u64 v[52:53], v[186:187], 0, s[54:55]
	s_ashr_i32 s53, s52, 31
	v_add_co_u32_e32 v56, vcc, s77, v52
	s_lshl_b64 s[56:57], s[52:53], 18
	s_nop 0
	v_addc_co_u32_e32 v57, vcc, 0, v53, vcc
	s_mov_b32 s53, 0x40000
	v_add_co_u32_e32 v58, vcc, s53, v52
	s_mov_b32 s53, 0x60000
	s_nop 0
	v_addc_co_u32_e32 v59, vcc, 0, v53, vcc
	v_add_co_u32_e32 v60, vcc, s53, v52
	v_lshl_add_u64 v[54:55], v[188:189], 0, s[56:57]
	s_nop 0
	v_addc_co_u32_e32 v61, vcc, 0, v53, vcc
	v_add_co_u32_e32 v62, vcc, s77, v54
	s_waitcnt vmcnt(63) expcnt(7) lgkmcnt(15)
	s_nop 0
	v_addc_co_u32_e32 v63, vcc, 0, v55, vcc
	s_barrier
	global_load_dwordx4 v[28:31], v[52:53], off
	global_load_dwordx4 v[32:35], v[56:57], off
	global_load_dwordx4 v[36:39], v[58:59], off
	global_load_dwordx4 v[40:43], v[60:61], off
	global_load_dwordx4 v[44:47], v[54:55], off
	global_load_dwordx4 v[48:51], v[62:63], off
	global_load_dwordx4 v[128:131], v[52:53], off offset:64
	global_load_dwordx4 v[136:139], v[56:57], off offset:64
	global_load_dwordx4 v[148:151], v[60:61], off offset:64
	global_load_dwordx4 v[132:135], v[52:53], off offset:128
	global_load_dwordx4 v[140:143], v[56:57], off offset:128
	global_load_dwordx4 v[144:147], v[58:59], off offset:64
	global_load_dwordx4 v[152:155], v[58:59], off offset:128
	global_load_dwordx4 v[160:163], v[54:55], off offset:64
	global_load_dwordx4 v[164:167], v[54:55], off offset:128
	global_load_dwordx4 v[156:159], v[60:61], off offset:128
	global_load_dwordx4 v[168:171], v[62:63], off offset:64
	global_load_dwordx4 v[172:175], v[62:63], off offset:128
	v_mov_b32_e32 v0, 0
	s_mov_b32 s53, -2
	v_mov_b32_e32 v1, v0
	v_mov_b32_e32 v2, v0
	v_mov_b32_e32 v3, v0
	v_mov_b32_e32 v4, v0
	v_mov_b32_e32 v5, v0
	v_mov_b32_e32 v6, v0
	v_mov_b32_e32 v7, v0
	v_mov_b32_e32 v8, v0
	v_mov_b32_e32 v9, v0
	v_mov_b32_e32 v10, v0
	v_mov_b32_e32 v11, v0
	v_mov_b32_e32 v12, v0
	s_waitcnt vmcnt(62)
	v_mov_b32_e32 v13, v0
	v_mov_b32_e32 v14, v0
	v_mov_b32_e32 v15, v0
	s_waitcnt vmcnt(55)
	v_mov_b32_e32 v16, v0
	v_mov_b32_e32 v17, v0
	s_waitcnt vmcnt(43)
	v_mov_b32_e32 v18, v0
	v_mov_b32_e32 v19, v0
	s_waitcnt vmcnt(31)
	v_mov_b32_e32 v20, v0
	v_mov_b32_e32 v21, v0
	s_waitcnt vmcnt(19)
	v_mov_b32_e32 v22, v0
	v_mov_b32_e32 v23, v0
	v_mov_b32_e32 v24, v0
	v_mov_b32_e32 v25, v0
	v_mov_b32_e32 v26, v0
	v_lshl_add_u64 v[192:193], v[184:185], 0, s[54:55]
	v_lshl_add_u64 v[194:195], v[184:185], 0, s[56:57]
	v_lshl_add_u64 v[192:193], v[192:193], 0, v[190:191]
	v_lshl_add_u64 v[194:195], v[194:195], 0, v[190:191]
	s_mov_b32 s56, 0x1b00000
	s_mov_b32 s57, 0
	v_lshl_add_u64 v[192:193], v[192:193], 0, s[56:57]
	s_mov_b32 s56, 0xa00000
	v_lshl_add_u64 v[194:195], v[194:195], 0, s[56:57]
	v_mov_b32_e32 v27, v0
	v_mov_b32_e32 v52, v0
	v_mov_b32_e32 v53, v0
	v_mov_b32_e32 v54, v0
	v_mov_b32_e32 v55, v0
	v_mov_b32_e32 v56, v0
	v_mov_b32_e32 v57, v0
	v_mov_b32_e32 v58, v0
	v_mov_b32_e32 v59, v0
	v_mov_b32_e32 v60, v0
	v_mov_b32_e32 v61, v0
	v_mov_b32_e32 v62, v0
	v_mov_b32_e32 v63, v0
	v_mov_b32_e32 v64, v0
	v_mov_b32_e32 v65, v0
	v_mov_b32_e32 v66, v0
	v_mov_b32_e32 v67, v0
	v_mov_b32_e32 v68, v0
	v_mov_b32_e32 v69, v0
	v_mov_b32_e32 v70, v0
	v_mov_b32_e32 v71, v0
	s_waitcnt vmcnt(17)
	ds_write_b128 v179, v[28:31]
	s_waitcnt vmcnt(16)
	ds_write_b128 v179, v[32:35] offset:4096
	s_waitcnt vmcnt(15)
	ds_write_b128 v179, v[36:39] offset:8192
	s_waitcnt vmcnt(14)
	ds_write_b128 v179, v[40:43] offset:12288
	s_waitcnt vmcnt(13)
	ds_write_b128 v179, v[44:47] offset:16384
	s_waitcnt vmcnt(12)
	ds_write_b128 v179, v[48:51] offset:20480
	v_mov_b32_e32 v28, v0
	v_mov_b32_e32 v29, v0
	v_mov_b32_e32 v30, v0
	v_mov_b32_e32 v31, v0
	v_mov_b32_e32 v32, v0
	v_mov_b32_e32 v33, v0
	v_mov_b32_e32 v34, v0
	v_mov_b32_e32 v35, v0
	v_mov_b32_e32 v36, v0
	v_mov_b32_e32 v37, v0
	v_mov_b32_e32 v38, v0
	v_mov_b32_e32 v39, v0
	v_mov_b32_e32 v40, v0
	v_mov_b32_e32 v41, v0
	v_mov_b32_e32 v42, v0
	v_mov_b32_e32 v43, v0
	v_mov_b32_e32 v44, v0
	v_mov_b32_e32 v45, v0
	v_mov_b32_e32 v46, v0
	v_mov_b32_e32 v47, v0
	v_mov_b32_e32 v48, v0
	v_mov_b32_e32 v49, v0
	v_mov_b32_e32 v50, v0
	v_mov_b32_e32 v51, v0
	v_mov_b32_e32 v72, v0
	v_mov_b32_e32 v73, v0
	v_mov_b32_e32 v74, v0
	v_mov_b32_e32 v75, v0
	v_mov_b32_e32 v76, v0
	v_mov_b32_e32 v77, v0
	v_mov_b32_e32 v78, v0
	v_mov_b32_e32 v79, v0
	v_mov_b32_e32 v80, v0
	v_mov_b32_e32 v81, v0
	v_mov_b32_e32 v82, v0
	v_mov_b32_e32 v83, v0
	v_mov_b32_e32 v84, v0
	v_mov_b32_e32 v85, v0
	v_mov_b32_e32 v86, v0
	v_mov_b32_e32 v87, v0
	v_mov_b32_e32 v88, v0
	v_mov_b32_e32 v89, v0
	v_mov_b32_e32 v90, v0
	v_mov_b32_e32 v91, v0
	v_mov_b32_e32 v92, v0
	v_mov_b32_e32 v93, v0
	v_mov_b32_e32 v94, v0
	v_mov_b32_e32 v95, v0
	v_mov_b32_e32 v96, v0
	v_mov_b32_e32 v97, v0
	v_mov_b32_e32 v98, v0
	v_mov_b32_e32 v99, v0
	v_mov_b32_e32 v100, v0
	v_mov_b32_e32 v101, v0
	v_mov_b32_e32 v102, v0
	v_mov_b32_e32 v103, v0
	v_mov_b32_e32 v104, v0
	v_mov_b32_e32 v105, v0
	v_mov_b32_e32 v106, v0
	v_mov_b32_e32 v107, v0
	v_mov_b32_e32 v108, v0
	v_mov_b32_e32 v109, v0
	v_mov_b32_e32 v110, v0
	v_mov_b32_e32 v111, v0
	v_mov_b32_e32 v112, v0
	v_mov_b32_e32 v113, v0
	v_mov_b32_e32 v114, v0
	v_mov_b32_e32 v115, v0
	v_mov_b32_e32 v116, v0
	v_mov_b32_e32 v117, v0
	v_mov_b32_e32 v118, v0
	v_mov_b32_e32 v119, v0
	v_mov_b32_e32 v120, v0
	v_mov_b32_e32 v121, v0
	v_mov_b32_e32 v122, v0
	v_mov_b32_e32 v123, v0
	v_mov_b32_e32 v124, v0
	v_mov_b32_e32 v125, v0
	v_mov_b32_e32 v126, v0
	v_mov_b32_e32 v127, v0
	s_waitcnt lgkmcnt(0)
	s_barrier
	s_branch .LBB0_3203

; DEV void gemm_gload(GRegs& g, const bf16_t* A0, int lda0, const bf16_t* A1, int lda1, int ksplit,
;                     const bf16_t* Bt, int ldb, int k0, int tid) {
;   const bf16_t* Ab; int lda, kk;
;   if (k0 < ksplit) { Ab = A0; lda = lda0; kk = k0; }
;   else { Ab = A1; lda = lda1; kk = k0 - ksplit; }
;   const int row = tid >> 2, kc = (tid & 3) * 8;
;   const bf16_t* pa = Ab + (size_t)row * lda + kk + kc;
;   const bf16_t* pb = Bt + (size_t)row * ldb + k0 + kc;
;   g.a0 = *(const u32x4*)(pa);
;   g.a1 = *(const u32x4*)(pa + (size_t)64 * lda);
;   g.a2 = *(const u32x4*)(pa + (size_t)128 * lda);
;   g.a3 = *(const u32x4*)(pa + (size_t)192 * lda);
;   g.b0 = *(const u32x4*)(pb);
;   g.b1 = *(const u32x4*)(pb + (size_t)64 * ldb);
; template <bool RES, class Epi>
; DEV void gemm_tile_x(const bf16_t* A0, int lda0, const bf16_t* A1, int lda1, int ksplit,
;                      const bf16_t* Bt, int ldb, int K, char* smem, const float* resb, Epi epi) {
;     ...
;   for (int kt = 0; kt < nk; kt += 2) {
;     GEMM_COMPUTE(sbase);
;     if (kt + 1 < nk) gemm_lds_write(g1, sbase + GST + woff, sbase + GST + GSA + woff);
;     if (kt + 3 < nk) gemm_gload(g1, A0, lda0, A1, lda1, ksplit, Bt, ldb, (kt + 3) * 32, tid);
.LBB0_3203:
	s_add_i32 s53, s53, 2
	s_cmp_gt_u32 s53, 28
	ds_read_b128 v[196:199], v200
	ds_read_b128 v[208:211], v201 offset:16384
	ds_read_b128 v[228:231], v201 offset:18432
	ds_read_b128 v[232:235], v200 offset:2048
	ds_read_b128 v[252:255], v203 offset:16384
	s_waitcnt lgkmcnt(3)
	v_mfma_f32_32x32x16_bf16 v[112:127], v[196:199], v[208:211], v[112:127]
	s_waitcnt lgkmcnt(2)
	v_mfma_f32_32x32x16_bf16 v[96:111], v[196:199], v[228:231], v[96:111]
	ds_read_b128 v[196:199], v200 offset:4096
	s_waitcnt lgkmcnt(2)
	v_mfma_f32_32x32x16_bf16 v[80:95], v[232:235], v[208:211], v[80:95]
	v_mfma_f32_32x32x16_bf16 v[64:79], v[232:235], v[228:231], v[64:79]
	ds_read_b128 v[232:235], v200 offset:6144
	s_waitcnt lgkmcnt(1)
	v_mfma_f32_32x32x16_bf16 v[48:63], v[196:199], v[208:211], v[48:63]
	v_mfma_f32_32x32x16_bf16 v[32:47], v[196:199], v[228:231], v[32:47]
	ds_read_b128 v[196:199], v202
	s_waitcnt lgkmcnt(1)
	v_mfma_f32_32x32x16_bf16 v[0:15], v[232:235], v[228:231], v[0:15]
	ds_read_b128 v[228:231], v203 offset:18432
	v_mfma_f32_32x32x16_bf16 v[16:31], v[232:235], v[208:211], v[16:31]
	ds_read_b128 v[232:235], v202 offset:2048
	s_waitcnt lgkmcnt(2)
	v_mfma_f32_32x32x16_bf16 v[112:127], v[196:199], v[252:255], v[112:127]
	s_waitcnt lgkmcnt(1)
	v_mfma_f32_32x32x16_bf16 v[96:111], v[196:199], v[228:231], v[96:111]
	ds_read_b128 v[196:199], v202 offset:4096
	s_waitcnt lgkmcnt(1)
	v_mfma_f32_32x32x16_bf16 v[80:95], v[232:235], v[252:255], v[80:95]
	v_mfma_f32_32x32x16_bf16 v[64:79], v[232:235], v[228:231], v[64:79]
	ds_read_b128 v[232:235], v202 offset:6144
	s_waitcnt vmcnt(5)
	ds_write_b128 v179, v[128:131] offset:24576
	s_waitcnt vmcnt(4)
	ds_write_b128 v179, v[136:139] offset:28672
	s_waitcnt vmcnt(3)
	ds_write_b128 v179, v[144:147] offset:32768
	s_waitcnt vmcnt(2)
	ds_write_b128 v179, v[148:151] offset:36864
	s_waitcnt vmcnt(1)
	ds_write_b128 v179, v[160:163] offset:40960
	s_waitcnt vmcnt(0)
	ds_write_b128 v179, v[168:171] offset:45056
	s_waitcnt lgkmcnt(7)
	v_mfma_f32_32x32x16_bf16 v[48:63], v[196:199], v[252:255], v[48:63]
	v_mfma_f32_32x32x16_bf16 v[32:47], v[196:199], v[228:231], v[32:47]
	s_waitcnt lgkmcnt(6)
	v_mfma_f32_32x32x16_bf16 v[16:31], v[232:235], v[252:255], v[16:31]
	v_mfma_f32_32x32x16_bf16 v[0:15], v[232:235], v[228:231], v[0:15]
	s_waitcnt lgkmcnt(0)
	s_cbranch_scc1 .LBB0_3205
	global_load_dwordx4 v[128:131], v[192:193], off offset:192
	s_mov_b32 s56, 0x20000
	v_lshl_add_u64 v[136:137], v[192:193], 0, s[56:57]
	global_load_dwordx4 v[136:139], v[136:137], off offset:192
	s_mov_b32 s56, 0x40000
	v_lshl_add_u64 v[144:145], v[192:193], 0, s[56:57]
	global_load_dwordx4 v[144:147], v[144:145], off offset:192
	s_mov_b32 s56, 0x60000
	v_lshl_add_u64 v[148:149], v[192:193], 0, s[56:57]
	global_load_dwordx4 v[148:151], v[148:149], off offset:192
	global_load_dwordx4 v[160:163], v[194:195], off offset:192
	s_mov_b32 s56, 0x20000
	v_lshl_add_u64 v[168:169], v[194:195], 0, s[56:57]
	global_load_dwordx4 v[168:171], v[168:169], off offset:192
